# FF2 stream-K partial slots: sc0 sc1 write-through stores and sc0 sc1 loads, the per-workgroup buffer_wbl2 in the publish path removed; owner epilogues (prompt and sample tiles) pre-pass through a regi
# speedup vs baseline: 1.0163x; 1.0163x over previous
.LBB0_1412:
	s_cmp_gt_i32 s31, 31
	v_lshl_or_b32 v200, s95, 8, v226
	s_mov_b32 s40, s84
	s_cselect_b64 s[84:85], -1, 0
	s_cmp_lt_i32 s31, 32
	s_mov_b64 s[80:81], -1
	v_ashrrev_i32_e32 v201, 31, v200
	s_barrier
	s_cbranch_scc1 .Lfq_LBB0_1414
	s_mov_b64 s[80:81], 0
	s_branch .Lfs_LBB0_1414

.Lfq_LBB0_1423:
	v_lshlrev_b32_e32 v203, 12, v204
	v_lshl_add_u32 v203, v200, 2, v203
	v_lshlrev_b32_e32 v205, 2, v194
	s_cmp_eq_u32 s30, 1
	s_cbranch_scc1 .Lfq_np1
	s_cmp_eq_u32 s30, 2
	s_cbranch_scc1 .Lfq_np2
	s_add_u32 s42, s62, 0x0
	s_addc_u32 s43, s63, 0
	global_load_dwordx4 v[160:163], v205, s[42:43] sc0 sc1
	s_add_u32 s98, s62, 0x1000
	s_addc_u32 s99, s63, 0
	global_load_dwordx4 v[164:167], v205, s[98:99] sc0 sc1
	s_add_u32 s42, s62, 0x400
	s_addc_u32 s43, s63, 0
	global_load_dwordx4 v[168:171], v205, s[42:43] sc0 sc1
	s_add_u32 s98, s62, 0x1400
	s_addc_u32 s99, s63, 0
	global_load_dwordx4 v[172:175], v205, s[98:99] sc0 sc1
	s_add_u32 s42, s62, 0x800
	s_addc_u32 s43, s63, 0
	global_load_dwordx4 v[176:179], v205, s[42:43] sc0 sc1
	s_add_u32 s98, s62, 0x1800
	s_addc_u32 s99, s63, 0
	global_load_dwordx4 v[180:183], v205, s[98:99] sc0 sc1
	s_add_u32 s42, s62, 0xc00
	s_addc_u32 s43, s63, 0
	global_load_dwordx4 v[206:209], v205, s[42:43] sc0 sc1
	s_add_u32 s98, s62, 0x1c00
	s_addc_u32 s99, s63, 0
	global_load_dwordx4 v[210:213], v205, s[98:99] sc0 sc1
	s_add_u32 s42, s62, 0x2000
	s_addc_u32 s43, s63, 0
	global_load_dwordx4 v[236:239], v205, s[42:43] sc0 sc1
	s_waitcnt vmcnt(8)
	v_lshlrev_b32_e32 v240, 16, v160
	v_and_b32_e32 v241, 0xffff0000, v160
	v_pk_add_f32 v[124:125], v[124:125], v[240:241]
	v_lshlrev_b32_e32 v240, 16, v161
	v_and_b32_e32 v241, 0xffff0000, v161
	v_pk_add_f32 v[126:127], v[126:127], v[240:241]
	v_lshlrev_b32_e32 v240, 16, v162
	v_and_b32_e32 v241, 0xffff0000, v162
	v_pk_add_f32 v[120:121], v[120:121], v[240:241]
	v_lshlrev_b32_e32 v240, 16, v163
	v_and_b32_e32 v241, 0xffff0000, v163
	v_pk_add_f32 v[122:123], v[122:123], v[240:241]
	s_add_u32 s98, s62, 0x3000
	s_addc_u32 s99, s63, 0
	global_load_dwordx4 v[160:163], v205, s[98:99] sc0 sc1
	s_waitcnt vmcnt(8)
	v_lshlrev_b32_e32 v240, 16, v164
	v_and_b32_e32 v241, 0xffff0000, v164
	v_pk_add_f32 v[92:93], v[92:93], v[240:241]
	v_lshlrev_b32_e32 v240, 16, v165
	v_and_b32_e32 v241, 0xffff0000, v165
	v_pk_add_f32 v[94:95], v[94:95], v[240:241]
	v_lshlrev_b32_e32 v240, 16, v166
	v_and_b32_e32 v241, 0xffff0000, v166
	v_pk_add_f32 v[88:89], v[88:89], v[240:241]
	v_lshlrev_b32_e32 v240, 16, v167
	v_and_b32_e32 v241, 0xffff0000, v167
	v_pk_add_f32 v[90:91], v[90:91], v[240:241]
	s_add_u32 s42, s62, 0x2400
	s_addc_u32 s43, s63, 0
	global_load_dwordx4 v[164:167], v205, s[42:43] sc0 sc1
	s_waitcnt vmcnt(8)
	v_lshlrev_b32_e32 v240, 16, v168
	v_and_b32_e32 v241, 0xffff0000, v168
	v_pk_add_f32 v[116:117], v[116:117], v[240:241]
	v_lshlrev_b32_e32 v240, 16, v169
	v_and_b32_e32 v241, 0xffff0000, v169
	v_pk_add_f32 v[118:119], v[118:119], v[240:241]
	v_lshlrev_b32_e32 v240, 16, v170
	v_and_b32_e32 v241, 0xffff0000, v170
	v_pk_add_f32 v[112:113], v[112:113], v[240:241]
	v_lshlrev_b32_e32 v240, 16, v171
	v_and_b32_e32 v241, 0xffff0000, v171
	v_pk_add_f32 v[114:115], v[114:115], v[240:241]
	s_add_u32 s98, s62, 0x3400
	s_addc_u32 s99, s63, 0
	global_load_dwordx4 v[168:171], v205, s[98:99] sc0 sc1
	s_waitcnt vmcnt(8)
	v_lshlrev_b32_e32 v240, 16, v172
	v_and_b32_e32 v241, 0xffff0000, v172
	v_pk_add_f32 v[84:85], v[84:85], v[240:241]
	v_lshlrev_b32_e32 v240, 16, v173
	v_and_b32_e32 v241, 0xffff0000, v173
	v_pk_add_f32 v[86:87], v[86:87], v[240:241]
	v_lshlrev_b32_e32 v240, 16, v174
	v_and_b32_e32 v241, 0xffff0000, v174
	v_pk_add_f32 v[80:81], v[80:81], v[240:241]
	v_lshlrev_b32_e32 v240, 16, v175
	v_and_b32_e32 v241, 0xffff0000, v175
	v_pk_add_f32 v[82:83], v[82:83], v[240:241]
	s_add_u32 s42, s62, 0x2800
	s_addc_u32 s43, s63, 0
	global_load_dwordx4 v[172:175], v205, s[42:43] sc0 sc1
	s_waitcnt vmcnt(8)
	v_lshlrev_b32_e32 v240, 16, v176
	v_and_b32_e32 v241, 0xffff0000, v176
	v_pk_add_f32 v[108:109], v[108:109], v[240:241]
	v_lshlrev_b32_e32 v240, 16, v177
	v_and_b32_e32 v241, 0xffff0000, v177
	v_pk_add_f32 v[110:111], v[110:111], v[240:241]
	v_lshlrev_b32_e32 v240, 16, v178
	v_and_b32_e32 v241, 0xffff0000, v178
	v_pk_add_f32 v[104:105], v[104:105], v[240:241]
	v_lshlrev_b32_e32 v240, 16, v179
	v_and_b32_e32 v241, 0xffff0000, v179
	v_pk_add_f32 v[106:107], v[106:107], v[240:241]
	s_add_u32 s98, s62, 0x3800
	s_addc_u32 s99, s63, 0
	global_load_dwordx4 v[176:179], v205, s[98:99] sc0 sc1
	s_waitcnt vmcnt(8)
	v_lshlrev_b32_e32 v240, 16, v180
	v_and_b32_e32 v241, 0xffff0000, v180
	v_pk_add_f32 v[76:77], v[76:77], v[240:241]
	v_lshlrev_b32_e32 v240, 16, v181
	v_and_b32_e32 v241, 0xffff0000, v181
	v_pk_add_f32 v[78:79], v[78:79], v[240:241]
	v_lshlrev_b32_e32 v240, 16, v182
	v_and_b32_e32 v241, 0xffff0000, v182
	v_pk_add_f32 v[72:73], v[72:73], v[240:241]
	v_lshlrev_b32_e32 v240, 16, v183
	v_and_b32_e32 v241, 0xffff0000, v183
	v_pk_add_f32 v[74:75], v[74:75], v[240:241]
	s_add_u32 s42, s62, 0x2c00
	s_addc_u32 s43, s63, 0
	global_load_dwordx4 v[180:183], v205, s[42:43] sc0 sc1
	s_waitcnt vmcnt(8)
	v_lshlrev_b32_e32 v240, 16, v206
	v_and_b32_e32 v241, 0xffff0000, v206
	v_pk_add_f32 v[100:101], v[100:101], v[240:241]
	v_lshlrev_b32_e32 v240, 16, v207
	v_and_b32_e32 v241, 0xffff0000, v207
	v_pk_add_f32 v[102:103], v[102:103], v[240:241]
	v_lshlrev_b32_e32 v240, 16, v208
	v_and_b32_e32 v241, 0xffff0000, v208
	v_pk_add_f32 v[96:97], v[96:97], v[240:241]
	v_lshlrev_b32_e32 v240, 16, v209
	v_and_b32_e32 v241, 0xffff0000, v209
	v_pk_add_f32 v[98:99], v[98:99], v[240:241]
	s_add_u32 s98, s62, 0x3c00
	s_addc_u32 s99, s63, 0
	global_load_dwordx4 v[206:209], v205, s[98:99] sc0 sc1
	s_waitcnt vmcnt(8)
	v_lshlrev_b32_e32 v240, 16, v210
	v_and_b32_e32 v241, 0xffff0000, v210
	v_pk_add_f32 v[68:69], v[68:69], v[240:241]
	v_lshlrev_b32_e32 v240, 16, v211
	v_and_b32_e32 v241, 0xffff0000, v211
	v_pk_add_f32 v[70:71], v[70:71], v[240:241]
	v_lshlrev_b32_e32 v240, 16, v212
	v_and_b32_e32 v241, 0xffff0000, v212
	v_pk_add_f32 v[64:65], v[64:65], v[240:241]
	v_lshlrev_b32_e32 v240, 16, v213
	v_and_b32_e32 v241, 0xffff0000, v213
	v_pk_add_f32 v[66:67], v[66:67], v[240:241]
	s_add_u32 s42, s62, 0x20000
	s_addc_u32 s43, s63, 0
	global_load_dwordx4 v[210:213], v205, s[42:43] sc0 sc1
	s_waitcnt vmcnt(8)
	v_lshlrev_b32_e32 v240, 16, v236
	v_and_b32_e32 v241, 0xffff0000, v236
	v_pk_add_f32 v[60:61], v[60:61], v[240:241]
	v_lshlrev_b32_e32 v240, 16, v237
	v_and_b32_e32 v241, 0xffff0000, v237
	v_pk_add_f32 v[62:63], v[62:63], v[240:241]
	v_lshlrev_b32_e32 v240, 16, v238
	v_and_b32_e32 v241, 0xffff0000, v238
	v_pk_add_f32 v[56:57], v[56:57], v[240:241]
	v_lshlrev_b32_e32 v240, 16, v239
	v_and_b32_e32 v241, 0xffff0000, v239
	v_pk_add_f32 v[58:59], v[58:59], v[240:241]
	s_add_u32 s98, s62, 0x21000
	s_addc_u32 s99, s63, 0
	global_load_dwordx4 v[236:239], v205, s[98:99] sc0 sc1
	s_waitcnt vmcnt(8)
	v_lshlrev_b32_e32 v240, 16, v160
	v_and_b32_e32 v241, 0xffff0000, v160
	v_pk_add_f32 v[28:29], v[28:29], v[240:241]
	v_lshlrev_b32_e32 v240, 16, v161
	v_and_b32_e32 v241, 0xffff0000, v161
	v_pk_add_f32 v[30:31], v[30:31], v[240:241]
	v_lshlrev_b32_e32 v240, 16, v162
	v_and_b32_e32 v241, 0xffff0000, v162
	v_pk_add_f32 v[24:25], v[24:25], v[240:241]
	v_lshlrev_b32_e32 v240, 16, v163
	v_and_b32_e32 v241, 0xffff0000, v163
	v_pk_add_f32 v[26:27], v[26:27], v[240:241]
	s_add_u32 s42, s62, 0x20400
	s_addc_u32 s43, s63, 0
	global_load_dwordx4 v[160:163], v205, s[42:43] sc0 sc1
	s_waitcnt vmcnt(8)
	v_lshlrev_b32_e32 v240, 16, v164
	v_and_b32_e32 v241, 0xffff0000, v164
	v_pk_add_f32 v[52:53], v[52:53], v[240:241]
	v_lshlrev_b32_e32 v240, 16, v165
	v_and_b32_e32 v241, 0xffff0000, v165
	v_pk_add_f32 v[54:55], v[54:55], v[240:241]
	v_lshlrev_b32_e32 v240, 16, v166
	v_and_b32_e32 v241, 0xffff0000, v166
	v_pk_add_f32 v[48:49], v[48:49], v[240:241]
	v_lshlrev_b32_e32 v240, 16, v167
	v_and_b32_e32 v241, 0xffff0000, v167
	v_pk_add_f32 v[50:51], v[50:51], v[240:241]
	s_add_u32 s98, s62, 0x21400
	s_addc_u32 s99, s63, 0
	global_load_dwordx4 v[164:167], v205, s[98:99] sc0 sc1
	s_waitcnt vmcnt(8)
	v_lshlrev_b32_e32 v240, 16, v168
	v_and_b32_e32 v241, 0xffff0000, v168
	v_pk_add_f32 v[20:21], v[20:21], v[240:241]
	v_lshlrev_b32_e32 v240, 16, v169
	v_and_b32_e32 v241, 0xffff0000, v169
	v_pk_add_f32 v[22:23], v[22:23], v[240:241]
	v_lshlrev_b32_e32 v240, 16, v170
	v_and_b32_e32 v241, 0xffff0000, v170
	v_pk_add_f32 v[16:17], v[16:17], v[240:241]
	v_lshlrev_b32_e32 v240, 16, v171
	v_and_b32_e32 v241, 0xffff0000, v171
	v_pk_add_f32 v[18:19], v[18:19], v[240:241]
	s_add_u32 s42, s62, 0x20800
	s_addc_u32 s43, s63, 0
	global_load_dwordx4 v[168:171], v205, s[42:43] sc0 sc1
	s_waitcnt vmcnt(8)
	v_lshlrev_b32_e32 v240, 16, v172
	v_and_b32_e32 v241, 0xffff0000, v172
	v_pk_add_f32 v[44:45], v[44:45], v[240:241]
	v_lshlrev_b32_e32 v240, 16, v173
	v_and_b32_e32 v241, 0xffff0000, v173
	v_pk_add_f32 v[46:47], v[46:47], v[240:241]
	v_lshlrev_b32_e32 v240, 16, v174
	v_and_b32_e32 v241, 0xffff0000, v174
	v_pk_add_f32 v[40:41], v[40:41], v[240:241]
	v_lshlrev_b32_e32 v240, 16, v175
	v_and_b32_e32 v241, 0xffff0000, v175
	v_pk_add_f32 v[42:43], v[42:43], v[240:241]
	s_add_u32 s98, s62, 0x21800
	s_addc_u32 s99, s63, 0
	global_load_dwordx4 v[172:175], v205, s[98:99] sc0 sc1
	s_waitcnt vmcnt(8)
	v_lshlrev_b32_e32 v240, 16, v176
	v_and_b32_e32 v241, 0xffff0000, v176
	v_pk_add_f32 v[12:13], v[12:13], v[240:241]
	v_lshlrev_b32_e32 v240, 16, v177
	v_and_b32_e32 v241, 0xffff0000, v177
	v_pk_add_f32 v[14:15], v[14:15], v[240:241]
	v_lshlrev_b32_e32 v240, 16, v178
	v_and_b32_e32 v241, 0xffff0000, v178
	v_pk_add_f32 v[8:9], v[8:9], v[240:241]
	v_lshlrev_b32_e32 v240, 16, v179
	v_and_b32_e32 v241, 0xffff0000, v179
	v_pk_add_f32 v[10:11], v[10:11], v[240:241]
	s_add_u32 s42, s62, 0x20c00
	s_addc_u32 s43, s63, 0
	global_load_dwordx4 v[176:179], v205, s[42:43] sc0 sc1
	s_waitcnt vmcnt(8)
	v_lshlrev_b32_e32 v240, 16, v180
	v_and_b32_e32 v241, 0xffff0000, v180
	v_pk_add_f32 v[36:37], v[36:37], v[240:241]
	v_lshlrev_b32_e32 v240, 16, v181
	v_and_b32_e32 v241, 0xffff0000, v181
	v_pk_add_f32 v[38:39], v[38:39], v[240:241]
	v_lshlrev_b32_e32 v240, 16, v182
	v_and_b32_e32 v241, 0xffff0000, v182
	v_pk_add_f32 v[32:33], v[32:33], v[240:241]
	v_lshlrev_b32_e32 v240, 16, v183
	v_and_b32_e32 v241, 0xffff0000, v183
	v_pk_add_f32 v[34:35], v[34:35], v[240:241]
	s_add_u32 s98, s62, 0x21c00
	s_addc_u32 s99, s63, 0
	global_load_dwordx4 v[180:183], v205, s[98:99] sc0 sc1
	s_waitcnt vmcnt(8)
	v_lshlrev_b32_e32 v240, 16, v206
	v_and_b32_e32 v241, 0xffff0000, v206
	v_pk_add_f32 v[4:5], v[4:5], v[240:241]
	v_lshlrev_b32_e32 v240, 16, v207
	v_and_b32_e32 v241, 0xffff0000, v207
	v_pk_add_f32 v[6:7], v[6:7], v[240:241]
	v_lshlrev_b32_e32 v240, 16, v208
	v_and_b32_e32 v241, 0xffff0000, v208
	v_pk_add_f32 v[0:1], v[0:1], v[240:241]
	v_lshlrev_b32_e32 v240, 16, v209
	v_and_b32_e32 v241, 0xffff0000, v209
	v_pk_add_f32 v[2:3], v[2:3], v[240:241]
	s_add_u32 s42, s62, 0x22000
	s_addc_u32 s43, s63, 0
	global_load_dwordx4 v[206:209], v205, s[42:43] sc0 sc1
	s_waitcnt vmcnt(8)
	v_lshlrev_b32_e32 v240, 16, v210
	v_and_b32_e32 v241, 0xffff0000, v210
	v_pk_add_f32 v[124:125], v[124:125], v[240:241]
	v_lshlrev_b32_e32 v240, 16, v211
	v_and_b32_e32 v241, 0xffff0000, v211
	v_pk_add_f32 v[126:127], v[126:127], v[240:241]
	v_lshlrev_b32_e32 v240, 16, v212
	v_and_b32_e32 v241, 0xffff0000, v212
	v_pk_add_f32 v[120:121], v[120:121], v[240:241]
	v_lshlrev_b32_e32 v240, 16, v213
	v_and_b32_e32 v241, 0xffff0000, v213
	v_pk_add_f32 v[122:123], v[122:123], v[240:241]
	s_add_u32 s98, s62, 0x23000
	s_addc_u32 s99, s63, 0
	global_load_dwordx4 v[210:213], v205, s[98:99] sc0 sc1
	s_waitcnt vmcnt(8)
	v_lshlrev_b32_e32 v240, 16, v236
	v_and_b32_e32 v241, 0xffff0000, v236
	v_pk_add_f32 v[92:93], v[92:93], v[240:241]
	v_lshlrev_b32_e32 v240, 16, v237
	v_and_b32_e32 v241, 0xffff0000, v237
	v_pk_add_f32 v[94:95], v[94:95], v[240:241]
	v_lshlrev_b32_e32 v240, 16, v238
	v_and_b32_e32 v241, 0xffff0000, v238
	v_pk_add_f32 v[88:89], v[88:89], v[240:241]
	v_lshlrev_b32_e32 v240, 16, v239
	v_and_b32_e32 v241, 0xffff0000, v239
	v_pk_add_f32 v[90:91], v[90:91], v[240:241]
	s_add_u32 s42, s62, 0x22400
	s_addc_u32 s43, s63, 0
	global_load_dwordx4 v[236:239], v205, s[42:43] sc0 sc1
	s_waitcnt vmcnt(8)
	v_lshlrev_b32_e32 v240, 16, v160
	v_and_b32_e32 v241, 0xffff0000, v160
	v_pk_add_f32 v[116:117], v[116:117], v[240:241]
	v_lshlrev_b32_e32 v240, 16, v161
	v_and_b32_e32 v241, 0xffff0000, v161
	v_pk_add_f32 v[118:119], v[118:119], v[240:241]
	v_lshlrev_b32_e32 v240, 16, v162
	v_and_b32_e32 v241, 0xffff0000, v162
	v_pk_add_f32 v[112:113], v[112:113], v[240:241]
	v_lshlrev_b32_e32 v240, 16, v163
	v_and_b32_e32 v241, 0xffff0000, v163
	v_pk_add_f32 v[114:115], v[114:115], v[240:241]
	s_add_u32 s98, s62, 0x23400
	s_addc_u32 s99, s63, 0
	global_load_dwordx4 v[160:163], v205, s[98:99] sc0 sc1
	s_waitcnt vmcnt(8)
	v_lshlrev_b32_e32 v240, 16, v164
	v_and_b32_e32 v241, 0xffff0000, v164
	v_pk_add_f32 v[84:85], v[84:85], v[240:241]
	v_lshlrev_b32_e32 v240, 16, v165
	v_and_b32_e32 v241, 0xffff0000, v165
	v_pk_add_f32 v[86:87], v[86:87], v[240:241]
	v_lshlrev_b32_e32 v240, 16, v166
	v_and_b32_e32 v241, 0xffff0000, v166
	v_pk_add_f32 v[80:81], v[80:81], v[240:241]
	v_lshlrev_b32_e32 v240, 16, v167
	v_and_b32_e32 v241, 0xffff0000, v167
	v_pk_add_f32 v[82:83], v[82:83], v[240:241]
	s_add_u32 s42, s62, 0x22800
	s_addc_u32 s43, s63, 0
	global_load_dwordx4 v[164:167], v205, s[42:43] sc0 sc1
	s_waitcnt vmcnt(8)
	v_lshlrev_b32_e32 v240, 16, v168
	v_and_b32_e32 v241, 0xffff0000, v168
	v_pk_add_f32 v[108:109], v[108:109], v[240:241]
	v_lshlrev_b32_e32 v240, 16, v169
	v_and_b32_e32 v241, 0xffff0000, v169
	v_pk_add_f32 v[110:111], v[110:111], v[240:241]
	v_lshlrev_b32_e32 v240, 16, v170
	v_and_b32_e32 v241, 0xffff0000, v170
	v_pk_add_f32 v[104:105], v[104:105], v[240:241]
	v_lshlrev_b32_e32 v240, 16, v171
	v_and_b32_e32 v241, 0xffff0000, v171
	v_pk_add_f32 v[106:107], v[106:107], v[240:241]
	s_add_u32 s98, s62, 0x23800
	s_addc_u32 s99, s63, 0
	global_load_dwordx4 v[168:171], v205, s[98:99] sc0 sc1
	s_waitcnt vmcnt(8)
	v_lshlrev_b32_e32 v240, 16, v172
	v_and_b32_e32 v241, 0xffff0000, v172
	v_pk_add_f32 v[76:77], v[76:77], v[240:241]
	v_lshlrev_b32_e32 v240, 16, v173
	v_and_b32_e32 v241, 0xffff0000, v173
	v_pk_add_f32 v[78:79], v[78:79], v[240:241]
	v_lshlrev_b32_e32 v240, 16, v174
	v_and_b32_e32 v241, 0xffff0000, v174
	v_pk_add_f32 v[72:73], v[72:73], v[240:241]
	v_lshlrev_b32_e32 v240, 16, v175
	v_and_b32_e32 v241, 0xffff0000, v175
	v_pk_add_f32 v[74:75], v[74:75], v[240:241]
	s_add_u32 s42, s62, 0x22c00
	s_addc_u32 s43, s63, 0
	global_load_dwordx4 v[172:175], v205, s[42:43] sc0 sc1
	s_waitcnt vmcnt(8)
	v_lshlrev_b32_e32 v240, 16, v176
	v_and_b32_e32 v241, 0xffff0000, v176
	v_pk_add_f32 v[100:101], v[100:101], v[240:241]
	v_lshlrev_b32_e32 v240, 16, v177
	v_and_b32_e32 v241, 0xffff0000, v177
	v_pk_add_f32 v[102:103], v[102:103], v[240:241]
	v_lshlrev_b32_e32 v240, 16, v178
	v_and_b32_e32 v241, 0xffff0000, v178
	v_pk_add_f32 v[96:97], v[96:97], v[240:241]
	v_lshlrev_b32_e32 v240, 16, v179
	v_and_b32_e32 v241, 0xffff0000, v179
	v_pk_add_f32 v[98:99], v[98:99], v[240:241]
	s_add_u32 s98, s62, 0x23c00
	s_addc_u32 s99, s63, 0
	global_load_dwordx4 v[176:179], v205, s[98:99] sc0 sc1
	s_waitcnt vmcnt(8)
	v_lshlrev_b32_e32 v240, 16, v180
	v_and_b32_e32 v241, 0xffff0000, v180
	v_pk_add_f32 v[68:69], v[68:69], v[240:241]
	v_lshlrev_b32_e32 v240, 16, v181
	v_and_b32_e32 v241, 0xffff0000, v181
	v_pk_add_f32 v[70:71], v[70:71], v[240:241]
	v_lshlrev_b32_e32 v240, 16, v182
	v_and_b32_e32 v241, 0xffff0000, v182
	v_pk_add_f32 v[64:65], v[64:65], v[240:241]
	v_lshlrev_b32_e32 v240, 16, v183
	v_and_b32_e32 v241, 0xffff0000, v183
	v_pk_add_f32 v[66:67], v[66:67], v[240:241]
	s_add_u32 s42, s62, 0x40000
	s_addc_u32 s43, s63, 0
	global_load_dwordx4 v[180:183], v205, s[42:43] sc0 sc1
	s_waitcnt vmcnt(8)
	v_lshlrev_b32_e32 v240, 16, v206
	v_and_b32_e32 v241, 0xffff0000, v206
	v_pk_add_f32 v[60:61], v[60:61], v[240:241]
	v_lshlrev_b32_e32 v240, 16, v207
	v_and_b32_e32 v241, 0xffff0000, v207
	v_pk_add_f32 v[62:63], v[62:63], v[240:241]
	v_lshlrev_b32_e32 v240, 16, v208
	v_and_b32_e32 v241, 0xffff0000, v208
	v_pk_add_f32 v[56:57], v[56:57], v[240:241]
	v_lshlrev_b32_e32 v240, 16, v209
	v_and_b32_e32 v241, 0xffff0000, v209
	v_pk_add_f32 v[58:59], v[58:59], v[240:241]
	s_add_u32 s98, s62, 0x41000
	s_addc_u32 s99, s63, 0
	global_load_dwordx4 v[206:209], v205, s[98:99] sc0 sc1
	s_waitcnt vmcnt(8)
	v_lshlrev_b32_e32 v240, 16, v210
	v_and_b32_e32 v241, 0xffff0000, v210
	v_pk_add_f32 v[28:29], v[28:29], v[240:241]
	v_lshlrev_b32_e32 v240, 16, v211
	v_and_b32_e32 v241, 0xffff0000, v211
	v_pk_add_f32 v[30:31], v[30:31], v[240:241]
	v_lshlrev_b32_e32 v240, 16, v212
	v_and_b32_e32 v241, 0xffff0000, v212
	v_pk_add_f32 v[24:25], v[24:25], v[240:241]
	v_lshlrev_b32_e32 v240, 16, v213
	v_and_b32_e32 v241, 0xffff0000, v213
	v_pk_add_f32 v[26:27], v[26:27], v[240:241]
	s_add_u32 s42, s62, 0x40400
	s_addc_u32 s43, s63, 0
	global_load_dwordx4 v[210:213], v205, s[42:43] sc0 sc1
	s_waitcnt vmcnt(8)
	v_lshlrev_b32_e32 v240, 16, v236
	v_and_b32_e32 v241, 0xffff0000, v236
	v_pk_add_f32 v[52:53], v[52:53], v[240:241]
	v_lshlrev_b32_e32 v240, 16, v237
	v_and_b32_e32 v241, 0xffff0000, v237
	v_pk_add_f32 v[54:55], v[54:55], v[240:241]
	v_lshlrev_b32_e32 v240, 16, v238
	v_and_b32_e32 v241, 0xffff0000, v238
	v_pk_add_f32 v[48:49], v[48:49], v[240:241]
	v_lshlrev_b32_e32 v240, 16, v239
	v_and_b32_e32 v241, 0xffff0000, v239
	v_pk_add_f32 v[50:51], v[50:51], v[240:241]
	s_add_u32 s98, s62, 0x41400
	s_addc_u32 s99, s63, 0
	global_load_dwordx4 v[236:239], v205, s[98:99] sc0 sc1
	s_waitcnt vmcnt(8)
	v_lshlrev_b32_e32 v240, 16, v160
	v_and_b32_e32 v241, 0xffff0000, v160
	v_pk_add_f32 v[20:21], v[20:21], v[240:241]
	v_lshlrev_b32_e32 v240, 16, v161
	v_and_b32_e32 v241, 0xffff0000, v161
	v_pk_add_f32 v[22:23], v[22:23], v[240:241]
	v_lshlrev_b32_e32 v240, 16, v162
	v_and_b32_e32 v241, 0xffff0000, v162
	v_pk_add_f32 v[16:17], v[16:17], v[240:241]
	v_lshlrev_b32_e32 v240, 16, v163
	v_and_b32_e32 v241, 0xffff0000, v163
	v_pk_add_f32 v[18:19], v[18:19], v[240:241]
	s_add_u32 s42, s62, 0x40800
	s_addc_u32 s43, s63, 0
	global_load_dwordx4 v[160:163], v205, s[42:43] sc0 sc1
	s_waitcnt vmcnt(8)
	v_lshlrev_b32_e32 v240, 16, v164
	v_and_b32_e32 v241, 0xffff0000, v164
	v_pk_add_f32 v[44:45], v[44:45], v[240:241]
	v_lshlrev_b32_e32 v240, 16, v165
	v_and_b32_e32 v241, 0xffff0000, v165
	v_pk_add_f32 v[46:47], v[46:47], v[240:241]
	v_lshlrev_b32_e32 v240, 16, v166
	v_and_b32_e32 v241, 0xffff0000, v166
	v_pk_add_f32 v[40:41], v[40:41], v[240:241]
	v_lshlrev_b32_e32 v240, 16, v167
	v_and_b32_e32 v241, 0xffff0000, v167
	v_pk_add_f32 v[42:43], v[42:43], v[240:241]
	s_add_u32 s98, s62, 0x41800
	s_addc_u32 s99, s63, 0
	global_load_dwordx4 v[164:167], v205, s[98:99] sc0 sc1
	s_waitcnt vmcnt(8)
	v_lshlrev_b32_e32 v240, 16, v168
	v_and_b32_e32 v241, 0xffff0000, v168
	v_pk_add_f32 v[12:13], v[12:13], v[240:241]
	v_lshlrev_b32_e32 v240, 16, v169
	v_and_b32_e32 v241, 0xffff0000, v169
	v_pk_add_f32 v[14:15], v[14:15], v[240:241]
	v_lshlrev_b32_e32 v240, 16, v170
	v_and_b32_e32 v241, 0xffff0000, v170
	v_pk_add_f32 v[8:9], v[8:9], v[240:241]
	v_lshlrev_b32_e32 v240, 16, v171
	v_and_b32_e32 v241, 0xffff0000, v171
	v_pk_add_f32 v[10:11], v[10:11], v[240:241]
	s_add_u32 s42, s62, 0x40c00
	s_addc_u32 s43, s63, 0
	global_load_dwordx4 v[168:171], v205, s[42:43] sc0 sc1
	s_waitcnt vmcnt(8)
	v_lshlrev_b32_e32 v240, 16, v172
	v_and_b32_e32 v241, 0xffff0000, v172
	v_pk_add_f32 v[36:37], v[36:37], v[240:241]
	v_lshlrev_b32_e32 v240, 16, v173
	v_and_b32_e32 v241, 0xffff0000, v173
	v_pk_add_f32 v[38:39], v[38:39], v[240:241]
	v_lshlrev_b32_e32 v240, 16, v174
	v_and_b32_e32 v241, 0xffff0000, v174
	v_pk_add_f32 v[32:33], v[32:33], v[240:241]
	v_lshlrev_b32_e32 v240, 16, v175
	v_and_b32_e32 v241, 0xffff0000, v175
	v_pk_add_f32 v[34:35], v[34:35], v[240:241]
	s_add_u32 s98, s62, 0x41c00
	s_addc_u32 s99, s63, 0
	global_load_dwordx4 v[172:175], v205, s[98:99] sc0 sc1
	s_waitcnt vmcnt(8)
	v_lshlrev_b32_e32 v240, 16, v176
	v_and_b32_e32 v241, 0xffff0000, v176
	v_pk_add_f32 v[4:5], v[4:5], v[240:241]
	v_lshlrev_b32_e32 v240, 16, v177
	v_and_b32_e32 v241, 0xffff0000, v177
	v_pk_add_f32 v[6:7], v[6:7], v[240:241]
	v_lshlrev_b32_e32 v240, 16, v178
	v_and_b32_e32 v241, 0xffff0000, v178
	v_pk_add_f32 v[0:1], v[0:1], v[240:241]
	v_lshlrev_b32_e32 v240, 16, v179
	v_and_b32_e32 v241, 0xffff0000, v179
	v_pk_add_f32 v[2:3], v[2:3], v[240:241]
	s_add_u32 s42, s62, 0x42000
	s_addc_u32 s43, s63, 0
	global_load_dwordx4 v[176:179], v205, s[42:43] sc0 sc1
	s_waitcnt vmcnt(8)
	v_lshlrev_b32_e32 v240, 16, v180
	v_and_b32_e32 v241, 0xffff0000, v180
	v_pk_add_f32 v[124:125], v[124:125], v[240:241]
	v_lshlrev_b32_e32 v240, 16, v181
	v_and_b32_e32 v241, 0xffff0000, v181
	v_pk_add_f32 v[126:127], v[126:127], v[240:241]
	v_lshlrev_b32_e32 v240, 16, v182
	v_and_b32_e32 v241, 0xffff0000, v182
	v_pk_add_f32 v[120:121], v[120:121], v[240:241]
	v_lshlrev_b32_e32 v240, 16, v183
	v_and_b32_e32 v241, 0xffff0000, v183
	v_pk_add_f32 v[122:123], v[122:123], v[240:241]
	s_add_u32 s98, s62, 0x43000
	s_addc_u32 s99, s63, 0
	global_load_dwordx4 v[180:183], v205, s[98:99] sc0 sc1
	s_waitcnt vmcnt(8)
	v_lshlrev_b32_e32 v240, 16, v206
	v_and_b32_e32 v241, 0xffff0000, v206
	v_pk_add_f32 v[92:93], v[92:93], v[240:241]
	v_lshlrev_b32_e32 v240, 16, v207
	v_and_b32_e32 v241, 0xffff0000, v207
	v_pk_add_f32 v[94:95], v[94:95], v[240:241]
	v_lshlrev_b32_e32 v240, 16, v208
	v_and_b32_e32 v241, 0xffff0000, v208
	v_pk_add_f32 v[88:89], v[88:89], v[240:241]
	v_lshlrev_b32_e32 v240, 16, v209
	v_and_b32_e32 v241, 0xffff0000, v209
	v_pk_add_f32 v[90:91], v[90:91], v[240:241]
	s_add_u32 s42, s62, 0x42400
	s_addc_u32 s43, s63, 0
	global_load_dwordx4 v[206:209], v205, s[42:43] sc0 sc1
	s_waitcnt vmcnt(8)
	v_lshlrev_b32_e32 v240, 16, v210
	v_and_b32_e32 v241, 0xffff0000, v210
	v_pk_add_f32 v[116:117], v[116:117], v[240:241]
	v_lshlrev_b32_e32 v240, 16, v211
	v_and_b32_e32 v241, 0xffff0000, v211
	v_pk_add_f32 v[118:119], v[118:119], v[240:241]
	v_lshlrev_b32_e32 v240, 16, v212
	v_and_b32_e32 v241, 0xffff0000, v212
	v_pk_add_f32 v[112:113], v[112:113], v[240:241]
	v_lshlrev_b32_e32 v240, 16, v213
	v_and_b32_e32 v241, 0xffff0000, v213
	v_pk_add_f32 v[114:115], v[114:115], v[240:241]
	s_add_u32 s98, s62, 0x43400
	s_addc_u32 s99, s63, 0
	global_load_dwordx4 v[210:213], v205, s[98:99] sc0 sc1
	s_waitcnt vmcnt(8)
	v_lshlrev_b32_e32 v240, 16, v236
	v_and_b32_e32 v241, 0xffff0000, v236
	v_pk_add_f32 v[84:85], v[84:85], v[240:241]
	v_lshlrev_b32_e32 v240, 16, v237
	v_and_b32_e32 v241, 0xffff0000, v237
	v_pk_add_f32 v[86:87], v[86:87], v[240:241]
	v_lshlrev_b32_e32 v240, 16, v238
	v_and_b32_e32 v241, 0xffff0000, v238
	v_pk_add_f32 v[80:81], v[80:81], v[240:241]
	v_lshlrev_b32_e32 v240, 16, v239
	v_and_b32_e32 v241, 0xffff0000, v239
	v_pk_add_f32 v[82:83], v[82:83], v[240:241]
	s_add_u32 s42, s62, 0x42800
	s_addc_u32 s43, s63, 0
	global_load_dwordx4 v[236:239], v205, s[42:43] sc0 sc1
	s_waitcnt vmcnt(8)
	v_lshlrev_b32_e32 v240, 16, v160
	v_and_b32_e32 v241, 0xffff0000, v160
	v_pk_add_f32 v[108:109], v[108:109], v[240:241]
	v_lshlrev_b32_e32 v240, 16, v161
	v_and_b32_e32 v241, 0xffff0000, v161
	v_pk_add_f32 v[110:111], v[110:111], v[240:241]
	v_lshlrev_b32_e32 v240, 16, v162
	v_and_b32_e32 v241, 0xffff0000, v162
	v_pk_add_f32 v[104:105], v[104:105], v[240:241]
	v_lshlrev_b32_e32 v240, 16, v163
	v_and_b32_e32 v241, 0xffff0000, v163
	v_pk_add_f32 v[106:107], v[106:107], v[240:241]
	s_add_u32 s98, s62, 0x43800
	s_addc_u32 s99, s63, 0
	global_load_dwordx4 v[160:163], v205, s[98:99] sc0 sc1
	s_waitcnt vmcnt(8)
	v_lshlrev_b32_e32 v240, 16, v164
	v_and_b32_e32 v241, 0xffff0000, v164
	v_pk_add_f32 v[76:77], v[76:77], v[240:241]
	v_lshlrev_b32_e32 v240, 16, v165
	v_and_b32_e32 v241, 0xffff0000, v165
	v_pk_add_f32 v[78:79], v[78:79], v[240:241]
	v_lshlrev_b32_e32 v240, 16, v166
	v_and_b32_e32 v241, 0xffff0000, v166
	v_pk_add_f32 v[72:73], v[72:73], v[240:241]
	v_lshlrev_b32_e32 v240, 16, v167
	v_and_b32_e32 v241, 0xffff0000, v167
	v_pk_add_f32 v[74:75], v[74:75], v[240:241]
	s_add_u32 s42, s62, 0x42c00
	s_addc_u32 s43, s63, 0
	global_load_dwordx4 v[164:167], v205, s[42:43] sc0 sc1
	s_waitcnt vmcnt(8)
	v_lshlrev_b32_e32 v240, 16, v168
	v_and_b32_e32 v241, 0xffff0000, v168
	v_pk_add_f32 v[100:101], v[100:101], v[240:241]
	v_lshlrev_b32_e32 v240, 16, v169
	v_and_b32_e32 v241, 0xffff0000, v169
	v_pk_add_f32 v[102:103], v[102:103], v[240:241]
	v_lshlrev_b32_e32 v240, 16, v170
	v_and_b32_e32 v241, 0xffff0000, v170
	v_pk_add_f32 v[96:97], v[96:97], v[240:241]
	v_lshlrev_b32_e32 v240, 16, v171
	v_and_b32_e32 v241, 0xffff0000, v171
	v_pk_add_f32 v[98:99], v[98:99], v[240:241]
	s_add_u32 s98, s62, 0x43c00
	s_addc_u32 s99, s63, 0
	global_load_dwordx4 v[168:171], v205, s[98:99] sc0 sc1
	s_waitcnt vmcnt(8)
	v_lshlrev_b32_e32 v240, 16, v172
	v_and_b32_e32 v241, 0xffff0000, v172
	v_pk_add_f32 v[68:69], v[68:69], v[240:241]
	v_lshlrev_b32_e32 v240, 16, v173
	v_and_b32_e32 v241, 0xffff0000, v173
	v_pk_add_f32 v[70:71], v[70:71], v[240:241]
	v_lshlrev_b32_e32 v240, 16, v174
	v_and_b32_e32 v241, 0xffff0000, v174
	v_pk_add_f32 v[64:65], v[64:65], v[240:241]
	v_lshlrev_b32_e32 v240, 16, v175
	v_and_b32_e32 v241, 0xffff0000, v175
	v_pk_add_f32 v[66:67], v[66:67], v[240:241]
	s_add_u32 s42, s10, 0x0
	s_addc_u32 s43, s11, 0
	global_load_dwordx4 v[172:175], v203, s[42:43]
	s_waitcnt vmcnt(8)
	v_lshlrev_b32_e32 v240, 16, v176
	v_and_b32_e32 v241, 0xffff0000, v176
	v_pk_add_f32 v[60:61], v[60:61], v[240:241]
	v_lshlrev_b32_e32 v240, 16, v177
	v_and_b32_e32 v241, 0xffff0000, v177
	v_pk_add_f32 v[62:63], v[62:63], v[240:241]
	v_lshlrev_b32_e32 v240, 16, v178
	v_and_b32_e32 v241, 0xffff0000, v178
	v_pk_add_f32 v[56:57], v[56:57], v[240:241]
	v_lshlrev_b32_e32 v240, 16, v179
	v_and_b32_e32 v241, 0xffff0000, v179
	v_pk_add_f32 v[58:59], v[58:59], v[240:241]
	s_add_u32 s98, s10, 0x0
	s_addc_u32 s99, s11, 0
	global_load_dwordx4 v[176:179], v203, s[98:99] offset:16
	s_waitcnt vmcnt(8)
	v_lshlrev_b32_e32 v240, 16, v180
	v_and_b32_e32 v241, 0xffff0000, v180
	v_pk_add_f32 v[28:29], v[28:29], v[240:241]
	v_lshlrev_b32_e32 v240, 16, v181
	v_and_b32_e32 v241, 0xffff0000, v181
	v_pk_add_f32 v[30:31], v[30:31], v[240:241]
	v_lshlrev_b32_e32 v240, 16, v182
	v_and_b32_e32 v241, 0xffff0000, v182
	v_pk_add_f32 v[24:25], v[24:25], v[240:241]
	v_lshlrev_b32_e32 v240, 16, v183
	v_and_b32_e32 v241, 0xffff0000, v183
	v_pk_add_f32 v[26:27], v[26:27], v[240:241]
	s_add_u32 s42, s10, 0x200
	s_addc_u32 s43, s11, 0
	global_load_dwordx4 v[180:183], v203, s[42:43]
	s_waitcnt vmcnt(8)
	v_lshlrev_b32_e32 v240, 16, v206
	v_and_b32_e32 v241, 0xffff0000, v206
	v_pk_add_f32 v[52:53], v[52:53], v[240:241]
	v_lshlrev_b32_e32 v240, 16, v207
	v_and_b32_e32 v241, 0xffff0000, v207
	v_pk_add_f32 v[54:55], v[54:55], v[240:241]
	v_lshlrev_b32_e32 v240, 16, v208
	v_and_b32_e32 v241, 0xffff0000, v208
	v_pk_add_f32 v[48:49], v[48:49], v[240:241]
	v_lshlrev_b32_e32 v240, 16, v209
	v_and_b32_e32 v241, 0xffff0000, v209
	v_pk_add_f32 v[50:51], v[50:51], v[240:241]
	s_add_u32 s98, s10, 0x200
	s_addc_u32 s99, s11, 0
	global_load_dwordx4 v[206:209], v203, s[98:99] offset:16
	s_waitcnt vmcnt(8)
	v_lshlrev_b32_e32 v240, 16, v210
	v_and_b32_e32 v241, 0xffff0000, v210
	v_pk_add_f32 v[20:21], v[20:21], v[240:241]
	v_lshlrev_b32_e32 v240, 16, v211
	v_and_b32_e32 v241, 0xffff0000, v211
	v_pk_add_f32 v[22:23], v[22:23], v[240:241]
	v_lshlrev_b32_e32 v240, 16, v212
	v_and_b32_e32 v241, 0xffff0000, v212
	v_pk_add_f32 v[16:17], v[16:17], v[240:241]
	v_lshlrev_b32_e32 v240, 16, v213
	v_and_b32_e32 v241, 0xffff0000, v213
	v_pk_add_f32 v[18:19], v[18:19], v[240:241]
	s_add_u32 s42, s10, 0x10000
	s_addc_u32 s43, s11, 0
	global_load_dwordx4 v[210:213], v203, s[42:43]
	s_waitcnt vmcnt(8)
	v_lshlrev_b32_e32 v240, 16, v236
	v_and_b32_e32 v241, 0xffff0000, v236
	v_pk_add_f32 v[44:45], v[44:45], v[240:241]
	v_lshlrev_b32_e32 v240, 16, v237
	v_and_b32_e32 v241, 0xffff0000, v237
	v_pk_add_f32 v[46:47], v[46:47], v[240:241]
	v_lshlrev_b32_e32 v240, 16, v238
	v_and_b32_e32 v241, 0xffff0000, v238
	v_pk_add_f32 v[40:41], v[40:41], v[240:241]
	v_lshlrev_b32_e32 v240, 16, v239
	v_and_b32_e32 v241, 0xffff0000, v239
	v_pk_add_f32 v[42:43], v[42:43], v[240:241]
	s_add_u32 s98, s10, 0x10000
	s_addc_u32 s99, s11, 0
	global_load_dwordx4 v[236:239], v203, s[98:99] offset:16
	s_waitcnt vmcnt(8)
	v_lshlrev_b32_e32 v240, 16, v160
	v_and_b32_e32 v241, 0xffff0000, v160
	v_pk_add_f32 v[12:13], v[12:13], v[240:241]
	v_lshlrev_b32_e32 v240, 16, v161
	v_and_b32_e32 v241, 0xffff0000, v161
	v_pk_add_f32 v[14:15], v[14:15], v[240:241]
	v_lshlrev_b32_e32 v240, 16, v162
	v_and_b32_e32 v241, 0xffff0000, v162
	v_pk_add_f32 v[8:9], v[8:9], v[240:241]
	v_lshlrev_b32_e32 v240, 16, v163
	v_and_b32_e32 v241, 0xffff0000, v163
	v_pk_add_f32 v[10:11], v[10:11], v[240:241]
	s_add_u32 s42, s10, 0x10200
	s_addc_u32 s43, s11, 0
	global_load_dwordx4 v[160:163], v203, s[42:43]
	s_waitcnt vmcnt(8)
	v_lshlrev_b32_e32 v240, 16, v164
	v_and_b32_e32 v241, 0xffff0000, v164
	v_pk_add_f32 v[36:37], v[36:37], v[240:241]
	v_lshlrev_b32_e32 v240, 16, v165
	v_and_b32_e32 v241, 0xffff0000, v165
	v_pk_add_f32 v[38:39], v[38:39], v[240:241]
	v_lshlrev_b32_e32 v240, 16, v166
	v_and_b32_e32 v241, 0xffff0000, v166
	v_pk_add_f32 v[32:33], v[32:33], v[240:241]
	v_lshlrev_b32_e32 v240, 16, v167
	v_and_b32_e32 v241, 0xffff0000, v167
	v_pk_add_f32 v[34:35], v[34:35], v[240:241]
	s_add_u32 s98, s10, 0x10200
	s_addc_u32 s99, s11, 0
	global_load_dwordx4 v[164:167], v203, s[98:99] offset:16
	s_waitcnt vmcnt(8)
	v_lshlrev_b32_e32 v240, 16, v168
	v_and_b32_e32 v241, 0xffff0000, v168
	v_pk_add_f32 v[4:5], v[4:5], v[240:241]
	v_lshlrev_b32_e32 v240, 16, v169
	v_and_b32_e32 v241, 0xffff0000, v169
	v_pk_add_f32 v[6:7], v[6:7], v[240:241]
	v_lshlrev_b32_e32 v240, 16, v170
	v_and_b32_e32 v241, 0xffff0000, v170
	v_pk_add_f32 v[0:1], v[0:1], v[240:241]
	v_lshlrev_b32_e32 v240, 16, v171
	v_and_b32_e32 v241, 0xffff0000, v171
	v_pk_add_f32 v[2:3], v[2:3], v[240:241]
	s_add_u32 s42, s10, 0x20000
	s_addc_u32 s43, s11, 0
	global_load_dwordx4 v[168:171], v203, s[42:43]
	s_waitcnt vmcnt(8)
	v_pk_fma_f32 v[124:125], v[148:149], v[124:125], v[172:173]
	v_pk_fma_f32 v[126:127], v[150:151], v[126:127], v[174:175]
	s_add_u32 s98, s10, 0x0
	s_addc_u32 s99, s11, 0
	global_store_dwordx4 v203, v[124:127], s[98:99]
	s_add_u32 s42, s10, 0x20000
	s_addc_u32 s43, s11, 0
	global_load_dwordx4 v[172:175], v203, s[42:43] offset:16
	s_waitcnt vmcnt(9)
	v_pk_fma_f32 v[120:121], v[144:145], v[120:121], v[176:177]
	v_pk_fma_f32 v[122:123], v[146:147], v[122:123], v[178:179]
	s_add_u32 s98, s10, 0x0
	s_addc_u32 s99, s11, 0
	global_store_dwordx4 v203, v[120:123], s[98:99] offset:16
	s_add_u32 s42, s10, 0x20200
	s_addc_u32 s43, s11, 0
	global_load_dwordx4 v[176:179], v203, s[42:43]
	s_waitcnt vmcnt(10)
	v_pk_fma_f32 v[92:93], v[156:157], v[92:93], v[180:181]
	v_pk_fma_f32 v[94:95], v[158:159], v[94:95], v[182:183]
	s_add_u32 s98, s10, 0x200
	s_addc_u32 s99, s11, 0
	global_store_dwordx4 v203, v[92:95], s[98:99]
	s_add_u32 s42, s10, 0x20200
	s_addc_u32 s43, s11, 0
	global_load_dwordx4 v[180:183], v203, s[42:43] offset:16
	s_waitcnt vmcnt(11)
	v_pk_fma_f32 v[88:89], v[152:153], v[88:89], v[206:207]
	v_pk_fma_f32 v[90:91], v[154:155], v[90:91], v[208:209]
	s_add_u32 s98, s10, 0x200
	s_addc_u32 s99, s11, 0
	global_store_dwordx4 v203, v[88:91], s[98:99] offset:16
	s_add_u32 s42, s10, 0x30000
	s_addc_u32 s43, s11, 0
	global_load_dwordx4 v[206:209], v203, s[42:43]
	s_waitcnt vmcnt(12)
	v_pk_fma_f32 v[116:117], v[148:149], v[116:117], v[210:211]
	v_pk_fma_f32 v[118:119], v[150:151], v[118:119], v[212:213]
	s_add_u32 s98, s10, 0x10000
	s_addc_u32 s99, s11, 0
	global_store_dwordx4 v203, v[116:119], s[98:99]
	s_add_u32 s42, s10, 0x30000
	s_addc_u32 s43, s11, 0
	global_load_dwordx4 v[210:213], v203, s[42:43] offset:16
	s_waitcnt vmcnt(13)
	v_pk_fma_f32 v[112:113], v[144:145], v[112:113], v[236:237]
	v_pk_fma_f32 v[114:115], v[146:147], v[114:115], v[238:239]
	s_add_u32 s98, s10, 0x10000
	s_addc_u32 s99, s11, 0
	global_store_dwordx4 v203, v[112:115], s[98:99] offset:16
	s_add_u32 s42, s10, 0x30200
	s_addc_u32 s43, s11, 0
	global_load_dwordx4 v[236:239], v203, s[42:43]
	s_waitcnt vmcnt(14)
	v_pk_fma_f32 v[84:85], v[156:157], v[84:85], v[160:161]
	v_pk_fma_f32 v[86:87], v[158:159], v[86:87], v[162:163]
	s_add_u32 s98, s10, 0x10200
	s_addc_u32 s99, s11, 0
	global_store_dwordx4 v203, v[84:87], s[98:99]
	s_add_u32 s42, s10, 0x30200
	s_addc_u32 s43, s11, 0
	global_load_dwordx4 v[160:163], v203, s[42:43] offset:16
	s_waitcnt vmcnt(15)
	v_pk_fma_f32 v[80:81], v[152:153], v[80:81], v[164:165]
	v_pk_fma_f32 v[82:83], v[154:155], v[82:83], v[166:167]
	s_add_u32 s98, s10, 0x10200
	s_addc_u32 s99, s11, 0
	global_store_dwordx4 v203, v[80:83], s[98:99] offset:16
	s_add_u32 s42, s10, 0x80000
	s_addc_u32 s43, s11, 0
	global_load_dwordx4 v[164:167], v203, s[42:43]
	s_waitcnt vmcnt(16)
	v_pk_fma_f32 v[108:109], v[148:149], v[108:109], v[168:169]
	v_pk_fma_f32 v[110:111], v[150:151], v[110:111], v[170:171]
	s_add_u32 s98, s10, 0x20000
	s_addc_u32 s99, s11, 0
	global_store_dwordx4 v203, v[108:111], s[98:99]
	s_add_u32 s42, s10, 0x80000
	s_addc_u32 s43, s11, 0
	global_load_dwordx4 v[168:171], v203, s[42:43] offset:16
	s_waitcnt vmcnt(16)
	v_pk_fma_f32 v[104:105], v[144:145], v[104:105], v[172:173]
	v_pk_fma_f32 v[106:107], v[146:147], v[106:107], v[174:175]
	s_add_u32 s98, s10, 0x20000
	s_addc_u32 s99, s11, 0
	global_store_dwordx4 v203, v[104:107], s[98:99] offset:16
	s_add_u32 s42, s10, 0x80200
	s_addc_u32 s43, s11, 0
	global_load_dwordx4 v[172:175], v203, s[42:43]
	s_waitcnt vmcnt(16)
	v_pk_fma_f32 v[76:77], v[156:157], v[76:77], v[176:177]
	v_pk_fma_f32 v[78:79], v[158:159], v[78:79], v[178:179]
	s_add_u32 s98, s10, 0x20200
	s_addc_u32 s99, s11, 0
	global_store_dwordx4 v203, v[76:79], s[98:99]
	s_add_u32 s42, s10, 0x80200
	s_addc_u32 s43, s11, 0
	global_load_dwordx4 v[176:179], v203, s[42:43] offset:16
	s_waitcnt vmcnt(16)
	v_pk_fma_f32 v[72:73], v[152:153], v[72:73], v[180:181]
	v_pk_fma_f32 v[74:75], v[154:155], v[74:75], v[182:183]
	s_add_u32 s98, s10, 0x20200
	s_addc_u32 s99, s11, 0
	global_store_dwordx4 v203, v[72:75], s[98:99] offset:16
	s_add_u32 s42, s10, 0x90000
	s_addc_u32 s43, s11, 0
	global_load_dwordx4 v[180:183], v203, s[42:43]
	s_waitcnt vmcnt(16)
	v_pk_fma_f32 v[100:101], v[148:149], v[100:101], v[206:207]
	v_pk_fma_f32 v[102:103], v[150:151], v[102:103], v[208:209]
	s_add_u32 s98, s10, 0x30000
	s_addc_u32 s99, s11, 0
	global_store_dwordx4 v203, v[100:103], s[98:99]
	s_add_u32 s42, s10, 0x90000
	s_addc_u32 s43, s11, 0
	global_load_dwordx4 v[206:209], v203, s[42:43] offset:16
	s_waitcnt vmcnt(16)
	v_pk_fma_f32 v[96:97], v[144:145], v[96:97], v[210:211]
	v_pk_fma_f32 v[98:99], v[146:147], v[98:99], v[212:213]
	s_add_u32 s98, s10, 0x30000
	s_addc_u32 s99, s11, 0
	global_store_dwordx4 v203, v[96:99], s[98:99] offset:16
	s_add_u32 s42, s10, 0x90200
	s_addc_u32 s43, s11, 0
	global_load_dwordx4 v[210:213], v203, s[42:43]
	s_waitcnt vmcnt(16)
	v_pk_fma_f32 v[68:69], v[156:157], v[68:69], v[236:237]
	v_pk_fma_f32 v[70:71], v[158:159], v[70:71], v[238:239]
	s_add_u32 s98, s10, 0x30200
	s_addc_u32 s99, s11, 0
	global_store_dwordx4 v203, v[68:71], s[98:99]
	s_add_u32 s42, s10, 0x90200
	s_addc_u32 s43, s11, 0
	global_load_dwordx4 v[236:239], v203, s[42:43] offset:16
	s_waitcnt vmcnt(16)
	v_pk_fma_f32 v[64:65], v[152:153], v[64:65], v[160:161]
	v_pk_fma_f32 v[66:67], v[154:155], v[66:67], v[162:163]
	s_add_u32 s98, s10, 0x30200
	s_addc_u32 s99, s11, 0
	global_store_dwordx4 v203, v[64:67], s[98:99] offset:16
	s_add_u32 s42, s10, 0xa0000
	s_addc_u32 s43, s11, 0
	global_load_dwordx4 v[160:163], v203, s[42:43]
	s_waitcnt vmcnt(16)
	v_pk_fma_f32 v[60:61], v[148:149], v[60:61], v[164:165]
	v_pk_fma_f32 v[62:63], v[150:151], v[62:63], v[166:167]
	s_add_u32 s98, s10, 0x80000
	s_addc_u32 s99, s11, 0
	global_store_dwordx4 v203, v[60:63], s[98:99]
	s_add_u32 s42, s10, 0xa0000
	s_addc_u32 s43, s11, 0
	global_load_dwordx4 v[164:167], v203, s[42:43] offset:16
	s_waitcnt vmcnt(16)
	v_pk_fma_f32 v[56:57], v[144:145], v[56:57], v[168:169]
	v_pk_fma_f32 v[58:59], v[146:147], v[58:59], v[170:171]
	s_add_u32 s98, s10, 0x80000
	s_addc_u32 s99, s11, 0
	global_store_dwordx4 v203, v[56:59], s[98:99] offset:16
	s_add_u32 s42, s10, 0xa0200
	s_addc_u32 s43, s11, 0
	global_load_dwordx4 v[168:171], v203, s[42:43]
	s_waitcnt vmcnt(16)
	v_pk_fma_f32 v[28:29], v[156:157], v[28:29], v[172:173]
	v_pk_fma_f32 v[30:31], v[158:159], v[30:31], v[174:175]
	s_add_u32 s98, s10, 0x80200
	s_addc_u32 s99, s11, 0
	global_store_dwordx4 v203, v[28:31], s[98:99]
	s_add_u32 s42, s10, 0xa0200
	s_addc_u32 s43, s11, 0
	global_load_dwordx4 v[172:175], v203, s[42:43] offset:16
	s_waitcnt vmcnt(16)
	v_pk_fma_f32 v[24:25], v[152:153], v[24:25], v[176:177]
	v_pk_fma_f32 v[26:27], v[154:155], v[26:27], v[178:179]
	s_add_u32 s98, s10, 0x80200
	s_addc_u32 s99, s11, 0
	global_store_dwordx4 v203, v[24:27], s[98:99] offset:16
	s_waitcnt vmcnt(15)
	v_pk_fma_f32 v[52:53], v[148:149], v[52:53], v[180:181]
	v_pk_fma_f32 v[54:55], v[150:151], v[54:55], v[182:183]
	s_add_u32 s42, s10, 0x90000
	s_addc_u32 s43, s11, 0
	global_store_dwordx4 v203, v[52:55], s[42:43]
	s_waitcnt vmcnt(14)
	v_pk_fma_f32 v[48:49], v[144:145], v[48:49], v[206:207]
	v_pk_fma_f32 v[50:51], v[146:147], v[50:51], v[208:209]
	s_add_u32 s98, s10, 0x90000
	s_addc_u32 s99, s11, 0
	global_store_dwordx4 v203, v[48:51], s[98:99] offset:16
	s_waitcnt vmcnt(13)
	v_pk_fma_f32 v[20:21], v[156:157], v[20:21], v[210:211]
	v_pk_fma_f32 v[22:23], v[158:159], v[22:23], v[212:213]
	s_add_u32 s42, s10, 0x90200
	s_addc_u32 s43, s11, 0
	global_store_dwordx4 v203, v[20:23], s[42:43]
	s_waitcnt vmcnt(12)
	v_pk_fma_f32 v[16:17], v[152:153], v[16:17], v[236:237]
	v_pk_fma_f32 v[18:19], v[154:155], v[18:19], v[238:239]
	s_add_u32 s98, s10, 0x90200
	s_addc_u32 s99, s11, 0
	global_store_dwordx4 v203, v[16:19], s[98:99] offset:16
	s_waitcnt vmcnt(11)
	v_pk_fma_f32 v[44:45], v[148:149], v[44:45], v[160:161]
	v_pk_fma_f32 v[46:47], v[150:151], v[46:47], v[162:163]
	s_add_u32 s42, s10, 0xa0000
	s_addc_u32 s43, s11, 0
	global_store_dwordx4 v203, v[44:47], s[42:43]
	s_waitcnt vmcnt(10)
	v_pk_fma_f32 v[40:41], v[144:145], v[40:41], v[164:165]
	v_pk_fma_f32 v[42:43], v[146:147], v[42:43], v[166:167]
	s_add_u32 s98, s10, 0xa0000
	s_addc_u32 s99, s11, 0
	global_store_dwordx4 v203, v[40:43], s[98:99] offset:16
	s_waitcnt vmcnt(9)
	v_pk_fma_f32 v[12:13], v[156:157], v[12:13], v[168:169]
	v_pk_fma_f32 v[14:15], v[158:159], v[14:15], v[170:171]
	s_add_u32 s42, s10, 0xa0200
	s_addc_u32 s43, s11, 0
	global_store_dwordx4 v203, v[12:15], s[42:43]
	s_waitcnt vmcnt(8)
	v_pk_fma_f32 v[8:9], v[152:153], v[8:9], v[172:173]
	v_pk_fma_f32 v[10:11], v[154:155], v[10:11], v[174:175]
	s_add_u32 s98, s10, 0xa0200
	s_addc_u32 s99, s11, 0
	global_store_dwordx4 v203, v[8:11], s[98:99] offset:16
	s_branch .Lfq_predone
.Lfq_np2:
	s_add_u32 s42, s62, 0x0
	s_addc_u32 s43, s63, 0
	global_load_dwordx4 v[160:163], v205, s[42:43] sc0 sc1
	s_add_u32 s98, s62, 0x1000
	s_addc_u32 s99, s63, 0
	global_load_dwordx4 v[164:167], v205, s[98:99] sc0 sc1
	s_add_u32 s42, s62, 0x400
	s_addc_u32 s43, s63, 0
	global_load_dwordx4 v[168:171], v205, s[42:43] sc0 sc1
	s_add_u32 s98, s62, 0x1400
	s_addc_u32 s99, s63, 0
	global_load_dwordx4 v[172:175], v205, s[98:99] sc0 sc1
	s_add_u32 s42, s62, 0x800
	s_addc_u32 s43, s63, 0
	global_load_dwordx4 v[176:179], v205, s[42:43] sc0 sc1
	s_add_u32 s98, s62, 0x1800
	s_addc_u32 s99, s63, 0
	global_load_dwordx4 v[180:183], v205, s[98:99] sc0 sc1
	s_add_u32 s42, s62, 0xc00
	s_addc_u32 s43, s63, 0
	global_load_dwordx4 v[206:209], v205, s[42:43] sc0 sc1
	s_add_u32 s98, s62, 0x1c00
	s_addc_u32 s99, s63, 0
	global_load_dwordx4 v[210:213], v205, s[98:99] sc0 sc1
	s_add_u32 s42, s62, 0x2000
	s_addc_u32 s43, s63, 0
	global_load_dwordx4 v[236:239], v205, s[42:43] sc0 sc1
	s_waitcnt vmcnt(8)
	v_lshlrev_b32_e32 v240, 16, v160
	v_and_b32_e32 v241, 0xffff0000, v160
	v_pk_add_f32 v[124:125], v[124:125], v[240:241]
	v_lshlrev_b32_e32 v240, 16, v161
	v_and_b32_e32 v241, 0xffff0000, v161
	v_pk_add_f32 v[126:127], v[126:127], v[240:241]
	v_lshlrev_b32_e32 v240, 16, v162
	v_and_b32_e32 v241, 0xffff0000, v162
	v_pk_add_f32 v[120:121], v[120:121], v[240:241]
	v_lshlrev_b32_e32 v240, 16, v163
	v_and_b32_e32 v241, 0xffff0000, v163
	v_pk_add_f32 v[122:123], v[122:123], v[240:241]
	s_add_u32 s98, s62, 0x3000
	s_addc_u32 s99, s63, 0
	global_load_dwordx4 v[160:163], v205, s[98:99] sc0 sc1
	s_waitcnt vmcnt(8)
	v_lshlrev_b32_e32 v240, 16, v164
	v_and_b32_e32 v241, 0xffff0000, v164
	v_pk_add_f32 v[92:93], v[92:93], v[240:241]
	v_lshlrev_b32_e32 v240, 16, v165
	v_and_b32_e32 v241, 0xffff0000, v165
	v_pk_add_f32 v[94:95], v[94:95], v[240:241]
	v_lshlrev_b32_e32 v240, 16, v166
	v_and_b32_e32 v241, 0xffff0000, v166
	v_pk_add_f32 v[88:89], v[88:89], v[240:241]
	v_lshlrev_b32_e32 v240, 16, v167
	v_and_b32_e32 v241, 0xffff0000, v167
	v_pk_add_f32 v[90:91], v[90:91], v[240:241]
	s_add_u32 s42, s62, 0x2400
	s_addc_u32 s43, s63, 0
	global_load_dwordx4 v[164:167], v205, s[42:43] sc0 sc1
	s_waitcnt vmcnt(8)
	v_lshlrev_b32_e32 v240, 16, v168
	v_and_b32_e32 v241, 0xffff0000, v168
	v_pk_add_f32 v[116:117], v[116:117], v[240:241]
	v_lshlrev_b32_e32 v240, 16, v169
	v_and_b32_e32 v241, 0xffff0000, v169
	v_pk_add_f32 v[118:119], v[118:119], v[240:241]
	v_lshlrev_b32_e32 v240, 16, v170
	v_and_b32_e32 v241, 0xffff0000, v170
	v_pk_add_f32 v[112:113], v[112:113], v[240:241]
	v_lshlrev_b32_e32 v240, 16, v171
	v_and_b32_e32 v241, 0xffff0000, v171
	v_pk_add_f32 v[114:115], v[114:115], v[240:241]
	s_add_u32 s98, s62, 0x3400
	s_addc_u32 s99, s63, 0
	global_load_dwordx4 v[168:171], v205, s[98:99] sc0 sc1
	s_waitcnt vmcnt(8)
	v_lshlrev_b32_e32 v240, 16, v172
	v_and_b32_e32 v241, 0xffff0000, v172
	v_pk_add_f32 v[84:85], v[84:85], v[240:241]
	v_lshlrev_b32_e32 v240, 16, v173
	v_and_b32_e32 v241, 0xffff0000, v173
	v_pk_add_f32 v[86:87], v[86:87], v[240:241]
	v_lshlrev_b32_e32 v240, 16, v174
	v_and_b32_e32 v241, 0xffff0000, v174
	v_pk_add_f32 v[80:81], v[80:81], v[240:241]
	v_lshlrev_b32_e32 v240, 16, v175
	v_and_b32_e32 v241, 0xffff0000, v175
	v_pk_add_f32 v[82:83], v[82:83], v[240:241]
	s_add_u32 s42, s62, 0x2800
	s_addc_u32 s43, s63, 0
	global_load_dwordx4 v[172:175], v205, s[42:43] sc0 sc1
	s_waitcnt vmcnt(8)
	v_lshlrev_b32_e32 v240, 16, v176
	v_and_b32_e32 v241, 0xffff0000, v176
	v_pk_add_f32 v[108:109], v[108:109], v[240:241]
	v_lshlrev_b32_e32 v240, 16, v177
	v_and_b32_e32 v241, 0xffff0000, v177
	v_pk_add_f32 v[110:111], v[110:111], v[240:241]
	v_lshlrev_b32_e32 v240, 16, v178
	v_and_b32_e32 v241, 0xffff0000, v178
	v_pk_add_f32 v[104:105], v[104:105], v[240:241]
	v_lshlrev_b32_e32 v240, 16, v179
	v_and_b32_e32 v241, 0xffff0000, v179
	v_pk_add_f32 v[106:107], v[106:107], v[240:241]
	s_add_u32 s98, s62, 0x3800
	s_addc_u32 s99, s63, 0
	global_load_dwordx4 v[176:179], v205, s[98:99] sc0 sc1
	s_waitcnt vmcnt(8)
	v_lshlrev_b32_e32 v240, 16, v180
	v_and_b32_e32 v241, 0xffff0000, v180
	v_pk_add_f32 v[76:77], v[76:77], v[240:241]
	v_lshlrev_b32_e32 v240, 16, v181
	v_and_b32_e32 v241, 0xffff0000, v181
	v_pk_add_f32 v[78:79], v[78:79], v[240:241]
	v_lshlrev_b32_e32 v240, 16, v182
	v_and_b32_e32 v241, 0xffff0000, v182
	v_pk_add_f32 v[72:73], v[72:73], v[240:241]
	v_lshlrev_b32_e32 v240, 16, v183
	v_and_b32_e32 v241, 0xffff0000, v183
	v_pk_add_f32 v[74:75], v[74:75], v[240:241]
	s_add_u32 s42, s62, 0x2c00
	s_addc_u32 s43, s63, 0
	global_load_dwordx4 v[180:183], v205, s[42:43] sc0 sc1
	s_waitcnt vmcnt(8)
	v_lshlrev_b32_e32 v240, 16, v206
	v_and_b32_e32 v241, 0xffff0000, v206
	v_pk_add_f32 v[100:101], v[100:101], v[240:241]
	v_lshlrev_b32_e32 v240, 16, v207
	v_and_b32_e32 v241, 0xffff0000, v207
	v_pk_add_f32 v[102:103], v[102:103], v[240:241]
	v_lshlrev_b32_e32 v240, 16, v208
	v_and_b32_e32 v241, 0xffff0000, v208
	v_pk_add_f32 v[96:97], v[96:97], v[240:241]
	v_lshlrev_b32_e32 v240, 16, v209
	v_and_b32_e32 v241, 0xffff0000, v209
	v_pk_add_f32 v[98:99], v[98:99], v[240:241]
	s_add_u32 s98, s62, 0x3c00
	s_addc_u32 s99, s63, 0
	global_load_dwordx4 v[206:209], v205, s[98:99] sc0 sc1
	s_waitcnt vmcnt(8)
	v_lshlrev_b32_e32 v240, 16, v210
	v_and_b32_e32 v241, 0xffff0000, v210
	v_pk_add_f32 v[68:69], v[68:69], v[240:241]
	v_lshlrev_b32_e32 v240, 16, v211
	v_and_b32_e32 v241, 0xffff0000, v211
	v_pk_add_f32 v[70:71], v[70:71], v[240:241]
	v_lshlrev_b32_e32 v240, 16, v212
	v_and_b32_e32 v241, 0xffff0000, v212
	v_pk_add_f32 v[64:65], v[64:65], v[240:241]
	v_lshlrev_b32_e32 v240, 16, v213
	v_and_b32_e32 v241, 0xffff0000, v213
	v_pk_add_f32 v[66:67], v[66:67], v[240:241]
	s_add_u32 s42, s62, 0x20000
	s_addc_u32 s43, s63, 0
	global_load_dwordx4 v[210:213], v205, s[42:43] sc0 sc1
	s_waitcnt vmcnt(8)
	v_lshlrev_b32_e32 v240, 16, v236
	v_and_b32_e32 v241, 0xffff0000, v236
	v_pk_add_f32 v[60:61], v[60:61], v[240:241]
	v_lshlrev_b32_e32 v240, 16, v237
	v_and_b32_e32 v241, 0xffff0000, v237
	v_pk_add_f32 v[62:63], v[62:63], v[240:241]
	v_lshlrev_b32_e32 v240, 16, v238
	v_and_b32_e32 v241, 0xffff0000, v238
	v_pk_add_f32 v[56:57], v[56:57], v[240:241]
	v_lshlrev_b32_e32 v240, 16, v239
	v_and_b32_e32 v241, 0xffff0000, v239
	v_pk_add_f32 v[58:59], v[58:59], v[240:241]
	s_add_u32 s98, s62, 0x21000
	s_addc_u32 s99, s63, 0
	global_load_dwordx4 v[236:239], v205, s[98:99] sc0 sc1
	s_waitcnt vmcnt(8)
	v_lshlrev_b32_e32 v240, 16, v160
	v_and_b32_e32 v241, 0xffff0000, v160
	v_pk_add_f32 v[28:29], v[28:29], v[240:241]
	v_lshlrev_b32_e32 v240, 16, v161
	v_and_b32_e32 v241, 0xffff0000, v161
	v_pk_add_f32 v[30:31], v[30:31], v[240:241]
	v_lshlrev_b32_e32 v240, 16, v162
	v_and_b32_e32 v241, 0xffff0000, v162
	v_pk_add_f32 v[24:25], v[24:25], v[240:241]
	v_lshlrev_b32_e32 v240, 16, v163
	v_and_b32_e32 v241, 0xffff0000, v163
	v_pk_add_f32 v[26:27], v[26:27], v[240:241]
	s_add_u32 s42, s62, 0x20400
	s_addc_u32 s43, s63, 0
	global_load_dwordx4 v[160:163], v205, s[42:43] sc0 sc1
	s_waitcnt vmcnt(8)
	v_lshlrev_b32_e32 v240, 16, v164
	v_and_b32_e32 v241, 0xffff0000, v164
	v_pk_add_f32 v[52:53], v[52:53], v[240:241]
	v_lshlrev_b32_e32 v240, 16, v165
	v_and_b32_e32 v241, 0xffff0000, v165
	v_pk_add_f32 v[54:55], v[54:55], v[240:241]
	v_lshlrev_b32_e32 v240, 16, v166
	v_and_b32_e32 v241, 0xffff0000, v166
	v_pk_add_f32 v[48:49], v[48:49], v[240:241]
	v_lshlrev_b32_e32 v240, 16, v167
	v_and_b32_e32 v241, 0xffff0000, v167
	v_pk_add_f32 v[50:51], v[50:51], v[240:241]
	s_add_u32 s98, s62, 0x21400
	s_addc_u32 s99, s63, 0
	global_load_dwordx4 v[164:167], v205, s[98:99] sc0 sc1
	s_waitcnt vmcnt(8)
	v_lshlrev_b32_e32 v240, 16, v168
	v_and_b32_e32 v241, 0xffff0000, v168
	v_pk_add_f32 v[20:21], v[20:21], v[240:241]
	v_lshlrev_b32_e32 v240, 16, v169
	v_and_b32_e32 v241, 0xffff0000, v169
	v_pk_add_f32 v[22:23], v[22:23], v[240:241]
	v_lshlrev_b32_e32 v240, 16, v170
	v_and_b32_e32 v241, 0xffff0000, v170
	v_pk_add_f32 v[16:17], v[16:17], v[240:241]
	v_lshlrev_b32_e32 v240, 16, v171
	v_and_b32_e32 v241, 0xffff0000, v171
	v_pk_add_f32 v[18:19], v[18:19], v[240:241]
	s_add_u32 s42, s62, 0x20800
	s_addc_u32 s43, s63, 0
	global_load_dwordx4 v[168:171], v205, s[42:43] sc0 sc1
	s_waitcnt vmcnt(8)
	v_lshlrev_b32_e32 v240, 16, v172
	v_and_b32_e32 v241, 0xffff0000, v172
	v_pk_add_f32 v[44:45], v[44:45], v[240:241]
	v_lshlrev_b32_e32 v240, 16, v173
	v_and_b32_e32 v241, 0xffff0000, v173
	v_pk_add_f32 v[46:47], v[46:47], v[240:241]
	v_lshlrev_b32_e32 v240, 16, v174
	v_and_b32_e32 v241, 0xffff0000, v174
	v_pk_add_f32 v[40:41], v[40:41], v[240:241]
	v_lshlrev_b32_e32 v240, 16, v175
	v_and_b32_e32 v241, 0xffff0000, v175
	v_pk_add_f32 v[42:43], v[42:43], v[240:241]
	s_add_u32 s98, s62, 0x21800
	s_addc_u32 s99, s63, 0
	global_load_dwordx4 v[172:175], v205, s[98:99] sc0 sc1
	s_waitcnt vmcnt(8)
	v_lshlrev_b32_e32 v240, 16, v176
	v_and_b32_e32 v241, 0xffff0000, v176
	v_pk_add_f32 v[12:13], v[12:13], v[240:241]
	v_lshlrev_b32_e32 v240, 16, v177
	v_and_b32_e32 v241, 0xffff0000, v177
	v_pk_add_f32 v[14:15], v[14:15], v[240:241]
	v_lshlrev_b32_e32 v240, 16, v178
	v_and_b32_e32 v241, 0xffff0000, v178
	v_pk_add_f32 v[8:9], v[8:9], v[240:241]
	v_lshlrev_b32_e32 v240, 16, v179
	v_and_b32_e32 v241, 0xffff0000, v179
	v_pk_add_f32 v[10:11], v[10:11], v[240:241]
	s_add_u32 s42, s62, 0x20c00
	s_addc_u32 s43, s63, 0
	global_load_dwordx4 v[176:179], v205, s[42:43] sc0 sc1
	s_waitcnt vmcnt(8)
	v_lshlrev_b32_e32 v240, 16, v180
	v_and_b32_e32 v241, 0xffff0000, v180
	v_pk_add_f32 v[36:37], v[36:37], v[240:241]
	v_lshlrev_b32_e32 v240, 16, v181
	v_and_b32_e32 v241, 0xffff0000, v181
	v_pk_add_f32 v[38:39], v[38:39], v[240:241]
	v_lshlrev_b32_e32 v240, 16, v182
	v_and_b32_e32 v241, 0xffff0000, v182
	v_pk_add_f32 v[32:33], v[32:33], v[240:241]
	v_lshlrev_b32_e32 v240, 16, v183
	v_and_b32_e32 v241, 0xffff0000, v183
	v_pk_add_f32 v[34:35], v[34:35], v[240:241]
	s_add_u32 s98, s62, 0x21c00
	s_addc_u32 s99, s63, 0
	global_load_dwordx4 v[180:183], v205, s[98:99] sc0 sc1
	s_waitcnt vmcnt(8)
	v_lshlrev_b32_e32 v240, 16, v206
	v_and_b32_e32 v241, 0xffff0000, v206
	v_pk_add_f32 v[4:5], v[4:5], v[240:241]
	v_lshlrev_b32_e32 v240, 16, v207
	v_and_b32_e32 v241, 0xffff0000, v207
	v_pk_add_f32 v[6:7], v[6:7], v[240:241]
	v_lshlrev_b32_e32 v240, 16, v208
	v_and_b32_e32 v241, 0xffff0000, v208
	v_pk_add_f32 v[0:1], v[0:1], v[240:241]
	v_lshlrev_b32_e32 v240, 16, v209
	v_and_b32_e32 v241, 0xffff0000, v209
	v_pk_add_f32 v[2:3], v[2:3], v[240:241]
	s_add_u32 s42, s62, 0x22000
	s_addc_u32 s43, s63, 0
	global_load_dwordx4 v[206:209], v205, s[42:43] sc0 sc1
	s_waitcnt vmcnt(8)
	v_lshlrev_b32_e32 v240, 16, v210
	v_and_b32_e32 v241, 0xffff0000, v210
	v_pk_add_f32 v[124:125], v[124:125], v[240:241]
	v_lshlrev_b32_e32 v240, 16, v211
	v_and_b32_e32 v241, 0xffff0000, v211
	v_pk_add_f32 v[126:127], v[126:127], v[240:241]
	v_lshlrev_b32_e32 v240, 16, v212
	v_and_b32_e32 v241, 0xffff0000, v212
	v_pk_add_f32 v[120:121], v[120:121], v[240:241]
	v_lshlrev_b32_e32 v240, 16, v213
	v_and_b32_e32 v241, 0xffff0000, v213
	v_pk_add_f32 v[122:123], v[122:123], v[240:241]
	s_add_u32 s98, s62, 0x23000
	s_addc_u32 s99, s63, 0
	global_load_dwordx4 v[210:213], v205, s[98:99] sc0 sc1
	s_waitcnt vmcnt(8)
	v_lshlrev_b32_e32 v240, 16, v236
	v_and_b32_e32 v241, 0xffff0000, v236
	v_pk_add_f32 v[92:93], v[92:93], v[240:241]
	v_lshlrev_b32_e32 v240, 16, v237
	v_and_b32_e32 v241, 0xffff0000, v237
	v_pk_add_f32 v[94:95], v[94:95], v[240:241]
	v_lshlrev_b32_e32 v240, 16, v238
	v_and_b32_e32 v241, 0xffff0000, v238
	v_pk_add_f32 v[88:89], v[88:89], v[240:241]
	v_lshlrev_b32_e32 v240, 16, v239
	v_and_b32_e32 v241, 0xffff0000, v239
	v_pk_add_f32 v[90:91], v[90:91], v[240:241]
	s_add_u32 s42, s62, 0x22400
	s_addc_u32 s43, s63, 0
	global_load_dwordx4 v[236:239], v205, s[42:43] sc0 sc1
	s_waitcnt vmcnt(8)
	v_lshlrev_b32_e32 v240, 16, v160
	v_and_b32_e32 v241, 0xffff0000, v160
	v_pk_add_f32 v[116:117], v[116:117], v[240:241]
	v_lshlrev_b32_e32 v240, 16, v161
	v_and_b32_e32 v241, 0xffff0000, v161
	v_pk_add_f32 v[118:119], v[118:119], v[240:241]
	v_lshlrev_b32_e32 v240, 16, v162
	v_and_b32_e32 v241, 0xffff0000, v162
	v_pk_add_f32 v[112:113], v[112:113], v[240:241]
	v_lshlrev_b32_e32 v240, 16, v163
	v_and_b32_e32 v241, 0xffff0000, v163
	v_pk_add_f32 v[114:115], v[114:115], v[240:241]
	s_add_u32 s98, s62, 0x23400
	s_addc_u32 s99, s63, 0
	global_load_dwordx4 v[160:163], v205, s[98:99] sc0 sc1
	s_waitcnt vmcnt(8)
	v_lshlrev_b32_e32 v240, 16, v164
	v_and_b32_e32 v241, 0xffff0000, v164
	v_pk_add_f32 v[84:85], v[84:85], v[240:241]
	v_lshlrev_b32_e32 v240, 16, v165
	v_and_b32_e32 v241, 0xffff0000, v165
	v_pk_add_f32 v[86:87], v[86:87], v[240:241]
	v_lshlrev_b32_e32 v240, 16, v166
	v_and_b32_e32 v241, 0xffff0000, v166
	v_pk_add_f32 v[80:81], v[80:81], v[240:241]
	v_lshlrev_b32_e32 v240, 16, v167
	v_and_b32_e32 v241, 0xffff0000, v167
	v_pk_add_f32 v[82:83], v[82:83], v[240:241]
	s_add_u32 s42, s62, 0x22800
	s_addc_u32 s43, s63, 0
	global_load_dwordx4 v[164:167], v205, s[42:43] sc0 sc1
	s_waitcnt vmcnt(8)
	v_lshlrev_b32_e32 v240, 16, v168
	v_and_b32_e32 v241, 0xffff0000, v168
	v_pk_add_f32 v[108:109], v[108:109], v[240:241]
	v_lshlrev_b32_e32 v240, 16, v169
	v_and_b32_e32 v241, 0xffff0000, v169
	v_pk_add_f32 v[110:111], v[110:111], v[240:241]
	v_lshlrev_b32_e32 v240, 16, v170
	v_and_b32_e32 v241, 0xffff0000, v170
	v_pk_add_f32 v[104:105], v[104:105], v[240:241]
	v_lshlrev_b32_e32 v240, 16, v171
	v_and_b32_e32 v241, 0xffff0000, v171
	v_pk_add_f32 v[106:107], v[106:107], v[240:241]
	s_add_u32 s98, s62, 0x23800
	s_addc_u32 s99, s63, 0
	global_load_dwordx4 v[168:171], v205, s[98:99] sc0 sc1
	s_waitcnt vmcnt(8)
	v_lshlrev_b32_e32 v240, 16, v172
	v_and_b32_e32 v241, 0xffff0000, v172
	v_pk_add_f32 v[76:77], v[76:77], v[240:241]
	v_lshlrev_b32_e32 v240, 16, v173
	v_and_b32_e32 v241, 0xffff0000, v173
	v_pk_add_f32 v[78:79], v[78:79], v[240:241]
	v_lshlrev_b32_e32 v240, 16, v174
	v_and_b32_e32 v241, 0xffff0000, v174
	v_pk_add_f32 v[72:73], v[72:73], v[240:241]
	v_lshlrev_b32_e32 v240, 16, v175
	v_and_b32_e32 v241, 0xffff0000, v175
	v_pk_add_f32 v[74:75], v[74:75], v[240:241]
	s_add_u32 s42, s62, 0x22c00
	s_addc_u32 s43, s63, 0
	global_load_dwordx4 v[172:175], v205, s[42:43] sc0 sc1
	s_waitcnt vmcnt(8)
	v_lshlrev_b32_e32 v240, 16, v176
	v_and_b32_e32 v241, 0xffff0000, v176
	v_pk_add_f32 v[100:101], v[100:101], v[240:241]
	v_lshlrev_b32_e32 v240, 16, v177
	v_and_b32_e32 v241, 0xffff0000, v177
	v_pk_add_f32 v[102:103], v[102:103], v[240:241]
	v_lshlrev_b32_e32 v240, 16, v178
	v_and_b32_e32 v241, 0xffff0000, v178
	v_pk_add_f32 v[96:97], v[96:97], v[240:241]
	v_lshlrev_b32_e32 v240, 16, v179
	v_and_b32_e32 v241, 0xffff0000, v179
	v_pk_add_f32 v[98:99], v[98:99], v[240:241]
	s_add_u32 s98, s62, 0x23c00
	s_addc_u32 s99, s63, 0
	global_load_dwordx4 v[176:179], v205, s[98:99] sc0 sc1
	s_waitcnt vmcnt(8)
	v_lshlrev_b32_e32 v240, 16, v180
	v_and_b32_e32 v241, 0xffff0000, v180
	v_pk_add_f32 v[68:69], v[68:69], v[240:241]
	v_lshlrev_b32_e32 v240, 16, v181
	v_and_b32_e32 v241, 0xffff0000, v181
	v_pk_add_f32 v[70:71], v[70:71], v[240:241]
	v_lshlrev_b32_e32 v240, 16, v182
	v_and_b32_e32 v241, 0xffff0000, v182
	v_pk_add_f32 v[64:65], v[64:65], v[240:241]
	v_lshlrev_b32_e32 v240, 16, v183
	v_and_b32_e32 v241, 0xffff0000, v183
	v_pk_add_f32 v[66:67], v[66:67], v[240:241]
	s_add_u32 s42, s10, 0x0
	s_addc_u32 s43, s11, 0
	global_load_dwordx4 v[180:183], v203, s[42:43]
	s_waitcnt vmcnt(8)
	v_lshlrev_b32_e32 v240, 16, v206
	v_and_b32_e32 v241, 0xffff0000, v206
	v_pk_add_f32 v[60:61], v[60:61], v[240:241]
	v_lshlrev_b32_e32 v240, 16, v207
	v_and_b32_e32 v241, 0xffff0000, v207
	v_pk_add_f32 v[62:63], v[62:63], v[240:241]
	v_lshlrev_b32_e32 v240, 16, v208
	v_and_b32_e32 v241, 0xffff0000, v208
	v_pk_add_f32 v[56:57], v[56:57], v[240:241]
	v_lshlrev_b32_e32 v240, 16, v209
	v_and_b32_e32 v241, 0xffff0000, v209
	v_pk_add_f32 v[58:59], v[58:59], v[240:241]
	s_add_u32 s98, s10, 0x0
	s_addc_u32 s99, s11, 0
	global_load_dwordx4 v[206:209], v203, s[98:99] offset:16
	s_waitcnt vmcnt(8)
	v_lshlrev_b32_e32 v240, 16, v210
	v_and_b32_e32 v241, 0xffff0000, v210
	v_pk_add_f32 v[28:29], v[28:29], v[240:241]
	v_lshlrev_b32_e32 v240, 16, v211
	v_and_b32_e32 v241, 0xffff0000, v211
	v_pk_add_f32 v[30:31], v[30:31], v[240:241]
	v_lshlrev_b32_e32 v240, 16, v212
	v_and_b32_e32 v241, 0xffff0000, v212
	v_pk_add_f32 v[24:25], v[24:25], v[240:241]
	v_lshlrev_b32_e32 v240, 16, v213
	v_and_b32_e32 v241, 0xffff0000, v213
	v_pk_add_f32 v[26:27], v[26:27], v[240:241]
	s_add_u32 s42, s10, 0x200
	s_addc_u32 s43, s11, 0
	global_load_dwordx4 v[210:213], v203, s[42:43]
	s_waitcnt vmcnt(8)
	v_lshlrev_b32_e32 v240, 16, v236
	v_and_b32_e32 v241, 0xffff0000, v236
	v_pk_add_f32 v[52:53], v[52:53], v[240:241]
	v_lshlrev_b32_e32 v240, 16, v237
	v_and_b32_e32 v241, 0xffff0000, v237
	v_pk_add_f32 v[54:55], v[54:55], v[240:241]
	v_lshlrev_b32_e32 v240, 16, v238
	v_and_b32_e32 v241, 0xffff0000, v238
	v_pk_add_f32 v[48:49], v[48:49], v[240:241]
	v_lshlrev_b32_e32 v240, 16, v239
	v_and_b32_e32 v241, 0xffff0000, v239
	v_pk_add_f32 v[50:51], v[50:51], v[240:241]
	s_add_u32 s98, s10, 0x200
	s_addc_u32 s99, s11, 0
	global_load_dwordx4 v[236:239], v203, s[98:99] offset:16
	s_waitcnt vmcnt(8)
	v_lshlrev_b32_e32 v240, 16, v160
	v_and_b32_e32 v241, 0xffff0000, v160
	v_pk_add_f32 v[20:21], v[20:21], v[240:241]
	v_lshlrev_b32_e32 v240, 16, v161
	v_and_b32_e32 v241, 0xffff0000, v161
	v_pk_add_f32 v[22:23], v[22:23], v[240:241]
	v_lshlrev_b32_e32 v240, 16, v162
	v_and_b32_e32 v241, 0xffff0000, v162
	v_pk_add_f32 v[16:17], v[16:17], v[240:241]
	v_lshlrev_b32_e32 v240, 16, v163
	v_and_b32_e32 v241, 0xffff0000, v163
	v_pk_add_f32 v[18:19], v[18:19], v[240:241]
	s_add_u32 s42, s10, 0x10000
	s_addc_u32 s43, s11, 0
	global_load_dwordx4 v[160:163], v203, s[42:43]
	s_waitcnt vmcnt(8)
	v_lshlrev_b32_e32 v240, 16, v164
	v_and_b32_e32 v241, 0xffff0000, v164
	v_pk_add_f32 v[44:45], v[44:45], v[240:241]
	v_lshlrev_b32_e32 v240, 16, v165
	v_and_b32_e32 v241, 0xffff0000, v165
	v_pk_add_f32 v[46:47], v[46:47], v[240:241]
	v_lshlrev_b32_e32 v240, 16, v166
	v_and_b32_e32 v241, 0xffff0000, v166
	v_pk_add_f32 v[40:41], v[40:41], v[240:241]
	v_lshlrev_b32_e32 v240, 16, v167
	v_and_b32_e32 v241, 0xffff0000, v167
	v_pk_add_f32 v[42:43], v[42:43], v[240:241]
	s_add_u32 s98, s10, 0x10000
	s_addc_u32 s99, s11, 0
	global_load_dwordx4 v[164:167], v203, s[98:99] offset:16
	s_waitcnt vmcnt(8)
	v_lshlrev_b32_e32 v240, 16, v168
	v_and_b32_e32 v241, 0xffff0000, v168
	v_pk_add_f32 v[12:13], v[12:13], v[240:241]
	v_lshlrev_b32_e32 v240, 16, v169
	v_and_b32_e32 v241, 0xffff0000, v169
	v_pk_add_f32 v[14:15], v[14:15], v[240:241]
	v_lshlrev_b32_e32 v240, 16, v170
	v_and_b32_e32 v241, 0xffff0000, v170
	v_pk_add_f32 v[8:9], v[8:9], v[240:241]
	v_lshlrev_b32_e32 v240, 16, v171
	v_and_b32_e32 v241, 0xffff0000, v171
	v_pk_add_f32 v[10:11], v[10:11], v[240:241]
	s_add_u32 s42, s10, 0x10200
	s_addc_u32 s43, s11, 0
	global_load_dwordx4 v[168:171], v203, s[42:43]
	s_waitcnt vmcnt(8)
	v_lshlrev_b32_e32 v240, 16, v172
	v_and_b32_e32 v241, 0xffff0000, v172
	v_pk_add_f32 v[36:37], v[36:37], v[240:241]
	v_lshlrev_b32_e32 v240, 16, v173
	v_and_b32_e32 v241, 0xffff0000, v173
	v_pk_add_f32 v[38:39], v[38:39], v[240:241]
	v_lshlrev_b32_e32 v240, 16, v174
	v_and_b32_e32 v241, 0xffff0000, v174
	v_pk_add_f32 v[32:33], v[32:33], v[240:241]
	v_lshlrev_b32_e32 v240, 16, v175
	v_and_b32_e32 v241, 0xffff0000, v175
	v_pk_add_f32 v[34:35], v[34:35], v[240:241]
	s_add_u32 s98, s10, 0x10200
	s_addc_u32 s99, s11, 0
	global_load_dwordx4 v[172:175], v203, s[98:99] offset:16
	s_waitcnt vmcnt(8)
	v_lshlrev_b32_e32 v240, 16, v176
	v_and_b32_e32 v241, 0xffff0000, v176
	v_pk_add_f32 v[4:5], v[4:5], v[240:241]
	v_lshlrev_b32_e32 v240, 16, v177
	v_and_b32_e32 v241, 0xffff0000, v177
	v_pk_add_f32 v[6:7], v[6:7], v[240:241]
	v_lshlrev_b32_e32 v240, 16, v178
	v_and_b32_e32 v241, 0xffff0000, v178
	v_pk_add_f32 v[0:1], v[0:1], v[240:241]
	v_lshlrev_b32_e32 v240, 16, v179
	v_and_b32_e32 v241, 0xffff0000, v179
	v_pk_add_f32 v[2:3], v[2:3], v[240:241]
	s_add_u32 s42, s10, 0x20000
	s_addc_u32 s43, s11, 0
	global_load_dwordx4 v[176:179], v203, s[42:43]
	s_waitcnt vmcnt(8)
	v_pk_fma_f32 v[124:125], v[148:149], v[124:125], v[180:181]
	v_pk_fma_f32 v[126:127], v[150:151], v[126:127], v[182:183]
	s_add_u32 s98, s10, 0x0
	s_addc_u32 s99, s11, 0
	global_store_dwordx4 v203, v[124:127], s[98:99]
	s_add_u32 s42, s10, 0x20000
	s_addc_u32 s43, s11, 0
	global_load_dwordx4 v[180:183], v203, s[42:43] offset:16
	s_waitcnt vmcnt(9)
	v_pk_fma_f32 v[120:121], v[144:145], v[120:121], v[206:207]
	v_pk_fma_f32 v[122:123], v[146:147], v[122:123], v[208:209]
	s_add_u32 s98, s10, 0x0
	s_addc_u32 s99, s11, 0
	global_store_dwordx4 v203, v[120:123], s[98:99] offset:16
	s_add_u32 s42, s10, 0x20200
	s_addc_u32 s43, s11, 0
	global_load_dwordx4 v[206:209], v203, s[42:43]
	s_waitcnt vmcnt(10)
	v_pk_fma_f32 v[92:93], v[156:157], v[92:93], v[210:211]
	v_pk_fma_f32 v[94:95], v[158:159], v[94:95], v[212:213]
	s_add_u32 s98, s10, 0x200
	s_addc_u32 s99, s11, 0
	global_store_dwordx4 v203, v[92:95], s[98:99]
	s_add_u32 s42, s10, 0x20200
	s_addc_u32 s43, s11, 0
	global_load_dwordx4 v[210:213], v203, s[42:43] offset:16
	s_waitcnt vmcnt(11)
	v_pk_fma_f32 v[88:89], v[152:153], v[88:89], v[236:237]
	v_pk_fma_f32 v[90:91], v[154:155], v[90:91], v[238:239]
	s_add_u32 s98, s10, 0x200
	s_addc_u32 s99, s11, 0
	global_store_dwordx4 v203, v[88:91], s[98:99] offset:16
	s_add_u32 s42, s10, 0x30000
	s_addc_u32 s43, s11, 0
	global_load_dwordx4 v[236:239], v203, s[42:43]
	s_waitcnt vmcnt(12)
	v_pk_fma_f32 v[116:117], v[148:149], v[116:117], v[160:161]
	v_pk_fma_f32 v[118:119], v[150:151], v[118:119], v[162:163]
	s_add_u32 s98, s10, 0x10000
	s_addc_u32 s99, s11, 0
	global_store_dwordx4 v203, v[116:119], s[98:99]
	s_add_u32 s42, s10, 0x30000
	s_addc_u32 s43, s11, 0
	global_load_dwordx4 v[160:163], v203, s[42:43] offset:16
	s_waitcnt vmcnt(13)
	v_pk_fma_f32 v[112:113], v[144:145], v[112:113], v[164:165]
	v_pk_fma_f32 v[114:115], v[146:147], v[114:115], v[166:167]
	s_add_u32 s98, s10, 0x10000
	s_addc_u32 s99, s11, 0
	global_store_dwordx4 v203, v[112:115], s[98:99] offset:16
	s_add_u32 s42, s10, 0x30200
	s_addc_u32 s43, s11, 0
	global_load_dwordx4 v[164:167], v203, s[42:43]
	s_waitcnt vmcnt(14)
	v_pk_fma_f32 v[84:85], v[156:157], v[84:85], v[168:169]
	v_pk_fma_f32 v[86:87], v[158:159], v[86:87], v[170:171]
	s_add_u32 s98, s10, 0x10200
	s_addc_u32 s99, s11, 0
	global_store_dwordx4 v203, v[84:87], s[98:99]
	s_add_u32 s42, s10, 0x30200
	s_addc_u32 s43, s11, 0
	global_load_dwordx4 v[168:171], v203, s[42:43] offset:16
	s_waitcnt vmcnt(15)
	v_pk_fma_f32 v[80:81], v[152:153], v[80:81], v[172:173]
	v_pk_fma_f32 v[82:83], v[154:155], v[82:83], v[174:175]
	s_add_u32 s98, s10, 0x10200
	s_addc_u32 s99, s11, 0
	global_store_dwordx4 v203, v[80:83], s[98:99] offset:16
	s_add_u32 s42, s10, 0x80000
	s_addc_u32 s43, s11, 0
	global_load_dwordx4 v[172:175], v203, s[42:43]
	s_waitcnt vmcnt(16)
	v_pk_fma_f32 v[108:109], v[148:149], v[108:109], v[176:177]
	v_pk_fma_f32 v[110:111], v[150:151], v[110:111], v[178:179]
	s_add_u32 s98, s10, 0x20000
	s_addc_u32 s99, s11, 0
	global_store_dwordx4 v203, v[108:111], s[98:99]
	s_add_u32 s42, s10, 0x80000
	s_addc_u32 s43, s11, 0
	global_load_dwordx4 v[176:179], v203, s[42:43] offset:16
	s_waitcnt vmcnt(16)
	v_pk_fma_f32 v[104:105], v[144:145], v[104:105], v[180:181]
	v_pk_fma_f32 v[106:107], v[146:147], v[106:107], v[182:183]
	s_add_u32 s98, s10, 0x20000
	s_addc_u32 s99, s11, 0
	global_store_dwordx4 v203, v[104:107], s[98:99] offset:16
	s_add_u32 s42, s10, 0x80200
	s_addc_u32 s43, s11, 0
	global_load_dwordx4 v[180:183], v203, s[42:43]
	s_waitcnt vmcnt(16)
	v_pk_fma_f32 v[76:77], v[156:157], v[76:77], v[206:207]
	v_pk_fma_f32 v[78:79], v[158:159], v[78:79], v[208:209]
	s_add_u32 s98, s10, 0x20200
	s_addc_u32 s99, s11, 0
	global_store_dwordx4 v203, v[76:79], s[98:99]
	s_add_u32 s42, s10, 0x80200
	s_addc_u32 s43, s11, 0
	global_load_dwordx4 v[206:209], v203, s[42:43] offset:16
	s_waitcnt vmcnt(16)
	v_pk_fma_f32 v[72:73], v[152:153], v[72:73], v[210:211]
	v_pk_fma_f32 v[74:75], v[154:155], v[74:75], v[212:213]
	s_add_u32 s98, s10, 0x20200
	s_addc_u32 s99, s11, 0
	global_store_dwordx4 v203, v[72:75], s[98:99] offset:16
	s_add_u32 s42, s10, 0x90000
	s_addc_u32 s43, s11, 0
	global_load_dwordx4 v[210:213], v203, s[42:43]
	s_waitcnt vmcnt(16)
	v_pk_fma_f32 v[100:101], v[148:149], v[100:101], v[236:237]
	v_pk_fma_f32 v[102:103], v[150:151], v[102:103], v[238:239]
	s_add_u32 s98, s10, 0x30000
	s_addc_u32 s99, s11, 0
	global_store_dwordx4 v203, v[100:103], s[98:99]
	s_add_u32 s42, s10, 0x90000
	s_addc_u32 s43, s11, 0
	global_load_dwordx4 v[236:239], v203, s[42:43] offset:16
	s_waitcnt vmcnt(16)
	v_pk_fma_f32 v[96:97], v[144:145], v[96:97], v[160:161]
	v_pk_fma_f32 v[98:99], v[146:147], v[98:99], v[162:163]
	s_add_u32 s98, s10, 0x30000
	s_addc_u32 s99, s11, 0
	global_store_dwordx4 v203, v[96:99], s[98:99] offset:16
	s_add_u32 s42, s10, 0x90200
	s_addc_u32 s43, s11, 0
	global_load_dwordx4 v[160:163], v203, s[42:43]
	s_waitcnt vmcnt(16)
	v_pk_fma_f32 v[68:69], v[156:157], v[68:69], v[164:165]
	v_pk_fma_f32 v[70:71], v[158:159], v[70:71], v[166:167]
	s_add_u32 s98, s10, 0x30200
	s_addc_u32 s99, s11, 0
	global_store_dwordx4 v203, v[68:71], s[98:99]
	s_add_u32 s42, s10, 0x90200
	s_addc_u32 s43, s11, 0
	global_load_dwordx4 v[164:167], v203, s[42:43] offset:16
	s_waitcnt vmcnt(16)
	v_pk_fma_f32 v[64:65], v[152:153], v[64:65], v[168:169]
	v_pk_fma_f32 v[66:67], v[154:155], v[66:67], v[170:171]
	s_add_u32 s98, s10, 0x30200
	s_addc_u32 s99, s11, 0
	global_store_dwordx4 v203, v[64:67], s[98:99] offset:16
	s_add_u32 s42, s10, 0xa0000
	s_addc_u32 s43, s11, 0
	global_load_dwordx4 v[168:171], v203, s[42:43]
	s_waitcnt vmcnt(16)
	v_pk_fma_f32 v[60:61], v[148:149], v[60:61], v[172:173]
	v_pk_fma_f32 v[62:63], v[150:151], v[62:63], v[174:175]
	s_add_u32 s98, s10, 0x80000
	s_addc_u32 s99, s11, 0
	global_store_dwordx4 v203, v[60:63], s[98:99]
	s_add_u32 s42, s10, 0xa0000
	s_addc_u32 s43, s11, 0
	global_load_dwordx4 v[172:175], v203, s[42:43] offset:16
	s_waitcnt vmcnt(16)
	v_pk_fma_f32 v[56:57], v[144:145], v[56:57], v[176:177]
	v_pk_fma_f32 v[58:59], v[146:147], v[58:59], v[178:179]
	s_add_u32 s98, s10, 0x80000
	s_addc_u32 s99, s11, 0
	global_store_dwordx4 v203, v[56:59], s[98:99] offset:16
	s_add_u32 s42, s10, 0xa0200
	s_addc_u32 s43, s11, 0
	global_load_dwordx4 v[176:179], v203, s[42:43]
	s_waitcnt vmcnt(16)
	v_pk_fma_f32 v[28:29], v[156:157], v[28:29], v[180:181]
	v_pk_fma_f32 v[30:31], v[158:159], v[30:31], v[182:183]
	s_add_u32 s98, s10, 0x80200
	s_addc_u32 s99, s11, 0
	global_store_dwordx4 v203, v[28:31], s[98:99]
	s_add_u32 s42, s10, 0xa0200
	s_addc_u32 s43, s11, 0
	global_load_dwordx4 v[180:183], v203, s[42:43] offset:16
	s_waitcnt vmcnt(16)
	v_pk_fma_f32 v[24:25], v[152:153], v[24:25], v[206:207]
	v_pk_fma_f32 v[26:27], v[154:155], v[26:27], v[208:209]
	s_add_u32 s98, s10, 0x80200
	s_addc_u32 s99, s11, 0
	global_store_dwordx4 v203, v[24:27], s[98:99] offset:16
	s_waitcnt vmcnt(15)
	v_pk_fma_f32 v[52:53], v[148:149], v[52:53], v[210:211]
	v_pk_fma_f32 v[54:55], v[150:151], v[54:55], v[212:213]
	s_add_u32 s42, s10, 0x90000
	s_addc_u32 s43, s11, 0
	global_store_dwordx4 v203, v[52:55], s[42:43]
	s_waitcnt vmcnt(14)
	v_pk_fma_f32 v[48:49], v[144:145], v[48:49], v[236:237]
	v_pk_fma_f32 v[50:51], v[146:147], v[50:51], v[238:239]
	s_add_u32 s98, s10, 0x90000
	s_addc_u32 s99, s11, 0
	global_store_dwordx4 v203, v[48:51], s[98:99] offset:16
	s_waitcnt vmcnt(13)
	v_pk_fma_f32 v[20:21], v[156:157], v[20:21], v[160:161]
	v_pk_fma_f32 v[22:23], v[158:159], v[22:23], v[162:163]
	s_add_u32 s42, s10, 0x90200
	s_addc_u32 s43, s11, 0
	global_store_dwordx4 v203, v[20:23], s[42:43]
	s_waitcnt vmcnt(12)
	v_pk_fma_f32 v[16:17], v[152:153], v[16:17], v[164:165]
	v_pk_fma_f32 v[18:19], v[154:155], v[18:19], v[166:167]
	s_add_u32 s98, s10, 0x90200
	s_addc_u32 s99, s11, 0
	global_store_dwordx4 v203, v[16:19], s[98:99] offset:16
	s_waitcnt vmcnt(11)
	v_pk_fma_f32 v[44:45], v[148:149], v[44:45], v[168:169]
	v_pk_fma_f32 v[46:47], v[150:151], v[46:47], v[170:171]
	s_add_u32 s42, s10, 0xa0000
	s_addc_u32 s43, s11, 0
	global_store_dwordx4 v203, v[44:47], s[42:43]
	s_waitcnt vmcnt(10)
	v_pk_fma_f32 v[40:41], v[144:145], v[40:41], v[172:173]
	v_pk_fma_f32 v[42:43], v[146:147], v[42:43], v[174:175]
	s_add_u32 s98, s10, 0xa0000
	s_addc_u32 s99, s11, 0
	global_store_dwordx4 v203, v[40:43], s[98:99] offset:16
	s_waitcnt vmcnt(9)
	v_pk_fma_f32 v[12:13], v[156:157], v[12:13], v[176:177]
	v_pk_fma_f32 v[14:15], v[158:159], v[14:15], v[178:179]
	s_add_u32 s42, s10, 0xa0200
	s_addc_u32 s43, s11, 0
	global_store_dwordx4 v203, v[12:15], s[42:43]
	s_waitcnt vmcnt(8)
	v_pk_fma_f32 v[8:9], v[152:153], v[8:9], v[180:181]
	v_pk_fma_f32 v[10:11], v[154:155], v[10:11], v[182:183]
	s_add_u32 s98, s10, 0xa0200
	s_addc_u32 s99, s11, 0
	global_store_dwordx4 v203, v[8:11], s[98:99] offset:16
	s_branch .Lfq_predone
.Lfq_np1:
	s_add_u32 s42, s62, 0x0
	s_addc_u32 s43, s63, 0
	global_load_dwordx4 v[160:163], v205, s[42:43] sc0 sc1
	s_add_u32 s98, s62, 0x1000
	s_addc_u32 s99, s63, 0
	global_load_dwordx4 v[164:167], v205, s[98:99] sc0 sc1
	s_add_u32 s42, s62, 0x400
	s_addc_u32 s43, s63, 0
	global_load_dwordx4 v[168:171], v205, s[42:43] sc0 sc1
	s_add_u32 s98, s62, 0x1400
	s_addc_u32 s99, s63, 0
	global_load_dwordx4 v[172:175], v205, s[98:99] sc0 sc1
	s_add_u32 s42, s62, 0x800
	s_addc_u32 s43, s63, 0
	global_load_dwordx4 v[176:179], v205, s[42:43] sc0 sc1
	s_add_u32 s98, s62, 0x1800
	s_addc_u32 s99, s63, 0
	global_load_dwordx4 v[180:183], v205, s[98:99] sc0 sc1
	s_add_u32 s42, s62, 0xc00
	s_addc_u32 s43, s63, 0
	global_load_dwordx4 v[206:209], v205, s[42:43] sc0 sc1
	s_add_u32 s98, s62, 0x1c00
	s_addc_u32 s99, s63, 0
	global_load_dwordx4 v[210:213], v205, s[98:99] sc0 sc1
	s_add_u32 s42, s62, 0x2000
	s_addc_u32 s43, s63, 0
	global_load_dwordx4 v[236:239], v205, s[42:43] sc0 sc1
	s_waitcnt vmcnt(8)
	v_lshlrev_b32_e32 v240, 16, v160
	v_and_b32_e32 v241, 0xffff0000, v160
	v_pk_add_f32 v[124:125], v[124:125], v[240:241]
	v_lshlrev_b32_e32 v240, 16, v161
	v_and_b32_e32 v241, 0xffff0000, v161
	v_pk_add_f32 v[126:127], v[126:127], v[240:241]
	v_lshlrev_b32_e32 v240, 16, v162
	v_and_b32_e32 v241, 0xffff0000, v162
	v_pk_add_f32 v[120:121], v[120:121], v[240:241]
	v_lshlrev_b32_e32 v240, 16, v163
	v_and_b32_e32 v241, 0xffff0000, v163
	v_pk_add_f32 v[122:123], v[122:123], v[240:241]
	s_add_u32 s98, s62, 0x3000
	s_addc_u32 s99, s63, 0
	global_load_dwordx4 v[160:163], v205, s[98:99] sc0 sc1
	s_waitcnt vmcnt(8)
	v_lshlrev_b32_e32 v240, 16, v164
	v_and_b32_e32 v241, 0xffff0000, v164
	v_pk_add_f32 v[92:93], v[92:93], v[240:241]
	v_lshlrev_b32_e32 v240, 16, v165
	v_and_b32_e32 v241, 0xffff0000, v165
	v_pk_add_f32 v[94:95], v[94:95], v[240:241]
	v_lshlrev_b32_e32 v240, 16, v166
	v_and_b32_e32 v241, 0xffff0000, v166
	v_pk_add_f32 v[88:89], v[88:89], v[240:241]
	v_lshlrev_b32_e32 v240, 16, v167
	v_and_b32_e32 v241, 0xffff0000, v167
	v_pk_add_f32 v[90:91], v[90:91], v[240:241]
	s_add_u32 s42, s62, 0x2400
	s_addc_u32 s43, s63, 0
	global_load_dwordx4 v[164:167], v205, s[42:43] sc0 sc1
	s_waitcnt vmcnt(8)
	v_lshlrev_b32_e32 v240, 16, v168
	v_and_b32_e32 v241, 0xffff0000, v168
	v_pk_add_f32 v[116:117], v[116:117], v[240:241]
	v_lshlrev_b32_e32 v240, 16, v169
	v_and_b32_e32 v241, 0xffff0000, v169
	v_pk_add_f32 v[118:119], v[118:119], v[240:241]
	v_lshlrev_b32_e32 v240, 16, v170
	v_and_b32_e32 v241, 0xffff0000, v170
	v_pk_add_f32 v[112:113], v[112:113], v[240:241]
	v_lshlrev_b32_e32 v240, 16, v171
	v_and_b32_e32 v241, 0xffff0000, v171
	v_pk_add_f32 v[114:115], v[114:115], v[240:241]
	s_add_u32 s98, s62, 0x3400
	s_addc_u32 s99, s63, 0
	global_load_dwordx4 v[168:171], v205, s[98:99] sc0 sc1
	s_waitcnt vmcnt(8)
	v_lshlrev_b32_e32 v240, 16, v172
	v_and_b32_e32 v241, 0xffff0000, v172
	v_pk_add_f32 v[84:85], v[84:85], v[240:241]
	v_lshlrev_b32_e32 v240, 16, v173
	v_and_b32_e32 v241, 0xffff0000, v173
	v_pk_add_f32 v[86:87], v[86:87], v[240:241]
	v_lshlrev_b32_e32 v240, 16, v174
	v_and_b32_e32 v241, 0xffff0000, v174
	v_pk_add_f32 v[80:81], v[80:81], v[240:241]
	v_lshlrev_b32_e32 v240, 16, v175
	v_and_b32_e32 v241, 0xffff0000, v175
	v_pk_add_f32 v[82:83], v[82:83], v[240:241]
	s_add_u32 s42, s62, 0x2800
	s_addc_u32 s43, s63, 0
	global_load_dwordx4 v[172:175], v205, s[42:43] sc0 sc1
	s_waitcnt vmcnt(8)
	v_lshlrev_b32_e32 v240, 16, v176
	v_and_b32_e32 v241, 0xffff0000, v176
	v_pk_add_f32 v[108:109], v[108:109], v[240:241]
	v_lshlrev_b32_e32 v240, 16, v177
	v_and_b32_e32 v241, 0xffff0000, v177
	v_pk_add_f32 v[110:111], v[110:111], v[240:241]
	v_lshlrev_b32_e32 v240, 16, v178
	v_and_b32_e32 v241, 0xffff0000, v178
	v_pk_add_f32 v[104:105], v[104:105], v[240:241]
	v_lshlrev_b32_e32 v240, 16, v179
	v_and_b32_e32 v241, 0xffff0000, v179
	v_pk_add_f32 v[106:107], v[106:107], v[240:241]
	s_add_u32 s98, s62, 0x3800
	s_addc_u32 s99, s63, 0
	global_load_dwordx4 v[176:179], v205, s[98:99] sc0 sc1
	s_waitcnt vmcnt(8)
	v_lshlrev_b32_e32 v240, 16, v180
	v_and_b32_e32 v241, 0xffff0000, v180
	v_pk_add_f32 v[76:77], v[76:77], v[240:241]
	v_lshlrev_b32_e32 v240, 16, v181
	v_and_b32_e32 v241, 0xffff0000, v181
	v_pk_add_f32 v[78:79], v[78:79], v[240:241]
	v_lshlrev_b32_e32 v240, 16, v182
	v_and_b32_e32 v241, 0xffff0000, v182
	v_pk_add_f32 v[72:73], v[72:73], v[240:241]
	v_lshlrev_b32_e32 v240, 16, v183
	v_and_b32_e32 v241, 0xffff0000, v183
	v_pk_add_f32 v[74:75], v[74:75], v[240:241]
	s_add_u32 s42, s62, 0x2c00
	s_addc_u32 s43, s63, 0
	global_load_dwordx4 v[180:183], v205, s[42:43] sc0 sc1
	s_waitcnt vmcnt(8)
	v_lshlrev_b32_e32 v240, 16, v206
	v_and_b32_e32 v241, 0xffff0000, v206
	v_pk_add_f32 v[100:101], v[100:101], v[240:241]
	v_lshlrev_b32_e32 v240, 16, v207
	v_and_b32_e32 v241, 0xffff0000, v207
	v_pk_add_f32 v[102:103], v[102:103], v[240:241]
	v_lshlrev_b32_e32 v240, 16, v208
	v_and_b32_e32 v241, 0xffff0000, v208
	v_pk_add_f32 v[96:97], v[96:97], v[240:241]
	v_lshlrev_b32_e32 v240, 16, v209
	v_and_b32_e32 v241, 0xffff0000, v209
	v_pk_add_f32 v[98:99], v[98:99], v[240:241]
	s_add_u32 s98, s62, 0x3c00
	s_addc_u32 s99, s63, 0
	global_load_dwordx4 v[206:209], v205, s[98:99] sc0 sc1
	s_waitcnt vmcnt(8)
	v_lshlrev_b32_e32 v240, 16, v210
	v_and_b32_e32 v241, 0xffff0000, v210
	v_pk_add_f32 v[68:69], v[68:69], v[240:241]
	v_lshlrev_b32_e32 v240, 16, v211
	v_and_b32_e32 v241, 0xffff0000, v211
	v_pk_add_f32 v[70:71], v[70:71], v[240:241]
	v_lshlrev_b32_e32 v240, 16, v212
	v_and_b32_e32 v241, 0xffff0000, v212
	v_pk_add_f32 v[64:65], v[64:65], v[240:241]
	v_lshlrev_b32_e32 v240, 16, v213
	v_and_b32_e32 v241, 0xffff0000, v213
	v_pk_add_f32 v[66:67], v[66:67], v[240:241]
	s_add_u32 s42, s10, 0x0
	s_addc_u32 s43, s11, 0
	global_load_dwordx4 v[210:213], v203, s[42:43]
	s_waitcnt vmcnt(8)
	v_lshlrev_b32_e32 v240, 16, v236
	v_and_b32_e32 v241, 0xffff0000, v236
	v_pk_add_f32 v[60:61], v[60:61], v[240:241]
	v_lshlrev_b32_e32 v240, 16, v237
	v_and_b32_e32 v241, 0xffff0000, v237
	v_pk_add_f32 v[62:63], v[62:63], v[240:241]
	v_lshlrev_b32_e32 v240, 16, v238
	v_and_b32_e32 v241, 0xffff0000, v238
	v_pk_add_f32 v[56:57], v[56:57], v[240:241]
	v_lshlrev_b32_e32 v240, 16, v239
	v_and_b32_e32 v241, 0xffff0000, v239
	v_pk_add_f32 v[58:59], v[58:59], v[240:241]
	s_add_u32 s98, s10, 0x0
	s_addc_u32 s99, s11, 0
	global_load_dwordx4 v[236:239], v203, s[98:99] offset:16
	s_waitcnt vmcnt(8)
	v_lshlrev_b32_e32 v240, 16, v160
	v_and_b32_e32 v241, 0xffff0000, v160
	v_pk_add_f32 v[28:29], v[28:29], v[240:241]
	v_lshlrev_b32_e32 v240, 16, v161
	v_and_b32_e32 v241, 0xffff0000, v161
	v_pk_add_f32 v[30:31], v[30:31], v[240:241]
	v_lshlrev_b32_e32 v240, 16, v162
	v_and_b32_e32 v241, 0xffff0000, v162
	v_pk_add_f32 v[24:25], v[24:25], v[240:241]
	v_lshlrev_b32_e32 v240, 16, v163
	v_and_b32_e32 v241, 0xffff0000, v163
	v_pk_add_f32 v[26:27], v[26:27], v[240:241]
	s_add_u32 s42, s10, 0x200
	s_addc_u32 s43, s11, 0
	global_load_dwordx4 v[160:163], v203, s[42:43]
	s_waitcnt vmcnt(8)
	v_lshlrev_b32_e32 v240, 16, v164
	v_and_b32_e32 v241, 0xffff0000, v164
	v_pk_add_f32 v[52:53], v[52:53], v[240:241]
	v_lshlrev_b32_e32 v240, 16, v165
	v_and_b32_e32 v241, 0xffff0000, v165
	v_pk_add_f32 v[54:55], v[54:55], v[240:241]
	v_lshlrev_b32_e32 v240, 16, v166
	v_and_b32_e32 v241, 0xffff0000, v166
	v_pk_add_f32 v[48:49], v[48:49], v[240:241]
	v_lshlrev_b32_e32 v240, 16, v167
	v_and_b32_e32 v241, 0xffff0000, v167
	v_pk_add_f32 v[50:51], v[50:51], v[240:241]
	s_add_u32 s98, s10, 0x200
	s_addc_u32 s99, s11, 0
	global_load_dwordx4 v[164:167], v203, s[98:99] offset:16
	s_waitcnt vmcnt(8)
	v_lshlrev_b32_e32 v240, 16, v168
	v_and_b32_e32 v241, 0xffff0000, v168
	v_pk_add_f32 v[20:21], v[20:21], v[240:241]
	v_lshlrev_b32_e32 v240, 16, v169
	v_and_b32_e32 v241, 0xffff0000, v169
	v_pk_add_f32 v[22:23], v[22:23], v[240:241]
	v_lshlrev_b32_e32 v240, 16, v170
	v_and_b32_e32 v241, 0xffff0000, v170
	v_pk_add_f32 v[16:17], v[16:17], v[240:241]
	v_lshlrev_b32_e32 v240, 16, v171
	v_and_b32_e32 v241, 0xffff0000, v171
	v_pk_add_f32 v[18:19], v[18:19], v[240:241]
	s_add_u32 s42, s10, 0x10000
	s_addc_u32 s43, s11, 0
	global_load_dwordx4 v[168:171], v203, s[42:43]
	s_waitcnt vmcnt(8)
	v_lshlrev_b32_e32 v240, 16, v172
	v_and_b32_e32 v241, 0xffff0000, v172
	v_pk_add_f32 v[44:45], v[44:45], v[240:241]
	v_lshlrev_b32_e32 v240, 16, v173
	v_and_b32_e32 v241, 0xffff0000, v173
	v_pk_add_f32 v[46:47], v[46:47], v[240:241]
	v_lshlrev_b32_e32 v240, 16, v174
	v_and_b32_e32 v241, 0xffff0000, v174
	v_pk_add_f32 v[40:41], v[40:41], v[240:241]
	v_lshlrev_b32_e32 v240, 16, v175
	v_and_b32_e32 v241, 0xffff0000, v175
	v_pk_add_f32 v[42:43], v[42:43], v[240:241]
	s_add_u32 s98, s10, 0x10000
	s_addc_u32 s99, s11, 0
	global_load_dwordx4 v[172:175], v203, s[98:99] offset:16
	s_waitcnt vmcnt(8)
	v_lshlrev_b32_e32 v240, 16, v176
	v_and_b32_e32 v241, 0xffff0000, v176
	v_pk_add_f32 v[12:13], v[12:13], v[240:241]
	v_lshlrev_b32_e32 v240, 16, v177
	v_and_b32_e32 v241, 0xffff0000, v177
	v_pk_add_f32 v[14:15], v[14:15], v[240:241]
	v_lshlrev_b32_e32 v240, 16, v178
	v_and_b32_e32 v241, 0xffff0000, v178
	v_pk_add_f32 v[8:9], v[8:9], v[240:241]
	v_lshlrev_b32_e32 v240, 16, v179
	v_and_b32_e32 v241, 0xffff0000, v179
	v_pk_add_f32 v[10:11], v[10:11], v[240:241]
	s_add_u32 s42, s10, 0x10200
	s_addc_u32 s43, s11, 0
	global_load_dwordx4 v[176:179], v203, s[42:43]
	s_waitcnt vmcnt(8)
	v_lshlrev_b32_e32 v240, 16, v180
	v_and_b32_e32 v241, 0xffff0000, v180
	v_pk_add_f32 v[36:37], v[36:37], v[240:241]
	v_lshlrev_b32_e32 v240, 16, v181
	v_and_b32_e32 v241, 0xffff0000, v181
	v_pk_add_f32 v[38:39], v[38:39], v[240:241]
	v_lshlrev_b32_e32 v240, 16, v182
	v_and_b32_e32 v241, 0xffff0000, v182
	v_pk_add_f32 v[32:33], v[32:33], v[240:241]
	v_lshlrev_b32_e32 v240, 16, v183
	v_and_b32_e32 v241, 0xffff0000, v183
	v_pk_add_f32 v[34:35], v[34:35], v[240:241]
	s_add_u32 s98, s10, 0x10200
	s_addc_u32 s99, s11, 0
	global_load_dwordx4 v[180:183], v203, s[98:99] offset:16
	s_waitcnt vmcnt(8)
	v_lshlrev_b32_e32 v240, 16, v206
	v_and_b32_e32 v241, 0xffff0000, v206
	v_pk_add_f32 v[4:5], v[4:5], v[240:241]
	v_lshlrev_b32_e32 v240, 16, v207
	v_and_b32_e32 v241, 0xffff0000, v207
	v_pk_add_f32 v[6:7], v[6:7], v[240:241]
	v_lshlrev_b32_e32 v240, 16, v208
	v_and_b32_e32 v241, 0xffff0000, v208
	v_pk_add_f32 v[0:1], v[0:1], v[240:241]
	v_lshlrev_b32_e32 v240, 16, v209
	v_and_b32_e32 v241, 0xffff0000, v209
	v_pk_add_f32 v[2:3], v[2:3], v[240:241]
	s_add_u32 s42, s10, 0x20000
	s_addc_u32 s43, s11, 0
	global_load_dwordx4 v[206:209], v203, s[42:43]
	s_waitcnt vmcnt(8)
	v_pk_fma_f32 v[124:125], v[148:149], v[124:125], v[210:211]
	v_pk_fma_f32 v[126:127], v[150:151], v[126:127], v[212:213]
	s_add_u32 s98, s10, 0x0
	s_addc_u32 s99, s11, 0
	global_store_dwordx4 v203, v[124:127], s[98:99]
	s_add_u32 s42, s10, 0x20000
	s_addc_u32 s43, s11, 0
	global_load_dwordx4 v[210:213], v203, s[42:43] offset:16
	s_waitcnt vmcnt(9)
	v_pk_fma_f32 v[120:121], v[144:145], v[120:121], v[236:237]
	v_pk_fma_f32 v[122:123], v[146:147], v[122:123], v[238:239]
	s_add_u32 s98, s10, 0x0
	s_addc_u32 s99, s11, 0
	global_store_dwordx4 v203, v[120:123], s[98:99] offset:16
	s_add_u32 s42, s10, 0x20200
	s_addc_u32 s43, s11, 0
	global_load_dwordx4 v[236:239], v203, s[42:43]
	s_waitcnt vmcnt(10)
	v_pk_fma_f32 v[92:93], v[156:157], v[92:93], v[160:161]
	v_pk_fma_f32 v[94:95], v[158:159], v[94:95], v[162:163]
	s_add_u32 s98, s10, 0x200
	s_addc_u32 s99, s11, 0
	global_store_dwordx4 v203, v[92:95], s[98:99]
	s_add_u32 s42, s10, 0x20200
	s_addc_u32 s43, s11, 0
	global_load_dwordx4 v[160:163], v203, s[42:43] offset:16
	s_waitcnt vmcnt(11)
	v_pk_fma_f32 v[88:89], v[152:153], v[88:89], v[164:165]
	v_pk_fma_f32 v[90:91], v[154:155], v[90:91], v[166:167]
	s_add_u32 s98, s10, 0x200
	s_addc_u32 s99, s11, 0
	global_store_dwordx4 v203, v[88:91], s[98:99] offset:16
	s_add_u32 s42, s10, 0x30000
	s_addc_u32 s43, s11, 0
	global_load_dwordx4 v[164:167], v203, s[42:43]
	s_waitcnt vmcnt(12)
	v_pk_fma_f32 v[116:117], v[148:149], v[116:117], v[168:169]
	v_pk_fma_f32 v[118:119], v[150:151], v[118:119], v[170:171]
	s_add_u32 s98, s10, 0x10000
	s_addc_u32 s99, s11, 0
	global_store_dwordx4 v203, v[116:119], s[98:99]
	s_add_u32 s42, s10, 0x30000
	s_addc_u32 s43, s11, 0
	global_load_dwordx4 v[168:171], v203, s[42:43] offset:16
	s_waitcnt vmcnt(13)
	v_pk_fma_f32 v[112:113], v[144:145], v[112:113], v[172:173]
	v_pk_fma_f32 v[114:115], v[146:147], v[114:115], v[174:175]
	s_add_u32 s98, s10, 0x10000
	s_addc_u32 s99, s11, 0
	global_store_dwordx4 v203, v[112:115], s[98:99] offset:16
	s_add_u32 s42, s10, 0x30200
	s_addc_u32 s43, s11, 0
	global_load_dwordx4 v[172:175], v203, s[42:43]
	s_waitcnt vmcnt(14)
	v_pk_fma_f32 v[84:85], v[156:157], v[84:85], v[176:177]
	v_pk_fma_f32 v[86:87], v[158:159], v[86:87], v[178:179]
	s_add_u32 s98, s10, 0x10200
	s_addc_u32 s99, s11, 0
	global_store_dwordx4 v203, v[84:87], s[98:99]
	s_add_u32 s42, s10, 0x30200
	s_addc_u32 s43, s11, 0
	global_load_dwordx4 v[176:179], v203, s[42:43] offset:16
	s_waitcnt vmcnt(15)
	v_pk_fma_f32 v[80:81], v[152:153], v[80:81], v[180:181]
	v_pk_fma_f32 v[82:83], v[154:155], v[82:83], v[182:183]
	s_add_u32 s98, s10, 0x10200
	s_addc_u32 s99, s11, 0
	global_store_dwordx4 v203, v[80:83], s[98:99] offset:16
	s_add_u32 s42, s10, 0x80000
	s_addc_u32 s43, s11, 0
	global_load_dwordx4 v[180:183], v203, s[42:43]
	s_waitcnt vmcnt(16)
	v_pk_fma_f32 v[108:109], v[148:149], v[108:109], v[206:207]
	v_pk_fma_f32 v[110:111], v[150:151], v[110:111], v[208:209]
	s_add_u32 s98, s10, 0x20000
	s_addc_u32 s99, s11, 0
	global_store_dwordx4 v203, v[108:111], s[98:99]
	s_add_u32 s42, s10, 0x80000
	s_addc_u32 s43, s11, 0
	global_load_dwordx4 v[206:209], v203, s[42:43] offset:16
	s_waitcnt vmcnt(16)
	v_pk_fma_f32 v[104:105], v[144:145], v[104:105], v[210:211]
	v_pk_fma_f32 v[106:107], v[146:147], v[106:107], v[212:213]
	s_add_u32 s98, s10, 0x20000
	s_addc_u32 s99, s11, 0
	global_store_dwordx4 v203, v[104:107], s[98:99] offset:16
	s_add_u32 s42, s10, 0x80200
	s_addc_u32 s43, s11, 0
	global_load_dwordx4 v[210:213], v203, s[42:43]
	s_waitcnt vmcnt(16)
	v_pk_fma_f32 v[76:77], v[156:157], v[76:77], v[236:237]
	v_pk_fma_f32 v[78:79], v[158:159], v[78:79], v[238:239]
	s_add_u32 s98, s10, 0x20200
	s_addc_u32 s99, s11, 0
	global_store_dwordx4 v203, v[76:79], s[98:99]
	s_add_u32 s42, s10, 0x80200
	s_addc_u32 s43, s11, 0
	global_load_dwordx4 v[236:239], v203, s[42:43] offset:16
	s_waitcnt vmcnt(16)
	v_pk_fma_f32 v[72:73], v[152:153], v[72:73], v[160:161]
	v_pk_fma_f32 v[74:75], v[154:155], v[74:75], v[162:163]
	s_add_u32 s98, s10, 0x20200
	s_addc_u32 s99, s11, 0
	global_store_dwordx4 v203, v[72:75], s[98:99] offset:16
	s_add_u32 s42, s10, 0x90000
	s_addc_u32 s43, s11, 0
	global_load_dwordx4 v[160:163], v203, s[42:43]
	s_waitcnt vmcnt(16)
	v_pk_fma_f32 v[100:101], v[148:149], v[100:101], v[164:165]
	v_pk_fma_f32 v[102:103], v[150:151], v[102:103], v[166:167]
	s_add_u32 s98, s10, 0x30000
	s_addc_u32 s99, s11, 0
	global_store_dwordx4 v203, v[100:103], s[98:99]
	s_add_u32 s42, s10, 0x90000
	s_addc_u32 s43, s11, 0
	global_load_dwordx4 v[164:167], v203, s[42:43] offset:16
	s_waitcnt vmcnt(16)
	v_pk_fma_f32 v[96:97], v[144:145], v[96:97], v[168:169]
	v_pk_fma_f32 v[98:99], v[146:147], v[98:99], v[170:171]
	s_add_u32 s98, s10, 0x30000
	s_addc_u32 s99, s11, 0
	global_store_dwordx4 v203, v[96:99], s[98:99] offset:16
	s_add_u32 s42, s10, 0x90200
	s_addc_u32 s43, s11, 0
	global_load_dwordx4 v[168:171], v203, s[42:43]
	s_waitcnt vmcnt(16)
	v_pk_fma_f32 v[68:69], v[156:157], v[68:69], v[172:173]
	v_pk_fma_f32 v[70:71], v[158:159], v[70:71], v[174:175]
	s_add_u32 s98, s10, 0x30200
	s_addc_u32 s99, s11, 0
	global_store_dwordx4 v203, v[68:71], s[98:99]
	s_add_u32 s42, s10, 0x90200
	s_addc_u32 s43, s11, 0
	global_load_dwordx4 v[172:175], v203, s[42:43] offset:16
	s_waitcnt vmcnt(16)
	v_pk_fma_f32 v[64:65], v[152:153], v[64:65], v[176:177]
	v_pk_fma_f32 v[66:67], v[154:155], v[66:67], v[178:179]
	s_add_u32 s98, s10, 0x30200
	s_addc_u32 s99, s11, 0
	global_store_dwordx4 v203, v[64:67], s[98:99] offset:16
	s_add_u32 s42, s10, 0xa0000
	s_addc_u32 s43, s11, 0
	global_load_dwordx4 v[176:179], v203, s[42:43]
	s_waitcnt vmcnt(16)
	v_pk_fma_f32 v[60:61], v[148:149], v[60:61], v[180:181]
	v_pk_fma_f32 v[62:63], v[150:151], v[62:63], v[182:183]
	s_add_u32 s98, s10, 0x80000
	s_addc_u32 s99, s11, 0
	global_store_dwordx4 v203, v[60:63], s[98:99]
	s_add_u32 s42, s10, 0xa0000
	s_addc_u32 s43, s11, 0
	global_load_dwordx4 v[180:183], v203, s[42:43] offset:16
	s_waitcnt vmcnt(16)
	v_pk_fma_f32 v[56:57], v[144:145], v[56:57], v[206:207]
	v_pk_fma_f32 v[58:59], v[146:147], v[58:59], v[208:209]
	s_add_u32 s98, s10, 0x80000
	s_addc_u32 s99, s11, 0
	global_store_dwordx4 v203, v[56:59], s[98:99] offset:16
	s_add_u32 s42, s10, 0xa0200
	s_addc_u32 s43, s11, 0
	global_load_dwordx4 v[206:209], v203, s[42:43]
	s_waitcnt vmcnt(16)
	v_pk_fma_f32 v[28:29], v[156:157], v[28:29], v[210:211]
	v_pk_fma_f32 v[30:31], v[158:159], v[30:31], v[212:213]
	s_add_u32 s98, s10, 0x80200
	s_addc_u32 s99, s11, 0
	global_store_dwordx4 v203, v[28:31], s[98:99]
	s_add_u32 s42, s10, 0xa0200
	s_addc_u32 s43, s11, 0
	global_load_dwordx4 v[210:213], v203, s[42:43] offset:16
	s_waitcnt vmcnt(16)
	v_pk_fma_f32 v[24:25], v[152:153], v[24:25], v[236:237]
	v_pk_fma_f32 v[26:27], v[154:155], v[26:27], v[238:239]
	s_add_u32 s98, s10, 0x80200
	s_addc_u32 s99, s11, 0
	global_store_dwordx4 v203, v[24:27], s[98:99] offset:16
	s_waitcnt vmcnt(15)
	v_pk_fma_f32 v[52:53], v[148:149], v[52:53], v[160:161]
	v_pk_fma_f32 v[54:55], v[150:151], v[54:55], v[162:163]
	s_add_u32 s42, s10, 0x90000
	s_addc_u32 s43, s11, 0
	global_store_dwordx4 v203, v[52:55], s[42:43]
	s_waitcnt vmcnt(14)
	v_pk_fma_f32 v[48:49], v[144:145], v[48:49], v[164:165]
	v_pk_fma_f32 v[50:51], v[146:147], v[50:51], v[166:167]
	s_add_u32 s98, s10, 0x90000
	s_addc_u32 s99, s11, 0
	global_store_dwordx4 v203, v[48:51], s[98:99] offset:16
	s_waitcnt vmcnt(13)
	v_pk_fma_f32 v[20:21], v[156:157], v[20:21], v[168:169]
	v_pk_fma_f32 v[22:23], v[158:159], v[22:23], v[170:171]
	s_add_u32 s42, s10, 0x90200
	s_addc_u32 s43, s11, 0
	global_store_dwordx4 v203, v[20:23], s[42:43]
	s_waitcnt vmcnt(12)
	v_pk_fma_f32 v[16:17], v[152:153], v[16:17], v[172:173]
	v_pk_fma_f32 v[18:19], v[154:155], v[18:19], v[174:175]
	s_add_u32 s98, s10, 0x90200
	s_addc_u32 s99, s11, 0
	global_store_dwordx4 v203, v[16:19], s[98:99] offset:16
	s_waitcnt vmcnt(11)
	v_pk_fma_f32 v[44:45], v[148:149], v[44:45], v[176:177]
	v_pk_fma_f32 v[46:47], v[150:151], v[46:47], v[178:179]
	s_add_u32 s42, s10, 0xa0000
	s_addc_u32 s43, s11, 0
	global_store_dwordx4 v203, v[44:47], s[42:43]
	s_waitcnt vmcnt(10)
	v_pk_fma_f32 v[40:41], v[144:145], v[40:41], v[180:181]
	v_pk_fma_f32 v[42:43], v[146:147], v[42:43], v[182:183]
	s_add_u32 s98, s10, 0xa0000
	s_addc_u32 s99, s11, 0
	global_store_dwordx4 v203, v[40:43], s[98:99] offset:16
	s_waitcnt vmcnt(9)
	v_pk_fma_f32 v[12:13], v[156:157], v[12:13], v[206:207]
	v_pk_fma_f32 v[14:15], v[158:159], v[14:15], v[208:209]
	s_add_u32 s42, s10, 0xa0200
	s_addc_u32 s43, s11, 0
	global_store_dwordx4 v203, v[12:15], s[42:43]
	s_waitcnt vmcnt(8)
	v_pk_fma_f32 v[8:9], v[152:153], v[8:9], v[210:211]
	v_pk_fma_f32 v[10:11], v[154:155], v[10:11], v[212:213]
	s_add_u32 s98, s10, 0xa0200
	s_addc_u32 s99, s11, 0
	global_store_dwordx4 v203, v[8:11], s[98:99] offset:16

.Lfq_LBB0_1572:
	s_or_b64 exec, exec, s[80:81]
	s_mov_b64 s[80:81], 0
	s_branch .LBB0_1573
.Lfq_LBB0_1582:
	global_load_dwordx4 v[136:139], v[160:161], off offset:16
	global_load_dwordx4 v[140:143], v[160:161], off
	global_load_dwordx4 v[156:159], v[152:153], off offset:512
	s_nop 0
	global_load_dwordx4 v[152:155], v[152:153], off offset:528
	s_and_b64 vcc, exec, s[80:81]
	s_cbranch_vccnz .Lfq_LBB0_1423

.Lfq_LBB0_1597:
	global_load_dwordx4 v[132:135], v[160:161], off offset:512
	global_load_dwordx4 v[128:131], v[160:161], off offset:528
	s_branch .Lfq_LBB0_1556
.Lfs_LBB0_1414:
	v_readlane_b32 s36, v243, 58
	v_readlane_b32 s37, v243, 59
	v_mov_b32_e32 v155, 0
	s_andn2_b64 vcc, exec, s[80:81]
	v_cndmask_b32_e64 v128, 0, 1, s[36:37]
	v_cmp_ne_u32_e64 s[80:81], 1, v128
	v_mov_b32_e32 v154, 0
	v_mov_b32_e32 v153, 0
	v_mov_b32_e32 v152, 0
	v_mov_b32_e32 v159, 0
	v_mov_b32_e32 v158, 0
	v_mov_b32_e32 v157, 0
	v_mov_b32_e32 v156, 0
	v_mov_b32_e32 v147, 0
	v_mov_b32_e32 v146, 0
	v_mov_b32_e32 v145, 0
	v_mov_b32_e32 v144, 0
	v_mov_b32_e32 v151, 0
	v_mov_b32_e32 v150, 0
	v_mov_b32_e32 v149, 0
	v_mov_b32_e32 v148, 0
	v_mov_b32_e32 v131, 0
	v_mov_b32_e32 v130, 0
	s_waitcnt lgkmcnt(0)
	v_mov_b32_e32 v129, 0
	v_mov_b32_e32 v128, 0
	v_mov_b32_e32 v135, 0
	v_mov_b32_e32 v134, 0
	v_mov_b32_e32 v133, 0
	v_mov_b32_e32 v132, 0
	v_mov_b32_e32 v139, 0
	v_mov_b32_e32 v138, 0
	v_mov_b32_e32 v137, 0
	v_mov_b32_e32 v136, 0
	v_mov_b32_e32 v143, 0
	v_mov_b32_e32 v142, 0
	v_mov_b32_e32 v141, 0
	v_mov_b32_e32 v140, 0
	s_cbranch_vccnz .Lfs_LBB0_1420
	s_ashr_i32 s35, s31, 3
	v_readlane_b32 s36, v243, 57
	s_add_i32 s36, s35, s36
	s_ashr_i32 s37, s36, 31
	s_mul_i32 s38, s36, 0xc000
	s_mul_hi_i32 s35, s36, 0xc000
	s_add_u32 s38, s14, s38
	s_addc_u32 s39, s15, s35
	v_lshlrev_b64 v[130:131], 2, v[200:201]
	v_lshl_add_u64 v[128:129], s[38:39], 0, v[130:131]
	global_load_dwordx4 v[144:147], v[128:129], off offset:16
	global_load_dwordx4 v[148:151], v[128:129], off
	v_lshl_add_u64 v[130:131], s[16:17], 0, v[130:131]
	s_lshl_b64 s[36:37], s[36:37], 12
	v_lshl_add_u64 v[160:161], v[130:131], 0, s[36:37]
	v_mov_b32_e32 v131, 0
	s_and_b64 vcc, exec, s[80:81]
	v_mov_b32_e32 v140, 0
	v_mov_b32_e32 v141, 0
	v_mov_b32_e32 v142, 0
	v_mov_b32_e32 v143, 0
	v_mov_b32_e32 v136, 0
	v_mov_b32_e32 v137, 0
	v_mov_b32_e32 v138, 0
	v_mov_b32_e32 v139, 0
	s_cbranch_vccnz .Lfs_LBB0_1417
	global_load_dwordx4 v[140:143], v[160:161], off
	global_load_dwordx4 v[136:139], v[160:161], off offset:16

.Lfs_LBB0_1420:
	s_lshl_b32 s31, s31, 8
	v_add_u32_e32 v202, s31, v224
	v_mov_b32_e32 v160, s92
	v_mov_b32_e32 v161, s93
	v_cmp_gt_i32_e32 vcc, s33, v202
	s_nop 1
	v_cndmask_b32_e32 v160, v160, v161, vcc
	v_cndmask_b32_e64 v161, 0, 1, s[84:85]
	v_cmp_ne_u32_e64 s[82:83], 1, v161
	v_add_u32_e32 v204, v202, v160
	v_lshlrev_b32_e32 v203, 12, v204
	v_lshl_add_u32 v203, v200, 2, v203
	v_lshlrev_b32_e32 v205, 2, v194
	v_add_u32_e32 v235, 0xffffc000, v204
	v_lshrrev_b32_e32 v235, 3, v235
	v_add_u32_e32 v235, 8, v235
	v_mul_u32_u24_e32 v235, 0xc000, v235
	v_lshl_add_u32 v235, v200, 2, v235
	s_cmp_eq_u32 s30, 1
	s_cbranch_scc1 .Lfs_np1
	s_cmp_eq_u32 s30, 2
	s_cbranch_scc1 .Lfs_np2
	s_add_u32 s42, s62, 0x0
	s_addc_u32 s43, s63, 0
	global_load_dwordx4 v[128:131], v205, s[42:43] sc0 sc1
	s_add_u32 s98, s62, 0x1000
	s_addc_u32 s99, s63, 0
	global_load_dwordx4 v[132:135], v205, s[98:99] sc0 sc1
	s_add_u32 s42, s62, 0x400
	s_addc_u32 s43, s63, 0
	global_load_dwordx4 v[136:139], v205, s[42:43] sc0 sc1
	s_add_u32 s98, s62, 0x1400
	s_addc_u32 s99, s63, 0
	global_load_dwordx4 v[140:143], v205, s[98:99] sc0 sc1
	s_add_u32 s42, s62, 0x800
	s_addc_u32 s43, s63, 0
	global_load_dwordx4 v[144:147], v205, s[42:43] sc0 sc1
	s_add_u32 s98, s62, 0x1800
	s_addc_u32 s99, s63, 0
	global_load_dwordx4 v[148:151], v205, s[98:99] sc0 sc1
	s_add_u32 s42, s62, 0xc00
	s_addc_u32 s43, s63, 0
	global_load_dwordx4 v[152:155], v205, s[42:43] sc0 sc1
	s_add_u32 s98, s62, 0x1c00
	s_addc_u32 s99, s63, 0
	global_load_dwordx4 v[156:159], v205, s[98:99] sc0 sc1
	s_add_u32 s42, s62, 0x2000
	s_addc_u32 s43, s63, 0
	global_load_dwordx4 v[160:163], v205, s[42:43] sc0 sc1
	s_add_u32 s98, s62, 0x3000
	s_addc_u32 s99, s63, 0
	global_load_dwordx4 v[164:167], v205, s[98:99] sc0 sc1
	s_add_u32 s42, s62, 0x2400
	s_addc_u32 s43, s63, 0
	global_load_dwordx4 v[168:171], v205, s[42:43] sc0 sc1
	s_add_u32 s98, s62, 0x3400
	s_addc_u32 s99, s63, 0
	global_load_dwordx4 v[172:175], v205, s[98:99] sc0 sc1
	s_add_u32 s42, s62, 0x2800
	s_addc_u32 s43, s63, 0
	global_load_dwordx4 v[176:179], v205, s[42:43] sc0 sc1
	s_add_u32 s98, s62, 0x3800
	s_addc_u32 s99, s63, 0
	global_load_dwordx4 v[180:183], v205, s[98:99] sc0 sc1
	s_add_u32 s42, s62, 0x2c00
	s_addc_u32 s43, s63, 0
	global_load_dwordx4 v[206:209], v205, s[42:43] sc0 sc1
	s_add_u32 s98, s62, 0x3c00
	s_addc_u32 s99, s63, 0
	global_load_dwordx4 v[210:213], v205, s[98:99] sc0 sc1
	s_add_u32 s42, s62, 0x20000
	s_addc_u32 s43, s63, 0
	global_load_dwordx4 v[236:239], v205, s[42:43] sc0 sc1
	s_waitcnt vmcnt(16)
	v_lshlrev_b32_e32 v240, 16, v128
	v_and_b32_e32 v241, 0xffff0000, v128
	v_pk_add_f32 v[124:125], v[124:125], v[240:241]
	v_lshlrev_b32_e32 v240, 16, v129
	v_and_b32_e32 v241, 0xffff0000, v129
	v_pk_add_f32 v[126:127], v[126:127], v[240:241]
	v_lshlrev_b32_e32 v240, 16, v130
	v_and_b32_e32 v241, 0xffff0000, v130
	v_pk_add_f32 v[120:121], v[120:121], v[240:241]
	v_lshlrev_b32_e32 v240, 16, v131
	v_and_b32_e32 v241, 0xffff0000, v131
	v_pk_add_f32 v[122:123], v[122:123], v[240:241]
	s_add_u32 s98, s62, 0x21000
	s_addc_u32 s99, s63, 0
	global_load_dwordx4 v[128:131], v205, s[98:99] sc0 sc1
	s_waitcnt vmcnt(16)
	v_lshlrev_b32_e32 v240, 16, v132
	v_and_b32_e32 v241, 0xffff0000, v132
	v_pk_add_f32 v[92:93], v[92:93], v[240:241]
	v_lshlrev_b32_e32 v240, 16, v133
	v_and_b32_e32 v241, 0xffff0000, v133
	v_pk_add_f32 v[94:95], v[94:95], v[240:241]
	v_lshlrev_b32_e32 v240, 16, v134
	v_and_b32_e32 v241, 0xffff0000, v134
	v_pk_add_f32 v[88:89], v[88:89], v[240:241]
	v_lshlrev_b32_e32 v240, 16, v135
	v_and_b32_e32 v241, 0xffff0000, v135
	v_pk_add_f32 v[90:91], v[90:91], v[240:241]
	s_add_u32 s42, s62, 0x20400
	s_addc_u32 s43, s63, 0
	global_load_dwordx4 v[132:135], v205, s[42:43] sc0 sc1
	s_waitcnt vmcnt(16)
	v_lshlrev_b32_e32 v240, 16, v136
	v_and_b32_e32 v241, 0xffff0000, v136
	v_pk_add_f32 v[116:117], v[116:117], v[240:241]
	v_lshlrev_b32_e32 v240, 16, v137
	v_and_b32_e32 v241, 0xffff0000, v137
	v_pk_add_f32 v[118:119], v[118:119], v[240:241]
	v_lshlrev_b32_e32 v240, 16, v138
	v_and_b32_e32 v241, 0xffff0000, v138
	v_pk_add_f32 v[112:113], v[112:113], v[240:241]
	v_lshlrev_b32_e32 v240, 16, v139
	v_and_b32_e32 v241, 0xffff0000, v139
	v_pk_add_f32 v[114:115], v[114:115], v[240:241]
	s_add_u32 s98, s62, 0x21400
	s_addc_u32 s99, s63, 0
	global_load_dwordx4 v[136:139], v205, s[98:99] sc0 sc1
	s_waitcnt vmcnt(16)
	v_lshlrev_b32_e32 v240, 16, v140
	v_and_b32_e32 v241, 0xffff0000, v140
	v_pk_add_f32 v[84:85], v[84:85], v[240:241]
	v_lshlrev_b32_e32 v240, 16, v141
	v_and_b32_e32 v241, 0xffff0000, v141
	v_pk_add_f32 v[86:87], v[86:87], v[240:241]
	v_lshlrev_b32_e32 v240, 16, v142
	v_and_b32_e32 v241, 0xffff0000, v142
	v_pk_add_f32 v[80:81], v[80:81], v[240:241]
	v_lshlrev_b32_e32 v240, 16, v143
	v_and_b32_e32 v241, 0xffff0000, v143
	v_pk_add_f32 v[82:83], v[82:83], v[240:241]
	s_add_u32 s42, s62, 0x20800
	s_addc_u32 s43, s63, 0
	global_load_dwordx4 v[140:143], v205, s[42:43] sc0 sc1
	s_waitcnt vmcnt(16)
	v_lshlrev_b32_e32 v240, 16, v144
	v_and_b32_e32 v241, 0xffff0000, v144
	v_pk_add_f32 v[108:109], v[108:109], v[240:241]
	v_lshlrev_b32_e32 v240, 16, v145
	v_and_b32_e32 v241, 0xffff0000, v145
	v_pk_add_f32 v[110:111], v[110:111], v[240:241]
	v_lshlrev_b32_e32 v240, 16, v146
	v_and_b32_e32 v241, 0xffff0000, v146
	v_pk_add_f32 v[104:105], v[104:105], v[240:241]
	v_lshlrev_b32_e32 v240, 16, v147
	v_and_b32_e32 v241, 0xffff0000, v147
	v_pk_add_f32 v[106:107], v[106:107], v[240:241]
	s_add_u32 s98, s62, 0x21800
	s_addc_u32 s99, s63, 0
	global_load_dwordx4 v[144:147], v205, s[98:99] sc0 sc1
	s_waitcnt vmcnt(16)
	v_lshlrev_b32_e32 v240, 16, v148
	v_and_b32_e32 v241, 0xffff0000, v148
	v_pk_add_f32 v[76:77], v[76:77], v[240:241]
	v_lshlrev_b32_e32 v240, 16, v149
	v_and_b32_e32 v241, 0xffff0000, v149
	v_pk_add_f32 v[78:79], v[78:79], v[240:241]
	v_lshlrev_b32_e32 v240, 16, v150
	v_and_b32_e32 v241, 0xffff0000, v150
	v_pk_add_f32 v[72:73], v[72:73], v[240:241]
	v_lshlrev_b32_e32 v240, 16, v151
	v_and_b32_e32 v241, 0xffff0000, v151
	v_pk_add_f32 v[74:75], v[74:75], v[240:241]
	s_add_u32 s42, s62, 0x20c00
	s_addc_u32 s43, s63, 0
	global_load_dwordx4 v[148:151], v205, s[42:43] sc0 sc1
	s_waitcnt vmcnt(16)
	v_lshlrev_b32_e32 v240, 16, v152
	v_and_b32_e32 v241, 0xffff0000, v152
	v_pk_add_f32 v[100:101], v[100:101], v[240:241]
	v_lshlrev_b32_e32 v240, 16, v153
	v_and_b32_e32 v241, 0xffff0000, v153
	v_pk_add_f32 v[102:103], v[102:103], v[240:241]
	v_lshlrev_b32_e32 v240, 16, v154
	v_and_b32_e32 v241, 0xffff0000, v154
	v_pk_add_f32 v[96:97], v[96:97], v[240:241]
	v_lshlrev_b32_e32 v240, 16, v155
	v_and_b32_e32 v241, 0xffff0000, v155
	v_pk_add_f32 v[98:99], v[98:99], v[240:241]
	s_add_u32 s98, s62, 0x21c00
	s_addc_u32 s99, s63, 0
	global_load_dwordx4 v[152:155], v205, s[98:99] sc0 sc1
	s_waitcnt vmcnt(16)
	v_lshlrev_b32_e32 v240, 16, v156
	v_and_b32_e32 v241, 0xffff0000, v156
	v_pk_add_f32 v[68:69], v[68:69], v[240:241]
	v_lshlrev_b32_e32 v240, 16, v157
	v_and_b32_e32 v241, 0xffff0000, v157
	v_pk_add_f32 v[70:71], v[70:71], v[240:241]
	v_lshlrev_b32_e32 v240, 16, v158
	v_and_b32_e32 v241, 0xffff0000, v158
	v_pk_add_f32 v[64:65], v[64:65], v[240:241]
	v_lshlrev_b32_e32 v240, 16, v159
	v_and_b32_e32 v241, 0xffff0000, v159
	v_pk_add_f32 v[66:67], v[66:67], v[240:241]
	s_add_u32 s42, s62, 0x22000
	s_addc_u32 s43, s63, 0
	global_load_dwordx4 v[156:159], v205, s[42:43] sc0 sc1
	s_waitcnt vmcnt(16)
	v_lshlrev_b32_e32 v240, 16, v160
	v_and_b32_e32 v241, 0xffff0000, v160
	v_pk_add_f32 v[60:61], v[60:61], v[240:241]
	v_lshlrev_b32_e32 v240, 16, v161
	v_and_b32_e32 v241, 0xffff0000, v161
	v_pk_add_f32 v[62:63], v[62:63], v[240:241]
	v_lshlrev_b32_e32 v240, 16, v162
	v_and_b32_e32 v241, 0xffff0000, v162
	v_pk_add_f32 v[56:57], v[56:57], v[240:241]
	v_lshlrev_b32_e32 v240, 16, v163
	v_and_b32_e32 v241, 0xffff0000, v163
	v_pk_add_f32 v[58:59], v[58:59], v[240:241]
	s_add_u32 s98, s62, 0x23000
	s_addc_u32 s99, s63, 0
	global_load_dwordx4 v[160:163], v205, s[98:99] sc0 sc1
	s_waitcnt vmcnt(16)
	v_lshlrev_b32_e32 v240, 16, v164
	v_and_b32_e32 v241, 0xffff0000, v164
	v_pk_add_f32 v[28:29], v[28:29], v[240:241]
	v_lshlrev_b32_e32 v240, 16, v165
	v_and_b32_e32 v241, 0xffff0000, v165
	v_pk_add_f32 v[30:31], v[30:31], v[240:241]
	v_lshlrev_b32_e32 v240, 16, v166
	v_and_b32_e32 v241, 0xffff0000, v166
	v_pk_add_f32 v[24:25], v[24:25], v[240:241]
	v_lshlrev_b32_e32 v240, 16, v167
	v_and_b32_e32 v241, 0xffff0000, v167
	v_pk_add_f32 v[26:27], v[26:27], v[240:241]
	s_add_u32 s42, s62, 0x22400
	s_addc_u32 s43, s63, 0
	global_load_dwordx4 v[164:167], v205, s[42:43] sc0 sc1
	s_waitcnt vmcnt(16)
	v_lshlrev_b32_e32 v240, 16, v168
	v_and_b32_e32 v241, 0xffff0000, v168
	v_pk_add_f32 v[52:53], v[52:53], v[240:241]
	v_lshlrev_b32_e32 v240, 16, v169
	v_and_b32_e32 v241, 0xffff0000, v169
	v_pk_add_f32 v[54:55], v[54:55], v[240:241]
	v_lshlrev_b32_e32 v240, 16, v170
	v_and_b32_e32 v241, 0xffff0000, v170
	v_pk_add_f32 v[48:49], v[48:49], v[240:241]
	v_lshlrev_b32_e32 v240, 16, v171
	v_and_b32_e32 v241, 0xffff0000, v171
	v_pk_add_f32 v[50:51], v[50:51], v[240:241]
	s_add_u32 s98, s62, 0x23400
	s_addc_u32 s99, s63, 0
	global_load_dwordx4 v[168:171], v205, s[98:99] sc0 sc1
	s_waitcnt vmcnt(16)
	v_lshlrev_b32_e32 v240, 16, v172
	v_and_b32_e32 v241, 0xffff0000, v172
	v_pk_add_f32 v[20:21], v[20:21], v[240:241]
	v_lshlrev_b32_e32 v240, 16, v173
	v_and_b32_e32 v241, 0xffff0000, v173
	v_pk_add_f32 v[22:23], v[22:23], v[240:241]
	v_lshlrev_b32_e32 v240, 16, v174
	v_and_b32_e32 v241, 0xffff0000, v174
	v_pk_add_f32 v[16:17], v[16:17], v[240:241]
	v_lshlrev_b32_e32 v240, 16, v175
	v_and_b32_e32 v241, 0xffff0000, v175
	v_pk_add_f32 v[18:19], v[18:19], v[240:241]
	s_add_u32 s42, s62, 0x22800
	s_addc_u32 s43, s63, 0
	global_load_dwordx4 v[172:175], v205, s[42:43] sc0 sc1
	s_waitcnt vmcnt(16)
	v_lshlrev_b32_e32 v240, 16, v176
	v_and_b32_e32 v241, 0xffff0000, v176
	v_pk_add_f32 v[44:45], v[44:45], v[240:241]
	v_lshlrev_b32_e32 v240, 16, v177
	v_and_b32_e32 v241, 0xffff0000, v177
	v_pk_add_f32 v[46:47], v[46:47], v[240:241]
	v_lshlrev_b32_e32 v240, 16, v178
	v_and_b32_e32 v241, 0xffff0000, v178
	v_pk_add_f32 v[40:41], v[40:41], v[240:241]
	v_lshlrev_b32_e32 v240, 16, v179
	v_and_b32_e32 v241, 0xffff0000, v179
	v_pk_add_f32 v[42:43], v[42:43], v[240:241]
	s_add_u32 s98, s62, 0x23800
	s_addc_u32 s99, s63, 0
	global_load_dwordx4 v[176:179], v205, s[98:99] sc0 sc1
	s_waitcnt vmcnt(16)
	v_lshlrev_b32_e32 v240, 16, v180
	v_and_b32_e32 v241, 0xffff0000, v180
	v_pk_add_f32 v[12:13], v[12:13], v[240:241]
	v_lshlrev_b32_e32 v240, 16, v181
	v_and_b32_e32 v241, 0xffff0000, v181
	v_pk_add_f32 v[14:15], v[14:15], v[240:241]
	v_lshlrev_b32_e32 v240, 16, v182
	v_and_b32_e32 v241, 0xffff0000, v182
	v_pk_add_f32 v[8:9], v[8:9], v[240:241]
	v_lshlrev_b32_e32 v240, 16, v183
	v_and_b32_e32 v241, 0xffff0000, v183
	v_pk_add_f32 v[10:11], v[10:11], v[240:241]
	s_add_u32 s42, s62, 0x22c00
	s_addc_u32 s43, s63, 0
	global_load_dwordx4 v[180:183], v205, s[42:43] sc0 sc1
	s_waitcnt vmcnt(16)
	v_lshlrev_b32_e32 v240, 16, v206
	v_and_b32_e32 v241, 0xffff0000, v206
	v_pk_add_f32 v[36:37], v[36:37], v[240:241]
	v_lshlrev_b32_e32 v240, 16, v207
	v_and_b32_e32 v241, 0xffff0000, v207
	v_pk_add_f32 v[38:39], v[38:39], v[240:241]
	v_lshlrev_b32_e32 v240, 16, v208
	v_and_b32_e32 v241, 0xffff0000, v208
	v_pk_add_f32 v[32:33], v[32:33], v[240:241]
	v_lshlrev_b32_e32 v240, 16, v209
	v_and_b32_e32 v241, 0xffff0000, v209
	v_pk_add_f32 v[34:35], v[34:35], v[240:241]
	s_add_u32 s98, s62, 0x23c00
	s_addc_u32 s99, s63, 0
	global_load_dwordx4 v[206:209], v205, s[98:99] sc0 sc1
	s_waitcnt vmcnt(16)
	v_lshlrev_b32_e32 v240, 16, v210
	v_and_b32_e32 v241, 0xffff0000, v210
	v_pk_add_f32 v[4:5], v[4:5], v[240:241]
	v_lshlrev_b32_e32 v240, 16, v211
	v_and_b32_e32 v241, 0xffff0000, v211
	v_pk_add_f32 v[6:7], v[6:7], v[240:241]
	v_lshlrev_b32_e32 v240, 16, v212
	v_and_b32_e32 v241, 0xffff0000, v212
	v_pk_add_f32 v[0:1], v[0:1], v[240:241]
	v_lshlrev_b32_e32 v240, 16, v213
	v_and_b32_e32 v241, 0xffff0000, v213
	v_pk_add_f32 v[2:3], v[2:3], v[240:241]
	s_add_u32 s42, s62, 0x40000
	s_addc_u32 s43, s63, 0
	global_load_dwordx4 v[210:213], v205, s[42:43] sc0 sc1
	s_waitcnt vmcnt(16)
	v_lshlrev_b32_e32 v240, 16, v236
	v_and_b32_e32 v241, 0xffff0000, v236
	v_pk_add_f32 v[124:125], v[124:125], v[240:241]
	v_lshlrev_b32_e32 v240, 16, v237
	v_and_b32_e32 v241, 0xffff0000, v237
	v_pk_add_f32 v[126:127], v[126:127], v[240:241]
	v_lshlrev_b32_e32 v240, 16, v238
	v_and_b32_e32 v241, 0xffff0000, v238
	v_pk_add_f32 v[120:121], v[120:121], v[240:241]
	v_lshlrev_b32_e32 v240, 16, v239
	v_and_b32_e32 v241, 0xffff0000, v239
	v_pk_add_f32 v[122:123], v[122:123], v[240:241]
	s_add_u32 s98, s62, 0x41000
	s_addc_u32 s99, s63, 0
	global_load_dwordx4 v[236:239], v205, s[98:99] sc0 sc1
	s_waitcnt vmcnt(16)
	v_lshlrev_b32_e32 v240, 16, v128
	v_and_b32_e32 v241, 0xffff0000, v128
	v_pk_add_f32 v[92:93], v[92:93], v[240:241]
	v_lshlrev_b32_e32 v240, 16, v129
	v_and_b32_e32 v241, 0xffff0000, v129
	v_pk_add_f32 v[94:95], v[94:95], v[240:241]
	v_lshlrev_b32_e32 v240, 16, v130
	v_and_b32_e32 v241, 0xffff0000, v130
	v_pk_add_f32 v[88:89], v[88:89], v[240:241]
	v_lshlrev_b32_e32 v240, 16, v131
	v_and_b32_e32 v241, 0xffff0000, v131
	v_pk_add_f32 v[90:91], v[90:91], v[240:241]
	s_add_u32 s42, s62, 0x40400
	s_addc_u32 s43, s63, 0
	global_load_dwordx4 v[128:131], v205, s[42:43] sc0 sc1
	s_waitcnt vmcnt(16)
	v_lshlrev_b32_e32 v240, 16, v132
	v_and_b32_e32 v241, 0xffff0000, v132
	v_pk_add_f32 v[116:117], v[116:117], v[240:241]
	v_lshlrev_b32_e32 v240, 16, v133
	v_and_b32_e32 v241, 0xffff0000, v133
	v_pk_add_f32 v[118:119], v[118:119], v[240:241]
	v_lshlrev_b32_e32 v240, 16, v134
	v_and_b32_e32 v241, 0xffff0000, v134
	v_pk_add_f32 v[112:113], v[112:113], v[240:241]
	v_lshlrev_b32_e32 v240, 16, v135
	v_and_b32_e32 v241, 0xffff0000, v135
	v_pk_add_f32 v[114:115], v[114:115], v[240:241]
	s_add_u32 s98, s62, 0x41400
	s_addc_u32 s99, s63, 0
	global_load_dwordx4 v[132:135], v205, s[98:99] sc0 sc1
	s_waitcnt vmcnt(16)
	v_lshlrev_b32_e32 v240, 16, v136
	v_and_b32_e32 v241, 0xffff0000, v136
	v_pk_add_f32 v[84:85], v[84:85], v[240:241]
	v_lshlrev_b32_e32 v240, 16, v137
	v_and_b32_e32 v241, 0xffff0000, v137
	v_pk_add_f32 v[86:87], v[86:87], v[240:241]
	v_lshlrev_b32_e32 v240, 16, v138
	v_and_b32_e32 v241, 0xffff0000, v138
	v_pk_add_f32 v[80:81], v[80:81], v[240:241]
	v_lshlrev_b32_e32 v240, 16, v139
	v_and_b32_e32 v241, 0xffff0000, v139
	v_pk_add_f32 v[82:83], v[82:83], v[240:241]
	s_add_u32 s42, s62, 0x40800
	s_addc_u32 s43, s63, 0
	global_load_dwordx4 v[136:139], v205, s[42:43] sc0 sc1
	s_waitcnt vmcnt(16)
	v_lshlrev_b32_e32 v240, 16, v140
	v_and_b32_e32 v241, 0xffff0000, v140
	v_pk_add_f32 v[108:109], v[108:109], v[240:241]
	v_lshlrev_b32_e32 v240, 16, v141
	v_and_b32_e32 v241, 0xffff0000, v141
	v_pk_add_f32 v[110:111], v[110:111], v[240:241]
	v_lshlrev_b32_e32 v240, 16, v142
	v_and_b32_e32 v241, 0xffff0000, v142
	v_pk_add_f32 v[104:105], v[104:105], v[240:241]
	v_lshlrev_b32_e32 v240, 16, v143
	v_and_b32_e32 v241, 0xffff0000, v143
	v_pk_add_f32 v[106:107], v[106:107], v[240:241]
	s_add_u32 s98, s62, 0x41800
	s_addc_u32 s99, s63, 0
	global_load_dwordx4 v[140:143], v205, s[98:99] sc0 sc1
	s_waitcnt vmcnt(16)
	v_lshlrev_b32_e32 v240, 16, v144
	v_and_b32_e32 v241, 0xffff0000, v144
	v_pk_add_f32 v[76:77], v[76:77], v[240:241]
	v_lshlrev_b32_e32 v240, 16, v145
	v_and_b32_e32 v241, 0xffff0000, v145
	v_pk_add_f32 v[78:79], v[78:79], v[240:241]
	v_lshlrev_b32_e32 v240, 16, v146
	v_and_b32_e32 v241, 0xffff0000, v146
	v_pk_add_f32 v[72:73], v[72:73], v[240:241]
	v_lshlrev_b32_e32 v240, 16, v147
	v_and_b32_e32 v241, 0xffff0000, v147
	v_pk_add_f32 v[74:75], v[74:75], v[240:241]
	s_add_u32 s42, s62, 0x40c00
	s_addc_u32 s43, s63, 0
	global_load_dwordx4 v[144:147], v205, s[42:43] sc0 sc1
	s_waitcnt vmcnt(16)
	v_lshlrev_b32_e32 v240, 16, v148
	v_and_b32_e32 v241, 0xffff0000, v148
	v_pk_add_f32 v[100:101], v[100:101], v[240:241]
	v_lshlrev_b32_e32 v240, 16, v149
	v_and_b32_e32 v241, 0xffff0000, v149
	v_pk_add_f32 v[102:103], v[102:103], v[240:241]
	v_lshlrev_b32_e32 v240, 16, v150
	v_and_b32_e32 v241, 0xffff0000, v150
	v_pk_add_f32 v[96:97], v[96:97], v[240:241]
	v_lshlrev_b32_e32 v240, 16, v151
	v_and_b32_e32 v241, 0xffff0000, v151
	v_pk_add_f32 v[98:99], v[98:99], v[240:241]
	s_add_u32 s98, s62, 0x41c00
	s_addc_u32 s99, s63, 0
	global_load_dwordx4 v[148:151], v205, s[98:99] sc0 sc1
	s_waitcnt vmcnt(16)
	v_lshlrev_b32_e32 v240, 16, v152
	v_and_b32_e32 v241, 0xffff0000, v152
	v_pk_add_f32 v[68:69], v[68:69], v[240:241]
	v_lshlrev_b32_e32 v240, 16, v153
	v_and_b32_e32 v241, 0xffff0000, v153
	v_pk_add_f32 v[70:71], v[70:71], v[240:241]
	v_lshlrev_b32_e32 v240, 16, v154
	v_and_b32_e32 v241, 0xffff0000, v154
	v_pk_add_f32 v[64:65], v[64:65], v[240:241]
	v_lshlrev_b32_e32 v240, 16, v155
	v_and_b32_e32 v241, 0xffff0000, v155
	v_pk_add_f32 v[66:67], v[66:67], v[240:241]
	s_add_u32 s42, s62, 0x42000
	s_addc_u32 s43, s63, 0
	global_load_dwordx4 v[152:155], v205, s[42:43] sc0 sc1
	s_waitcnt vmcnt(16)
	v_lshlrev_b32_e32 v240, 16, v156
	v_and_b32_e32 v241, 0xffff0000, v156
	v_pk_add_f32 v[60:61], v[60:61], v[240:241]
	v_lshlrev_b32_e32 v240, 16, v157
	v_and_b32_e32 v241, 0xffff0000, v157
	v_pk_add_f32 v[62:63], v[62:63], v[240:241]
	v_lshlrev_b32_e32 v240, 16, v158
	v_and_b32_e32 v241, 0xffff0000, v158
	v_pk_add_f32 v[56:57], v[56:57], v[240:241]
	v_lshlrev_b32_e32 v240, 16, v159
	v_and_b32_e32 v241, 0xffff0000, v159
	v_pk_add_f32 v[58:59], v[58:59], v[240:241]
	s_add_u32 s98, s62, 0x43000
	s_addc_u32 s99, s63, 0
	global_load_dwordx4 v[156:159], v205, s[98:99] sc0 sc1
	s_waitcnt vmcnt(16)
	v_lshlrev_b32_e32 v240, 16, v160
	v_and_b32_e32 v241, 0xffff0000, v160
	v_pk_add_f32 v[28:29], v[28:29], v[240:241]
	v_lshlrev_b32_e32 v240, 16, v161
	v_and_b32_e32 v241, 0xffff0000, v161
	v_pk_add_f32 v[30:31], v[30:31], v[240:241]
	v_lshlrev_b32_e32 v240, 16, v162
	v_and_b32_e32 v241, 0xffff0000, v162
	v_pk_add_f32 v[24:25], v[24:25], v[240:241]
	v_lshlrev_b32_e32 v240, 16, v163
	v_and_b32_e32 v241, 0xffff0000, v163
	v_pk_add_f32 v[26:27], v[26:27], v[240:241]
	s_add_u32 s42, s62, 0x42400
	s_addc_u32 s43, s63, 0
	global_load_dwordx4 v[160:163], v205, s[42:43] sc0 sc1
	s_waitcnt vmcnt(16)
	v_lshlrev_b32_e32 v240, 16, v164
	v_and_b32_e32 v241, 0xffff0000, v164
	v_pk_add_f32 v[52:53], v[52:53], v[240:241]
	v_lshlrev_b32_e32 v240, 16, v165
	v_and_b32_e32 v241, 0xffff0000, v165
	v_pk_add_f32 v[54:55], v[54:55], v[240:241]
	v_lshlrev_b32_e32 v240, 16, v166
	v_and_b32_e32 v241, 0xffff0000, v166
	v_pk_add_f32 v[48:49], v[48:49], v[240:241]
	v_lshlrev_b32_e32 v240, 16, v167
	v_and_b32_e32 v241, 0xffff0000, v167
	v_pk_add_f32 v[50:51], v[50:51], v[240:241]
	s_add_u32 s98, s62, 0x43400
	s_addc_u32 s99, s63, 0
	global_load_dwordx4 v[164:167], v205, s[98:99] sc0 sc1
	s_waitcnt vmcnt(16)
	v_lshlrev_b32_e32 v240, 16, v168
	v_and_b32_e32 v241, 0xffff0000, v168
	v_pk_add_f32 v[20:21], v[20:21], v[240:241]
	v_lshlrev_b32_e32 v240, 16, v169
	v_and_b32_e32 v241, 0xffff0000, v169
	v_pk_add_f32 v[22:23], v[22:23], v[240:241]
	v_lshlrev_b32_e32 v240, 16, v170
	v_and_b32_e32 v241, 0xffff0000, v170
	v_pk_add_f32 v[16:17], v[16:17], v[240:241]
	v_lshlrev_b32_e32 v240, 16, v171
	v_and_b32_e32 v241, 0xffff0000, v171
	v_pk_add_f32 v[18:19], v[18:19], v[240:241]
	s_add_u32 s42, s62, 0x42800
	s_addc_u32 s43, s63, 0
	global_load_dwordx4 v[168:171], v205, s[42:43] sc0 sc1
	s_waitcnt vmcnt(16)
	v_lshlrev_b32_e32 v240, 16, v172
	v_and_b32_e32 v241, 0xffff0000, v172
	v_pk_add_f32 v[44:45], v[44:45], v[240:241]
	v_lshlrev_b32_e32 v240, 16, v173
	v_and_b32_e32 v241, 0xffff0000, v173
	v_pk_add_f32 v[46:47], v[46:47], v[240:241]
	v_lshlrev_b32_e32 v240, 16, v174
	v_and_b32_e32 v241, 0xffff0000, v174
	v_pk_add_f32 v[40:41], v[40:41], v[240:241]
	v_lshlrev_b32_e32 v240, 16, v175
	v_and_b32_e32 v241, 0xffff0000, v175
	v_pk_add_f32 v[42:43], v[42:43], v[240:241]
	s_add_u32 s98, s62, 0x43800
	s_addc_u32 s99, s63, 0
	global_load_dwordx4 v[172:175], v205, s[98:99] sc0 sc1
	s_waitcnt vmcnt(16)
	v_lshlrev_b32_e32 v240, 16, v176
	v_and_b32_e32 v241, 0xffff0000, v176
	v_pk_add_f32 v[12:13], v[12:13], v[240:241]
	v_lshlrev_b32_e32 v240, 16, v177
	v_and_b32_e32 v241, 0xffff0000, v177
	v_pk_add_f32 v[14:15], v[14:15], v[240:241]
	v_lshlrev_b32_e32 v240, 16, v178
	v_and_b32_e32 v241, 0xffff0000, v178
	v_pk_add_f32 v[8:9], v[8:9], v[240:241]
	v_lshlrev_b32_e32 v240, 16, v179
	v_and_b32_e32 v241, 0xffff0000, v179
	v_pk_add_f32 v[10:11], v[10:11], v[240:241]
	s_add_u32 s42, s62, 0x42c00
	s_addc_u32 s43, s63, 0
	global_load_dwordx4 v[176:179], v205, s[42:43] sc0 sc1
	s_waitcnt vmcnt(16)
	v_lshlrev_b32_e32 v240, 16, v180
	v_and_b32_e32 v241, 0xffff0000, v180
	v_pk_add_f32 v[36:37], v[36:37], v[240:241]
	v_lshlrev_b32_e32 v240, 16, v181
	v_and_b32_e32 v241, 0xffff0000, v181
	v_pk_add_f32 v[38:39], v[38:39], v[240:241]
	v_lshlrev_b32_e32 v240, 16, v182
	v_and_b32_e32 v241, 0xffff0000, v182
	v_pk_add_f32 v[32:33], v[32:33], v[240:241]
	v_lshlrev_b32_e32 v240, 16, v183
	v_and_b32_e32 v241, 0xffff0000, v183
	v_pk_add_f32 v[34:35], v[34:35], v[240:241]
	s_add_u32 s98, s62, 0x43c00
	s_addc_u32 s99, s63, 0
	global_load_dwordx4 v[180:183], v205, s[98:99] sc0 sc1
	s_waitcnt vmcnt(16)
	v_lshlrev_b32_e32 v240, 16, v206
	v_and_b32_e32 v241, 0xffff0000, v206
	v_pk_add_f32 v[4:5], v[4:5], v[240:241]
	v_lshlrev_b32_e32 v240, 16, v207
	v_and_b32_e32 v241, 0xffff0000, v207
	v_pk_add_f32 v[6:7], v[6:7], v[240:241]
	v_lshlrev_b32_e32 v240, 16, v208
	v_and_b32_e32 v241, 0xffff0000, v208
	v_pk_add_f32 v[0:1], v[0:1], v[240:241]
	v_lshlrev_b32_e32 v240, 16, v209
	v_and_b32_e32 v241, 0xffff0000, v209
	v_pk_add_f32 v[2:3], v[2:3], v[240:241]
	s_add_u32 s42, s14, 0x0
	s_addc_u32 s43, s15, 0
	global_load_dwordx4 v[206:209], v235, s[42:43]
	s_waitcnt vmcnt(16)
	v_lshlrev_b32_e32 v240, 16, v210
	v_and_b32_e32 v241, 0xffff0000, v210
	v_pk_add_f32 v[124:125], v[124:125], v[240:241]
	v_lshlrev_b32_e32 v240, 16, v211
	v_and_b32_e32 v241, 0xffff0000, v211
	v_pk_add_f32 v[126:127], v[126:127], v[240:241]
	v_lshlrev_b32_e32 v240, 16, v212
	v_and_b32_e32 v241, 0xffff0000, v212
	v_pk_add_f32 v[120:121], v[120:121], v[240:241]
	v_lshlrev_b32_e32 v240, 16, v213
	v_and_b32_e32 v241, 0xffff0000, v213
	v_pk_add_f32 v[122:123], v[122:123], v[240:241]
	s_add_u32 s98, s10, 0x0
	s_addc_u32 s99, s11, 0
	global_load_dwordx4 v[210:213], v203, s[98:99]
	s_waitcnt vmcnt(16)
	v_lshlrev_b32_e32 v240, 16, v236
	v_and_b32_e32 v241, 0xffff0000, v236
	v_pk_add_f32 v[92:93], v[92:93], v[240:241]
	v_lshlrev_b32_e32 v240, 16, v237
	v_and_b32_e32 v241, 0xffff0000, v237
	v_pk_add_f32 v[94:95], v[94:95], v[240:241]
	v_lshlrev_b32_e32 v240, 16, v238
	v_and_b32_e32 v241, 0xffff0000, v238
	v_pk_add_f32 v[88:89], v[88:89], v[240:241]
	v_lshlrev_b32_e32 v240, 16, v239
	v_and_b32_e32 v241, 0xffff0000, v239
	v_pk_add_f32 v[90:91], v[90:91], v[240:241]
	s_add_u32 s42, s14, 0x0
	s_addc_u32 s43, s15, 0
	global_load_dwordx4 v[236:239], v235, s[42:43] offset:16
	s_waitcnt vmcnt(16)
	v_lshlrev_b32_e32 v240, 16, v128
	v_and_b32_e32 v241, 0xffff0000, v128
	v_pk_add_f32 v[116:117], v[116:117], v[240:241]
	v_lshlrev_b32_e32 v240, 16, v129
	v_and_b32_e32 v241, 0xffff0000, v129
	v_pk_add_f32 v[118:119], v[118:119], v[240:241]
	v_lshlrev_b32_e32 v240, 16, v130
	v_and_b32_e32 v241, 0xffff0000, v130
	v_pk_add_f32 v[112:113], v[112:113], v[240:241]
	v_lshlrev_b32_e32 v240, 16, v131
	v_and_b32_e32 v241, 0xffff0000, v131
	v_pk_add_f32 v[114:115], v[114:115], v[240:241]
	s_add_u32 s98, s10, 0x0
	s_addc_u32 s99, s11, 0
	global_load_dwordx4 v[128:131], v203, s[98:99] offset:16
	s_waitcnt vmcnt(16)
	v_lshlrev_b32_e32 v240, 16, v132
	v_and_b32_e32 v241, 0xffff0000, v132
	v_pk_add_f32 v[84:85], v[84:85], v[240:241]
	v_lshlrev_b32_e32 v240, 16, v133
	v_and_b32_e32 v241, 0xffff0000, v133
	v_pk_add_f32 v[86:87], v[86:87], v[240:241]
	v_lshlrev_b32_e32 v240, 16, v134
	v_and_b32_e32 v241, 0xffff0000, v134
	v_pk_add_f32 v[80:81], v[80:81], v[240:241]
	v_lshlrev_b32_e32 v240, 16, v135
	v_and_b32_e32 v241, 0xffff0000, v135
	v_pk_add_f32 v[82:83], v[82:83], v[240:241]
	s_add_u32 s42, s14, 0x200
	s_addc_u32 s43, s15, 0
	global_load_dwordx4 v[132:135], v235, s[42:43]
	s_waitcnt vmcnt(16)
	v_lshlrev_b32_e32 v240, 16, v136
	v_and_b32_e32 v241, 0xffff0000, v136
	v_pk_add_f32 v[108:109], v[108:109], v[240:241]
	v_lshlrev_b32_e32 v240, 16, v137
	v_and_b32_e32 v241, 0xffff0000, v137
	v_pk_add_f32 v[110:111], v[110:111], v[240:241]
	v_lshlrev_b32_e32 v240, 16, v138
	v_and_b32_e32 v241, 0xffff0000, v138
	v_pk_add_f32 v[104:105], v[104:105], v[240:241]
	v_lshlrev_b32_e32 v240, 16, v139
	v_and_b32_e32 v241, 0xffff0000, v139
	v_pk_add_f32 v[106:107], v[106:107], v[240:241]
	s_add_u32 s98, s10, 0x200
	s_addc_u32 s99, s11, 0
	global_load_dwordx4 v[136:139], v203, s[98:99]
	s_waitcnt vmcnt(16)
	v_lshlrev_b32_e32 v240, 16, v140
	v_and_b32_e32 v241, 0xffff0000, v140
	v_pk_add_f32 v[76:77], v[76:77], v[240:241]
	v_lshlrev_b32_e32 v240, 16, v141
	v_and_b32_e32 v241, 0xffff0000, v141
	v_pk_add_f32 v[78:79], v[78:79], v[240:241]
	v_lshlrev_b32_e32 v240, 16, v142
	v_and_b32_e32 v241, 0xffff0000, v142
	v_pk_add_f32 v[72:73], v[72:73], v[240:241]
	v_lshlrev_b32_e32 v240, 16, v143
	v_and_b32_e32 v241, 0xffff0000, v143
	v_pk_add_f32 v[74:75], v[74:75], v[240:241]
	s_add_u32 s42, s14, 0x200
	s_addc_u32 s43, s15, 0
	global_load_dwordx4 v[140:143], v235, s[42:43] offset:16
	s_waitcnt vmcnt(16)
	v_lshlrev_b32_e32 v240, 16, v144
	v_and_b32_e32 v241, 0xffff0000, v144
	v_pk_add_f32 v[100:101], v[100:101], v[240:241]
	v_lshlrev_b32_e32 v240, 16, v145
	v_and_b32_e32 v241, 0xffff0000, v145
	v_pk_add_f32 v[102:103], v[102:103], v[240:241]
	v_lshlrev_b32_e32 v240, 16, v146
	v_and_b32_e32 v241, 0xffff0000, v146
	v_pk_add_f32 v[96:97], v[96:97], v[240:241]
	v_lshlrev_b32_e32 v240, 16, v147
	v_and_b32_e32 v241, 0xffff0000, v147
	v_pk_add_f32 v[98:99], v[98:99], v[240:241]
	s_add_u32 s98, s10, 0x200
	s_addc_u32 s99, s11, 0
	global_load_dwordx4 v[144:147], v203, s[98:99] offset:16
	s_waitcnt vmcnt(16)
	v_lshlrev_b32_e32 v240, 16, v148
	v_and_b32_e32 v241, 0xffff0000, v148
	v_pk_add_f32 v[68:69], v[68:69], v[240:241]
	v_lshlrev_b32_e32 v240, 16, v149
	v_and_b32_e32 v241, 0xffff0000, v149
	v_pk_add_f32 v[70:71], v[70:71], v[240:241]
	v_lshlrev_b32_e32 v240, 16, v150
	v_and_b32_e32 v241, 0xffff0000, v150
	v_pk_add_f32 v[64:65], v[64:65], v[240:241]
	v_lshlrev_b32_e32 v240, 16, v151
	v_and_b32_e32 v241, 0xffff0000, v151
	v_pk_add_f32 v[66:67], v[66:67], v[240:241]
	s_add_u32 s42, s14, 0x18000
	s_addc_u32 s43, s15, 0
	global_load_dwordx4 v[148:151], v235, s[42:43]
	s_waitcnt vmcnt(16)
	v_lshlrev_b32_e32 v240, 16, v152
	v_and_b32_e32 v241, 0xffff0000, v152
	v_pk_add_f32 v[60:61], v[60:61], v[240:241]
	v_lshlrev_b32_e32 v240, 16, v153
	v_and_b32_e32 v241, 0xffff0000, v153
	v_pk_add_f32 v[62:63], v[62:63], v[240:241]
	v_lshlrev_b32_e32 v240, 16, v154
	v_and_b32_e32 v241, 0xffff0000, v154
	v_pk_add_f32 v[56:57], v[56:57], v[240:241]
	v_lshlrev_b32_e32 v240, 16, v155
	v_and_b32_e32 v241, 0xffff0000, v155
	v_pk_add_f32 v[58:59], v[58:59], v[240:241]
	s_add_u32 s98, s10, 0x10000
	s_addc_u32 s99, s11, 0
	global_load_dwordx4 v[152:155], v203, s[98:99]
	s_waitcnt vmcnt(16)
	v_lshlrev_b32_e32 v240, 16, v156
	v_and_b32_e32 v241, 0xffff0000, v156
	v_pk_add_f32 v[28:29], v[28:29], v[240:241]
	v_lshlrev_b32_e32 v240, 16, v157
	v_and_b32_e32 v241, 0xffff0000, v157
	v_pk_add_f32 v[30:31], v[30:31], v[240:241]
	v_lshlrev_b32_e32 v240, 16, v158
	v_and_b32_e32 v241, 0xffff0000, v158
	v_pk_add_f32 v[24:25], v[24:25], v[240:241]
	v_lshlrev_b32_e32 v240, 16, v159
	v_and_b32_e32 v241, 0xffff0000, v159
	v_pk_add_f32 v[26:27], v[26:27], v[240:241]
	s_add_u32 s42, s14, 0x18000
	s_addc_u32 s43, s15, 0
	global_load_dwordx4 v[156:159], v235, s[42:43] offset:16
	s_waitcnt vmcnt(16)
	v_lshlrev_b32_e32 v240, 16, v160
	v_and_b32_e32 v241, 0xffff0000, v160
	v_pk_add_f32 v[52:53], v[52:53], v[240:241]
	v_lshlrev_b32_e32 v240, 16, v161
	v_and_b32_e32 v241, 0xffff0000, v161
	v_pk_add_f32 v[54:55], v[54:55], v[240:241]
	v_lshlrev_b32_e32 v240, 16, v162
	v_and_b32_e32 v241, 0xffff0000, v162
	v_pk_add_f32 v[48:49], v[48:49], v[240:241]
	v_lshlrev_b32_e32 v240, 16, v163
	v_and_b32_e32 v241, 0xffff0000, v163
	v_pk_add_f32 v[50:51], v[50:51], v[240:241]
	s_add_u32 s98, s10, 0x10000
	s_addc_u32 s99, s11, 0
	global_load_dwordx4 v[160:163], v203, s[98:99] offset:16
	s_waitcnt vmcnt(16)
	v_lshlrev_b32_e32 v240, 16, v164
	v_and_b32_e32 v241, 0xffff0000, v164
	v_pk_add_f32 v[20:21], v[20:21], v[240:241]
	v_lshlrev_b32_e32 v240, 16, v165
	v_and_b32_e32 v241, 0xffff0000, v165
	v_pk_add_f32 v[22:23], v[22:23], v[240:241]
	v_lshlrev_b32_e32 v240, 16, v166
	v_and_b32_e32 v241, 0xffff0000, v166
	v_pk_add_f32 v[16:17], v[16:17], v[240:241]
	v_lshlrev_b32_e32 v240, 16, v167
	v_and_b32_e32 v241, 0xffff0000, v167
	v_pk_add_f32 v[18:19], v[18:19], v[240:241]
	s_add_u32 s42, s14, 0x18200
	s_addc_u32 s43, s15, 0
	global_load_dwordx4 v[164:167], v235, s[42:43]
	s_waitcnt vmcnt(16)
	v_lshlrev_b32_e32 v240, 16, v168
	v_and_b32_e32 v241, 0xffff0000, v168
	v_pk_add_f32 v[44:45], v[44:45], v[240:241]
	v_lshlrev_b32_e32 v240, 16, v169
	v_and_b32_e32 v241, 0xffff0000, v169
	v_pk_add_f32 v[46:47], v[46:47], v[240:241]
	v_lshlrev_b32_e32 v240, 16, v170
	v_and_b32_e32 v241, 0xffff0000, v170
	v_pk_add_f32 v[40:41], v[40:41], v[240:241]
	v_lshlrev_b32_e32 v240, 16, v171
	v_and_b32_e32 v241, 0xffff0000, v171
	v_pk_add_f32 v[42:43], v[42:43], v[240:241]
	s_add_u32 s98, s10, 0x10200
	s_addc_u32 s99, s11, 0
	global_load_dwordx4 v[168:171], v203, s[98:99]
	s_waitcnt vmcnt(16)
	v_lshlrev_b32_e32 v240, 16, v172
	v_and_b32_e32 v241, 0xffff0000, v172
	v_pk_add_f32 v[12:13], v[12:13], v[240:241]
	v_lshlrev_b32_e32 v240, 16, v173
	v_and_b32_e32 v241, 0xffff0000, v173
	v_pk_add_f32 v[14:15], v[14:15], v[240:241]
	v_lshlrev_b32_e32 v240, 16, v174
	v_and_b32_e32 v241, 0xffff0000, v174
	v_pk_add_f32 v[8:9], v[8:9], v[240:241]
	v_lshlrev_b32_e32 v240, 16, v175
	v_and_b32_e32 v241, 0xffff0000, v175
	v_pk_add_f32 v[10:11], v[10:11], v[240:241]
	s_add_u32 s42, s14, 0x18200
	s_addc_u32 s43, s15, 0
	global_load_dwordx4 v[172:175], v235, s[42:43] offset:16
	s_waitcnt vmcnt(16)
	v_lshlrev_b32_e32 v240, 16, v176
	v_and_b32_e32 v241, 0xffff0000, v176
	v_pk_add_f32 v[36:37], v[36:37], v[240:241]
	v_lshlrev_b32_e32 v240, 16, v177
	v_and_b32_e32 v241, 0xffff0000, v177
	v_pk_add_f32 v[38:39], v[38:39], v[240:241]
	v_lshlrev_b32_e32 v240, 16, v178
	v_and_b32_e32 v241, 0xffff0000, v178
	v_pk_add_f32 v[32:33], v[32:33], v[240:241]
	v_lshlrev_b32_e32 v240, 16, v179
	v_and_b32_e32 v241, 0xffff0000, v179
	v_pk_add_f32 v[34:35], v[34:35], v[240:241]
	s_add_u32 s98, s10, 0x10200
	s_addc_u32 s99, s11, 0
	global_load_dwordx4 v[176:179], v203, s[98:99] offset:16
	s_waitcnt vmcnt(16)
	v_lshlrev_b32_e32 v240, 16, v180
	v_and_b32_e32 v241, 0xffff0000, v180
	v_pk_add_f32 v[4:5], v[4:5], v[240:241]
	v_lshlrev_b32_e32 v240, 16, v181
	v_and_b32_e32 v241, 0xffff0000, v181
	v_pk_add_f32 v[6:7], v[6:7], v[240:241]
	v_lshlrev_b32_e32 v240, 16, v182
	v_and_b32_e32 v241, 0xffff0000, v182
	v_pk_add_f32 v[0:1], v[0:1], v[240:241]
	v_lshlrev_b32_e32 v240, 16, v183
	v_and_b32_e32 v241, 0xffff0000, v183
	v_pk_add_f32 v[2:3], v[2:3], v[240:241]
	s_add_u32 s42, s14, 0x30000
	s_addc_u32 s43, s15, 0
	global_load_dwordx4 v[180:183], v235, s[42:43]
	s_waitcnt vmcnt(15)
	v_pk_fma_f32 v[124:125], v[206:207], v[124:125], v[210:211]
	v_pk_fma_f32 v[126:127], v[208:209], v[126:127], v[212:213]
	s_add_u32 s98, s10, 0x0
	s_addc_u32 s99, s11, 0
	global_store_dwordx4 v203, v[124:127], s[98:99]
	s_add_u32 s42, s10, 0x20000
	s_addc_u32 s43, s11, 0
	global_load_dwordx4 v[206:209], v203, s[42:43]
	s_add_u32 s98, s14, 0x30000
	s_addc_u32 s99, s15, 0
	global_load_dwordx4 v[210:213], v235, s[98:99] offset:16
	s_waitcnt vmcnt(16)
	v_pk_fma_f32 v[120:121], v[236:237], v[120:121], v[128:129]
	v_pk_fma_f32 v[122:123], v[238:239], v[122:123], v[130:131]
	s_add_u32 s42, s10, 0x0
	s_addc_u32 s43, s11, 0
	global_store_dwordx4 v203, v[120:123], s[42:43] offset:16
	s_add_u32 s98, s10, 0x20000
	s_addc_u32 s99, s11, 0
	global_load_dwordx4 v[236:239], v203, s[98:99] offset:16
	s_add_u32 s42, s14, 0x30200
	s_addc_u32 s43, s15, 0
	global_load_dwordx4 v[128:131], v235, s[42:43]
	s_waitcnt vmcnt(17)
	v_pk_fma_f32 v[92:93], v[132:133], v[92:93], v[136:137]
	v_pk_fma_f32 v[94:95], v[134:135], v[94:95], v[138:139]
	s_add_u32 s98, s10, 0x200
	s_addc_u32 s99, s11, 0
	global_store_dwordx4 v203, v[92:95], s[98:99]
	s_add_u32 s42, s10, 0x20200
	s_addc_u32 s43, s11, 0
	global_load_dwordx4 v[132:135], v203, s[42:43]
	s_add_u32 s98, s14, 0x30200
	s_addc_u32 s99, s15, 0
	global_load_dwordx4 v[136:139], v235, s[98:99] offset:16
	s_waitcnt vmcnt(18)
	v_pk_fma_f32 v[88:89], v[140:141], v[88:89], v[144:145]
	v_pk_fma_f32 v[90:91], v[142:143], v[90:91], v[146:147]
	s_add_u32 s42, s10, 0x200
	s_addc_u32 s43, s11, 0
	global_store_dwordx4 v203, v[88:91], s[42:43] offset:16
	s_add_u32 s98, s10, 0x20200
	s_addc_u32 s99, s11, 0
	global_load_dwordx4 v[140:143], v203, s[98:99] offset:16
	s_add_u32 s42, s14, 0x48000
	s_addc_u32 s43, s15, 0
	global_load_dwordx4 v[144:147], v235, s[42:43]
	s_waitcnt vmcnt(19)
	v_pk_fma_f32 v[116:117], v[148:149], v[116:117], v[152:153]
	v_pk_fma_f32 v[118:119], v[150:151], v[118:119], v[154:155]
	s_add_u32 s98, s10, 0x10000
	s_addc_u32 s99, s11, 0
	global_store_dwordx4 v203, v[116:119], s[98:99]
	s_add_u32 s42, s10, 0x30000
	s_addc_u32 s43, s11, 0
	global_load_dwordx4 v[148:151], v203, s[42:43]
	s_add_u32 s98, s14, 0x48000
	s_addc_u32 s99, s15, 0
	global_load_dwordx4 v[152:155], v235, s[98:99] offset:16
	s_waitcnt vmcnt(20)
	v_pk_fma_f32 v[112:113], v[156:157], v[112:113], v[160:161]
	v_pk_fma_f32 v[114:115], v[158:159], v[114:115], v[162:163]
	s_add_u32 s42, s10, 0x10000
	s_addc_u32 s43, s11, 0
	global_store_dwordx4 v203, v[112:115], s[42:43] offset:16
	s_add_u32 s98, s10, 0x30000
	s_addc_u32 s99, s11, 0
	global_load_dwordx4 v[156:159], v203, s[98:99] offset:16
	s_add_u32 s42, s14, 0x48200
	s_addc_u32 s43, s15, 0
	global_load_dwordx4 v[160:163], v235, s[42:43]
	s_waitcnt vmcnt(21)
	v_pk_fma_f32 v[84:85], v[164:165], v[84:85], v[168:169]
	v_pk_fma_f32 v[86:87], v[166:167], v[86:87], v[170:171]
	s_add_u32 s98, s10, 0x10200
	s_addc_u32 s99, s11, 0
	global_store_dwordx4 v203, v[84:87], s[98:99]
	s_add_u32 s42, s10, 0x30200
	s_addc_u32 s43, s11, 0
	global_load_dwordx4 v[164:167], v203, s[42:43]
	s_add_u32 s98, s14, 0x48200
	s_addc_u32 s99, s15, 0
	global_load_dwordx4 v[168:171], v235, s[98:99] offset:16
	s_waitcnt vmcnt(22)
	v_pk_fma_f32 v[80:81], v[172:173], v[80:81], v[176:177]
	v_pk_fma_f32 v[82:83], v[174:175], v[82:83], v[178:179]
	s_add_u32 s42, s10, 0x10200
	s_addc_u32 s43, s11, 0
	global_store_dwordx4 v203, v[80:83], s[42:43] offset:16
	s_add_u32 s98, s10, 0x30200
	s_addc_u32 s99, s11, 0
	global_load_dwordx4 v[172:175], v203, s[98:99] offset:16
	s_add_u32 s42, s14, 0xc0000
	s_addc_u32 s43, s15, 0
	global_load_dwordx4 v[176:179], v235, s[42:43]
	s_waitcnt vmcnt(22)
	v_pk_fma_f32 v[108:109], v[180:181], v[108:109], v[206:207]
	v_pk_fma_f32 v[110:111], v[182:183], v[110:111], v[208:209]
	s_add_u32 s98, s10, 0x20000
	s_addc_u32 s99, s11, 0
	global_store_dwordx4 v203, v[108:111], s[98:99]
	s_add_u32 s42, s10, 0x80000
	s_addc_u32 s43, s11, 0
	global_load_dwordx4 v[180:183], v203, s[42:43]
	s_add_u32 s98, s14, 0xc0000
	s_addc_u32 s99, s15, 0
	global_load_dwordx4 v[206:209], v235, s[98:99] offset:16
	s_waitcnt vmcnt(22)
	v_pk_fma_f32 v[104:105], v[210:211], v[104:105], v[236:237]
	v_pk_fma_f32 v[106:107], v[212:213], v[106:107], v[238:239]
	s_add_u32 s42, s10, 0x20000
	s_addc_u32 s43, s11, 0
	global_store_dwordx4 v203, v[104:107], s[42:43] offset:16
	s_add_u32 s98, s10, 0x80000
	s_addc_u32 s99, s11, 0
	global_load_dwordx4 v[210:213], v203, s[98:99] offset:16
	s_add_u32 s42, s14, 0xc0200
	s_addc_u32 s43, s15, 0
	global_load_dwordx4 v[236:239], v235, s[42:43]
	s_waitcnt vmcnt(22)
	v_pk_fma_f32 v[76:77], v[128:129], v[76:77], v[132:133]
	v_pk_fma_f32 v[78:79], v[130:131], v[78:79], v[134:135]
	s_add_u32 s98, s10, 0x20200
	s_addc_u32 s99, s11, 0
	global_store_dwordx4 v203, v[76:79], s[98:99]
	s_add_u32 s42, s10, 0x80200
	s_addc_u32 s43, s11, 0
	global_load_dwordx4 v[128:131], v203, s[42:43]
	s_add_u32 s98, s14, 0xc0200
	s_addc_u32 s99, s15, 0
	global_load_dwordx4 v[132:135], v235, s[98:99] offset:16
	s_waitcnt vmcnt(22)
	v_pk_fma_f32 v[72:73], v[136:137], v[72:73], v[140:141]
	v_pk_fma_f32 v[74:75], v[138:139], v[74:75], v[142:143]
	s_add_u32 s42, s10, 0x20200
	s_addc_u32 s43, s11, 0
	global_store_dwordx4 v203, v[72:75], s[42:43] offset:16
	s_add_u32 s98, s10, 0x80200
	s_addc_u32 s99, s11, 0
	global_load_dwordx4 v[136:139], v203, s[98:99] offset:16
	s_add_u32 s42, s14, 0xd8000
	s_addc_u32 s43, s15, 0
	global_load_dwordx4 v[140:143], v235, s[42:43]
	s_waitcnt vmcnt(22)
	v_pk_fma_f32 v[100:101], v[144:145], v[100:101], v[148:149]
	v_pk_fma_f32 v[102:103], v[146:147], v[102:103], v[150:151]
	s_add_u32 s98, s10, 0x30000
	s_addc_u32 s99, s11, 0
	global_store_dwordx4 v203, v[100:103], s[98:99]
	s_add_u32 s42, s10, 0x90000
	s_addc_u32 s43, s11, 0
	global_load_dwordx4 v[144:147], v203, s[42:43]
	s_add_u32 s98, s14, 0xd8000
	s_addc_u32 s99, s15, 0
	global_load_dwordx4 v[148:151], v235, s[98:99] offset:16
	s_waitcnt vmcnt(22)
	v_pk_fma_f32 v[96:97], v[152:153], v[96:97], v[156:157]
	v_pk_fma_f32 v[98:99], v[154:155], v[98:99], v[158:159]
	s_add_u32 s42, s10, 0x30000
	s_addc_u32 s43, s11, 0
	global_store_dwordx4 v203, v[96:99], s[42:43] offset:16
	s_add_u32 s98, s10, 0x90000
	s_addc_u32 s99, s11, 0
	global_load_dwordx4 v[152:155], v203, s[98:99] offset:16
	s_add_u32 s42, s14, 0xd8200
	s_addc_u32 s43, s15, 0
	global_load_dwordx4 v[156:159], v235, s[42:43]
	s_waitcnt vmcnt(22)
	v_pk_fma_f32 v[68:69], v[160:161], v[68:69], v[164:165]
	v_pk_fma_f32 v[70:71], v[162:163], v[70:71], v[166:167]
	s_add_u32 s98, s10, 0x30200
	s_addc_u32 s99, s11, 0
	global_store_dwordx4 v203, v[68:71], s[98:99]
	s_add_u32 s42, s10, 0x90200
	s_addc_u32 s43, s11, 0
	global_load_dwordx4 v[160:163], v203, s[42:43]
	s_add_u32 s98, s14, 0xd8200
	s_addc_u32 s99, s15, 0
	global_load_dwordx4 v[164:167], v235, s[98:99] offset:16
	s_waitcnt vmcnt(22)
	v_pk_fma_f32 v[64:65], v[168:169], v[64:65], v[172:173]
	v_pk_fma_f32 v[66:67], v[170:171], v[66:67], v[174:175]
	s_add_u32 s42, s10, 0x30200
	s_addc_u32 s43, s11, 0
	global_store_dwordx4 v203, v[64:67], s[42:43] offset:16
	s_add_u32 s98, s10, 0x90200
	s_addc_u32 s99, s11, 0
	global_load_dwordx4 v[168:171], v203, s[98:99] offset:16
	s_add_u32 s42, s14, 0xf0000
	s_addc_u32 s43, s15, 0
	global_load_dwordx4 v[172:175], v235, s[42:43]
	s_waitcnt vmcnt(22)
	v_pk_fma_f32 v[60:61], v[176:177], v[60:61], v[180:181]
	v_pk_fma_f32 v[62:63], v[178:179], v[62:63], v[182:183]
	s_add_u32 s98, s10, 0x80000
	s_addc_u32 s99, s11, 0
	global_store_dwordx4 v203, v[60:63], s[98:99]
	s_add_u32 s42, s10, 0xa0000
	s_addc_u32 s43, s11, 0
	global_load_dwordx4 v[176:179], v203, s[42:43]
	s_add_u32 s98, s14, 0xf0000
	s_addc_u32 s99, s15, 0
	global_load_dwordx4 v[180:183], v235, s[98:99] offset:16
	s_waitcnt vmcnt(22)
	v_pk_fma_f32 v[56:57], v[206:207], v[56:57], v[210:211]
	v_pk_fma_f32 v[58:59], v[208:209], v[58:59], v[212:213]
	s_add_u32 s42, s10, 0x80000
	s_addc_u32 s43, s11, 0
	global_store_dwordx4 v203, v[56:59], s[42:43] offset:16
	s_add_u32 s98, s10, 0xa0000
	s_addc_u32 s99, s11, 0
	global_load_dwordx4 v[206:209], v203, s[98:99] offset:16
	s_add_u32 s42, s14, 0xf0200
	s_addc_u32 s43, s15, 0
	global_load_dwordx4 v[210:213], v235, s[42:43]
	s_waitcnt vmcnt(22)
	v_pk_fma_f32 v[28:29], v[236:237], v[28:29], v[128:129]
	v_pk_fma_f32 v[30:31], v[238:239], v[30:31], v[130:131]
	s_add_u32 s98, s10, 0x80200
	s_addc_u32 s99, s11, 0
	global_store_dwordx4 v203, v[28:31], s[98:99]
	s_add_u32 s42, s10, 0xa0200
	s_addc_u32 s43, s11, 0
	global_load_dwordx4 v[236:239], v203, s[42:43]
	s_add_u32 s98, s14, 0xf0200
	s_addc_u32 s99, s15, 0
	global_load_dwordx4 v[128:131], v235, s[98:99] offset:16
	s_waitcnt vmcnt(22)
	v_pk_fma_f32 v[24:25], v[132:133], v[24:25], v[136:137]
	v_pk_fma_f32 v[26:27], v[134:135], v[26:27], v[138:139]
	s_add_u32 s42, s10, 0x80200
	s_addc_u32 s43, s11, 0
	global_store_dwordx4 v203, v[24:27], s[42:43] offset:16
	s_add_u32 s98, s10, 0xa0200
	s_addc_u32 s99, s11, 0
	global_load_dwordx4 v[132:135], v203, s[98:99] offset:16
	s_waitcnt vmcnt(21)
	v_pk_fma_f32 v[52:53], v[140:141], v[52:53], v[144:145]
	v_pk_fma_f32 v[54:55], v[142:143], v[54:55], v[146:147]
	s_add_u32 s42, s10, 0x90000
	s_addc_u32 s43, s11, 0
	global_store_dwordx4 v203, v[52:55], s[42:43]
	s_waitcnt vmcnt(19)
	v_pk_fma_f32 v[48:49], v[148:149], v[48:49], v[152:153]
	v_pk_fma_f32 v[50:51], v[150:151], v[50:51], v[154:155]
	s_add_u32 s98, s10, 0x90000
	s_addc_u32 s99, s11, 0
	global_store_dwordx4 v203, v[48:51], s[98:99] offset:16
	s_waitcnt vmcnt(17)
	v_pk_fma_f32 v[20:21], v[156:157], v[20:21], v[160:161]
	v_pk_fma_f32 v[22:23], v[158:159], v[22:23], v[162:163]
	s_add_u32 s42, s10, 0x90200
	s_addc_u32 s43, s11, 0
	global_store_dwordx4 v203, v[20:23], s[42:43]
	s_waitcnt vmcnt(15)
	v_pk_fma_f32 v[16:17], v[164:165], v[16:17], v[168:169]
	v_pk_fma_f32 v[18:19], v[166:167], v[18:19], v[170:171]
	s_add_u32 s98, s10, 0x90200
	s_addc_u32 s99, s11, 0
	global_store_dwordx4 v203, v[16:19], s[98:99] offset:16
	s_waitcnt vmcnt(13)
	v_pk_fma_f32 v[44:45], v[172:173], v[44:45], v[176:177]
	v_pk_fma_f32 v[46:47], v[174:175], v[46:47], v[178:179]
	s_add_u32 s42, s10, 0xa0000
	s_addc_u32 s43, s11, 0
	global_store_dwordx4 v203, v[44:47], s[42:43]
	s_waitcnt vmcnt(11)
	v_pk_fma_f32 v[40:41], v[180:181], v[40:41], v[206:207]
	v_pk_fma_f32 v[42:43], v[182:183], v[42:43], v[208:209]
	s_add_u32 s98, s10, 0xa0000
	s_addc_u32 s99, s11, 0
	global_store_dwordx4 v203, v[40:43], s[98:99] offset:16
	s_waitcnt vmcnt(9)
	v_pk_fma_f32 v[12:13], v[210:211], v[12:13], v[236:237]
	v_pk_fma_f32 v[14:15], v[212:213], v[14:15], v[238:239]
	s_add_u32 s42, s10, 0xa0200
	s_addc_u32 s43, s11, 0
	global_store_dwordx4 v203, v[12:15], s[42:43]
	s_waitcnt vmcnt(7)
	v_pk_fma_f32 v[8:9], v[128:129], v[8:9], v[132:133]
	v_pk_fma_f32 v[10:11], v[130:131], v[10:11], v[134:135]
	s_add_u32 s98, s10, 0xa0200
	s_addc_u32 s99, s11, 0
	global_store_dwordx4 v203, v[8:11], s[98:99] offset:16
	s_branch .Lfs_predone
.Lfs_np2:
	s_add_u32 s42, s62, 0x0
	s_addc_u32 s43, s63, 0
	global_load_dwordx4 v[128:131], v205, s[42:43] sc0 sc1
	s_add_u32 s98, s62, 0x1000
	s_addc_u32 s99, s63, 0
	global_load_dwordx4 v[132:135], v205, s[98:99] sc0 sc1
	s_add_u32 s42, s62, 0x400
	s_addc_u32 s43, s63, 0
	global_load_dwordx4 v[136:139], v205, s[42:43] sc0 sc1
	s_add_u32 s98, s62, 0x1400
	s_addc_u32 s99, s63, 0
	global_load_dwordx4 v[140:143], v205, s[98:99] sc0 sc1
	s_add_u32 s42, s62, 0x800
	s_addc_u32 s43, s63, 0
	global_load_dwordx4 v[144:147], v205, s[42:43] sc0 sc1
	s_add_u32 s98, s62, 0x1800
	s_addc_u32 s99, s63, 0
	global_load_dwordx4 v[148:151], v205, s[98:99] sc0 sc1
	s_add_u32 s42, s62, 0xc00
	s_addc_u32 s43, s63, 0
	global_load_dwordx4 v[152:155], v205, s[42:43] sc0 sc1
	s_add_u32 s98, s62, 0x1c00
	s_addc_u32 s99, s63, 0
	global_load_dwordx4 v[156:159], v205, s[98:99] sc0 sc1
	s_add_u32 s42, s62, 0x2000
	s_addc_u32 s43, s63, 0
	global_load_dwordx4 v[160:163], v205, s[42:43] sc0 sc1
	s_add_u32 s98, s62, 0x3000
	s_addc_u32 s99, s63, 0
	global_load_dwordx4 v[164:167], v205, s[98:99] sc0 sc1
	s_add_u32 s42, s62, 0x2400
	s_addc_u32 s43, s63, 0
	global_load_dwordx4 v[168:171], v205, s[42:43] sc0 sc1
	s_add_u32 s98, s62, 0x3400
	s_addc_u32 s99, s63, 0
	global_load_dwordx4 v[172:175], v205, s[98:99] sc0 sc1
	s_add_u32 s42, s62, 0x2800
	s_addc_u32 s43, s63, 0
	global_load_dwordx4 v[176:179], v205, s[42:43] sc0 sc1
	s_add_u32 s98, s62, 0x3800
	s_addc_u32 s99, s63, 0
	global_load_dwordx4 v[180:183], v205, s[98:99] sc0 sc1
	s_add_u32 s42, s62, 0x2c00
	s_addc_u32 s43, s63, 0
	global_load_dwordx4 v[206:209], v205, s[42:43] sc0 sc1
	s_add_u32 s98, s62, 0x3c00
	s_addc_u32 s99, s63, 0
	global_load_dwordx4 v[210:213], v205, s[98:99] sc0 sc1
	s_add_u32 s42, s62, 0x20000
	s_addc_u32 s43, s63, 0
	global_load_dwordx4 v[236:239], v205, s[42:43] sc0 sc1
	s_waitcnt vmcnt(16)
	v_lshlrev_b32_e32 v240, 16, v128
	v_and_b32_e32 v241, 0xffff0000, v128
	v_pk_add_f32 v[124:125], v[124:125], v[240:241]
	v_lshlrev_b32_e32 v240, 16, v129
	v_and_b32_e32 v241, 0xffff0000, v129
	v_pk_add_f32 v[126:127], v[126:127], v[240:241]
	v_lshlrev_b32_e32 v240, 16, v130
	v_and_b32_e32 v241, 0xffff0000, v130
	v_pk_add_f32 v[120:121], v[120:121], v[240:241]
	v_lshlrev_b32_e32 v240, 16, v131
	v_and_b32_e32 v241, 0xffff0000, v131
	v_pk_add_f32 v[122:123], v[122:123], v[240:241]
	s_add_u32 s98, s62, 0x21000
	s_addc_u32 s99, s63, 0
	global_load_dwordx4 v[128:131], v205, s[98:99] sc0 sc1
	s_waitcnt vmcnt(16)
	v_lshlrev_b32_e32 v240, 16, v132
	v_and_b32_e32 v241, 0xffff0000, v132
	v_pk_add_f32 v[92:93], v[92:93], v[240:241]
	v_lshlrev_b32_e32 v240, 16, v133
	v_and_b32_e32 v241, 0xffff0000, v133
	v_pk_add_f32 v[94:95], v[94:95], v[240:241]
	v_lshlrev_b32_e32 v240, 16, v134
	v_and_b32_e32 v241, 0xffff0000, v134
	v_pk_add_f32 v[88:89], v[88:89], v[240:241]
	v_lshlrev_b32_e32 v240, 16, v135
	v_and_b32_e32 v241, 0xffff0000, v135
	v_pk_add_f32 v[90:91], v[90:91], v[240:241]
	s_add_u32 s42, s62, 0x20400
	s_addc_u32 s43, s63, 0
	global_load_dwordx4 v[132:135], v205, s[42:43] sc0 sc1
	s_waitcnt vmcnt(16)
	v_lshlrev_b32_e32 v240, 16, v136
	v_and_b32_e32 v241, 0xffff0000, v136
	v_pk_add_f32 v[116:117], v[116:117], v[240:241]
	v_lshlrev_b32_e32 v240, 16, v137
	v_and_b32_e32 v241, 0xffff0000, v137
	v_pk_add_f32 v[118:119], v[118:119], v[240:241]
	v_lshlrev_b32_e32 v240, 16, v138
	v_and_b32_e32 v241, 0xffff0000, v138
	v_pk_add_f32 v[112:113], v[112:113], v[240:241]
	v_lshlrev_b32_e32 v240, 16, v139
	v_and_b32_e32 v241, 0xffff0000, v139
	v_pk_add_f32 v[114:115], v[114:115], v[240:241]
	s_add_u32 s98, s62, 0x21400
	s_addc_u32 s99, s63, 0
	global_load_dwordx4 v[136:139], v205, s[98:99] sc0 sc1
	s_waitcnt vmcnt(16)
	v_lshlrev_b32_e32 v240, 16, v140
	v_and_b32_e32 v241, 0xffff0000, v140
	v_pk_add_f32 v[84:85], v[84:85], v[240:241]
	v_lshlrev_b32_e32 v240, 16, v141
	v_and_b32_e32 v241, 0xffff0000, v141
	v_pk_add_f32 v[86:87], v[86:87], v[240:241]
	v_lshlrev_b32_e32 v240, 16, v142
	v_and_b32_e32 v241, 0xffff0000, v142
	v_pk_add_f32 v[80:81], v[80:81], v[240:241]
	v_lshlrev_b32_e32 v240, 16, v143
	v_and_b32_e32 v241, 0xffff0000, v143
	v_pk_add_f32 v[82:83], v[82:83], v[240:241]
	s_add_u32 s42, s62, 0x20800
	s_addc_u32 s43, s63, 0
	global_load_dwordx4 v[140:143], v205, s[42:43] sc0 sc1
	s_waitcnt vmcnt(16)
	v_lshlrev_b32_e32 v240, 16, v144
	v_and_b32_e32 v241, 0xffff0000, v144
	v_pk_add_f32 v[108:109], v[108:109], v[240:241]
	v_lshlrev_b32_e32 v240, 16, v145
	v_and_b32_e32 v241, 0xffff0000, v145
	v_pk_add_f32 v[110:111], v[110:111], v[240:241]
	v_lshlrev_b32_e32 v240, 16, v146
	v_and_b32_e32 v241, 0xffff0000, v146
	v_pk_add_f32 v[104:105], v[104:105], v[240:241]
	v_lshlrev_b32_e32 v240, 16, v147
	v_and_b32_e32 v241, 0xffff0000, v147
	v_pk_add_f32 v[106:107], v[106:107], v[240:241]
	s_add_u32 s98, s62, 0x21800
	s_addc_u32 s99, s63, 0
	global_load_dwordx4 v[144:147], v205, s[98:99] sc0 sc1
	s_waitcnt vmcnt(16)
	v_lshlrev_b32_e32 v240, 16, v148
	v_and_b32_e32 v241, 0xffff0000, v148
	v_pk_add_f32 v[76:77], v[76:77], v[240:241]
	v_lshlrev_b32_e32 v240, 16, v149
	v_and_b32_e32 v241, 0xffff0000, v149
	v_pk_add_f32 v[78:79], v[78:79], v[240:241]
	v_lshlrev_b32_e32 v240, 16, v150
	v_and_b32_e32 v241, 0xffff0000, v150
	v_pk_add_f32 v[72:73], v[72:73], v[240:241]
	v_lshlrev_b32_e32 v240, 16, v151
	v_and_b32_e32 v241, 0xffff0000, v151
	v_pk_add_f32 v[74:75], v[74:75], v[240:241]
	s_add_u32 s42, s62, 0x20c00
	s_addc_u32 s43, s63, 0
	global_load_dwordx4 v[148:151], v205, s[42:43] sc0 sc1
	s_waitcnt vmcnt(16)
	v_lshlrev_b32_e32 v240, 16, v152
	v_and_b32_e32 v241, 0xffff0000, v152
	v_pk_add_f32 v[100:101], v[100:101], v[240:241]
	v_lshlrev_b32_e32 v240, 16, v153
	v_and_b32_e32 v241, 0xffff0000, v153
	v_pk_add_f32 v[102:103], v[102:103], v[240:241]
	v_lshlrev_b32_e32 v240, 16, v154
	v_and_b32_e32 v241, 0xffff0000, v154
	v_pk_add_f32 v[96:97], v[96:97], v[240:241]
	v_lshlrev_b32_e32 v240, 16, v155
	v_and_b32_e32 v241, 0xffff0000, v155
	v_pk_add_f32 v[98:99], v[98:99], v[240:241]
	s_add_u32 s98, s62, 0x21c00
	s_addc_u32 s99, s63, 0
	global_load_dwordx4 v[152:155], v205, s[98:99] sc0 sc1
	s_waitcnt vmcnt(16)
	v_lshlrev_b32_e32 v240, 16, v156
	v_and_b32_e32 v241, 0xffff0000, v156
	v_pk_add_f32 v[68:69], v[68:69], v[240:241]
	v_lshlrev_b32_e32 v240, 16, v157
	v_and_b32_e32 v241, 0xffff0000, v157
	v_pk_add_f32 v[70:71], v[70:71], v[240:241]
	v_lshlrev_b32_e32 v240, 16, v158
	v_and_b32_e32 v241, 0xffff0000, v158
	v_pk_add_f32 v[64:65], v[64:65], v[240:241]
	v_lshlrev_b32_e32 v240, 16, v159
	v_and_b32_e32 v241, 0xffff0000, v159
	v_pk_add_f32 v[66:67], v[66:67], v[240:241]
	s_add_u32 s42, s62, 0x22000
	s_addc_u32 s43, s63, 0
	global_load_dwordx4 v[156:159], v205, s[42:43] sc0 sc1
	s_waitcnt vmcnt(16)
	v_lshlrev_b32_e32 v240, 16, v160
	v_and_b32_e32 v241, 0xffff0000, v160
	v_pk_add_f32 v[60:61], v[60:61], v[240:241]
	v_lshlrev_b32_e32 v240, 16, v161
	v_and_b32_e32 v241, 0xffff0000, v161
	v_pk_add_f32 v[62:63], v[62:63], v[240:241]
	v_lshlrev_b32_e32 v240, 16, v162
	v_and_b32_e32 v241, 0xffff0000, v162
	v_pk_add_f32 v[56:57], v[56:57], v[240:241]
	v_lshlrev_b32_e32 v240, 16, v163
	v_and_b32_e32 v241, 0xffff0000, v163
	v_pk_add_f32 v[58:59], v[58:59], v[240:241]
	s_add_u32 s98, s62, 0x23000
	s_addc_u32 s99, s63, 0
	global_load_dwordx4 v[160:163], v205, s[98:99] sc0 sc1
	s_waitcnt vmcnt(16)
	v_lshlrev_b32_e32 v240, 16, v164
	v_and_b32_e32 v241, 0xffff0000, v164
	v_pk_add_f32 v[28:29], v[28:29], v[240:241]
	v_lshlrev_b32_e32 v240, 16, v165
	v_and_b32_e32 v241, 0xffff0000, v165
	v_pk_add_f32 v[30:31], v[30:31], v[240:241]
	v_lshlrev_b32_e32 v240, 16, v166
	v_and_b32_e32 v241, 0xffff0000, v166
	v_pk_add_f32 v[24:25], v[24:25], v[240:241]
	v_lshlrev_b32_e32 v240, 16, v167
	v_and_b32_e32 v241, 0xffff0000, v167
	v_pk_add_f32 v[26:27], v[26:27], v[240:241]
	s_add_u32 s42, s62, 0x22400
	s_addc_u32 s43, s63, 0
	global_load_dwordx4 v[164:167], v205, s[42:43] sc0 sc1
	s_waitcnt vmcnt(16)
	v_lshlrev_b32_e32 v240, 16, v168
	v_and_b32_e32 v241, 0xffff0000, v168
	v_pk_add_f32 v[52:53], v[52:53], v[240:241]
	v_lshlrev_b32_e32 v240, 16, v169
	v_and_b32_e32 v241, 0xffff0000, v169
	v_pk_add_f32 v[54:55], v[54:55], v[240:241]
	v_lshlrev_b32_e32 v240, 16, v170
	v_and_b32_e32 v241, 0xffff0000, v170
	v_pk_add_f32 v[48:49], v[48:49], v[240:241]
	v_lshlrev_b32_e32 v240, 16, v171
	v_and_b32_e32 v241, 0xffff0000, v171
	v_pk_add_f32 v[50:51], v[50:51], v[240:241]
	s_add_u32 s98, s62, 0x23400
	s_addc_u32 s99, s63, 0
	global_load_dwordx4 v[168:171], v205, s[98:99] sc0 sc1
	s_waitcnt vmcnt(16)
	v_lshlrev_b32_e32 v240, 16, v172
	v_and_b32_e32 v241, 0xffff0000, v172
	v_pk_add_f32 v[20:21], v[20:21], v[240:241]
	v_lshlrev_b32_e32 v240, 16, v173
	v_and_b32_e32 v241, 0xffff0000, v173
	v_pk_add_f32 v[22:23], v[22:23], v[240:241]
	v_lshlrev_b32_e32 v240, 16, v174
	v_and_b32_e32 v241, 0xffff0000, v174
	v_pk_add_f32 v[16:17], v[16:17], v[240:241]
	v_lshlrev_b32_e32 v240, 16, v175
	v_and_b32_e32 v241, 0xffff0000, v175
	v_pk_add_f32 v[18:19], v[18:19], v[240:241]
	s_add_u32 s42, s62, 0x22800
	s_addc_u32 s43, s63, 0
	global_load_dwordx4 v[172:175], v205, s[42:43] sc0 sc1
	s_waitcnt vmcnt(16)
	v_lshlrev_b32_e32 v240, 16, v176
	v_and_b32_e32 v241, 0xffff0000, v176
	v_pk_add_f32 v[44:45], v[44:45], v[240:241]
	v_lshlrev_b32_e32 v240, 16, v177
	v_and_b32_e32 v241, 0xffff0000, v177
	v_pk_add_f32 v[46:47], v[46:47], v[240:241]
	v_lshlrev_b32_e32 v240, 16, v178
	v_and_b32_e32 v241, 0xffff0000, v178
	v_pk_add_f32 v[40:41], v[40:41], v[240:241]
	v_lshlrev_b32_e32 v240, 16, v179
	v_and_b32_e32 v241, 0xffff0000, v179
	v_pk_add_f32 v[42:43], v[42:43], v[240:241]
	s_add_u32 s98, s62, 0x23800
	s_addc_u32 s99, s63, 0
	global_load_dwordx4 v[176:179], v205, s[98:99] sc0 sc1
	s_waitcnt vmcnt(16)
	v_lshlrev_b32_e32 v240, 16, v180
	v_and_b32_e32 v241, 0xffff0000, v180
	v_pk_add_f32 v[12:13], v[12:13], v[240:241]
	v_lshlrev_b32_e32 v240, 16, v181
	v_and_b32_e32 v241, 0xffff0000, v181
	v_pk_add_f32 v[14:15], v[14:15], v[240:241]
	v_lshlrev_b32_e32 v240, 16, v182
	v_and_b32_e32 v241, 0xffff0000, v182
	v_pk_add_f32 v[8:9], v[8:9], v[240:241]
	v_lshlrev_b32_e32 v240, 16, v183
	v_and_b32_e32 v241, 0xffff0000, v183
	v_pk_add_f32 v[10:11], v[10:11], v[240:241]
	s_add_u32 s42, s62, 0x22c00
	s_addc_u32 s43, s63, 0
	global_load_dwordx4 v[180:183], v205, s[42:43] sc0 sc1
	s_waitcnt vmcnt(16)
	v_lshlrev_b32_e32 v240, 16, v206
	v_and_b32_e32 v241, 0xffff0000, v206
	v_pk_add_f32 v[36:37], v[36:37], v[240:241]
	v_lshlrev_b32_e32 v240, 16, v207
	v_and_b32_e32 v241, 0xffff0000, v207
	v_pk_add_f32 v[38:39], v[38:39], v[240:241]
	v_lshlrev_b32_e32 v240, 16, v208
	v_and_b32_e32 v241, 0xffff0000, v208
	v_pk_add_f32 v[32:33], v[32:33], v[240:241]
	v_lshlrev_b32_e32 v240, 16, v209
	v_and_b32_e32 v241, 0xffff0000, v209
	v_pk_add_f32 v[34:35], v[34:35], v[240:241]
	s_add_u32 s98, s62, 0x23c00
	s_addc_u32 s99, s63, 0
	global_load_dwordx4 v[206:209], v205, s[98:99] sc0 sc1
	s_waitcnt vmcnt(16)
	v_lshlrev_b32_e32 v240, 16, v210
	v_and_b32_e32 v241, 0xffff0000, v210
	v_pk_add_f32 v[4:5], v[4:5], v[240:241]
	v_lshlrev_b32_e32 v240, 16, v211
	v_and_b32_e32 v241, 0xffff0000, v211
	v_pk_add_f32 v[6:7], v[6:7], v[240:241]
	v_lshlrev_b32_e32 v240, 16, v212
	v_and_b32_e32 v241, 0xffff0000, v212
	v_pk_add_f32 v[0:1], v[0:1], v[240:241]
	v_lshlrev_b32_e32 v240, 16, v213
	v_and_b32_e32 v241, 0xffff0000, v213
	v_pk_add_f32 v[2:3], v[2:3], v[240:241]
	s_add_u32 s42, s14, 0x0
	s_addc_u32 s43, s15, 0
	global_load_dwordx4 v[210:213], v235, s[42:43]
	s_waitcnt vmcnt(16)
	v_lshlrev_b32_e32 v240, 16, v236
	v_and_b32_e32 v241, 0xffff0000, v236
	v_pk_add_f32 v[124:125], v[124:125], v[240:241]
	v_lshlrev_b32_e32 v240, 16, v237
	v_and_b32_e32 v241, 0xffff0000, v237
	v_pk_add_f32 v[126:127], v[126:127], v[240:241]
	v_lshlrev_b32_e32 v240, 16, v238
	v_and_b32_e32 v241, 0xffff0000, v238
	v_pk_add_f32 v[120:121], v[120:121], v[240:241]
	v_lshlrev_b32_e32 v240, 16, v239
	v_and_b32_e32 v241, 0xffff0000, v239
	v_pk_add_f32 v[122:123], v[122:123], v[240:241]
	s_add_u32 s98, s10, 0x0
	s_addc_u32 s99, s11, 0
	global_load_dwordx4 v[236:239], v203, s[98:99]
	s_waitcnt vmcnt(16)
	v_lshlrev_b32_e32 v240, 16, v128
	v_and_b32_e32 v241, 0xffff0000, v128
	v_pk_add_f32 v[92:93], v[92:93], v[240:241]
	v_lshlrev_b32_e32 v240, 16, v129
	v_and_b32_e32 v241, 0xffff0000, v129
	v_pk_add_f32 v[94:95], v[94:95], v[240:241]
	v_lshlrev_b32_e32 v240, 16, v130
	v_and_b32_e32 v241, 0xffff0000, v130
	v_pk_add_f32 v[88:89], v[88:89], v[240:241]
	v_lshlrev_b32_e32 v240, 16, v131
	v_and_b32_e32 v241, 0xffff0000, v131
	v_pk_add_f32 v[90:91], v[90:91], v[240:241]
	s_add_u32 s42, s14, 0x0
	s_addc_u32 s43, s15, 0
	global_load_dwordx4 v[128:131], v235, s[42:43] offset:16
	s_waitcnt vmcnt(16)
	v_lshlrev_b32_e32 v240, 16, v132
	v_and_b32_e32 v241, 0xffff0000, v132
	v_pk_add_f32 v[116:117], v[116:117], v[240:241]
	v_lshlrev_b32_e32 v240, 16, v133
	v_and_b32_e32 v241, 0xffff0000, v133
	v_pk_add_f32 v[118:119], v[118:119], v[240:241]
	v_lshlrev_b32_e32 v240, 16, v134
	v_and_b32_e32 v241, 0xffff0000, v134
	v_pk_add_f32 v[112:113], v[112:113], v[240:241]
	v_lshlrev_b32_e32 v240, 16, v135
	v_and_b32_e32 v241, 0xffff0000, v135
	v_pk_add_f32 v[114:115], v[114:115], v[240:241]
	s_add_u32 s98, s10, 0x0
	s_addc_u32 s99, s11, 0
	global_load_dwordx4 v[132:135], v203, s[98:99] offset:16
	s_waitcnt vmcnt(16)
	v_lshlrev_b32_e32 v240, 16, v136
	v_and_b32_e32 v241, 0xffff0000, v136
	v_pk_add_f32 v[84:85], v[84:85], v[240:241]
	v_lshlrev_b32_e32 v240, 16, v137
	v_and_b32_e32 v241, 0xffff0000, v137
	v_pk_add_f32 v[86:87], v[86:87], v[240:241]
	v_lshlrev_b32_e32 v240, 16, v138
	v_and_b32_e32 v241, 0xffff0000, v138
	v_pk_add_f32 v[80:81], v[80:81], v[240:241]
	v_lshlrev_b32_e32 v240, 16, v139
	v_and_b32_e32 v241, 0xffff0000, v139
	v_pk_add_f32 v[82:83], v[82:83], v[240:241]
	s_add_u32 s42, s14, 0x200
	s_addc_u32 s43, s15, 0
	global_load_dwordx4 v[136:139], v235, s[42:43]
	s_waitcnt vmcnt(16)
	v_lshlrev_b32_e32 v240, 16, v140
	v_and_b32_e32 v241, 0xffff0000, v140
	v_pk_add_f32 v[108:109], v[108:109], v[240:241]
	v_lshlrev_b32_e32 v240, 16, v141
	v_and_b32_e32 v241, 0xffff0000, v141
	v_pk_add_f32 v[110:111], v[110:111], v[240:241]
	v_lshlrev_b32_e32 v240, 16, v142
	v_and_b32_e32 v241, 0xffff0000, v142
	v_pk_add_f32 v[104:105], v[104:105], v[240:241]
	v_lshlrev_b32_e32 v240, 16, v143
	v_and_b32_e32 v241, 0xffff0000, v143
	v_pk_add_f32 v[106:107], v[106:107], v[240:241]
	s_add_u32 s98, s10, 0x200
	s_addc_u32 s99, s11, 0
	global_load_dwordx4 v[140:143], v203, s[98:99]
	s_waitcnt vmcnt(16)
	v_lshlrev_b32_e32 v240, 16, v144
	v_and_b32_e32 v241, 0xffff0000, v144
	v_pk_add_f32 v[76:77], v[76:77], v[240:241]
	v_lshlrev_b32_e32 v240, 16, v145
	v_and_b32_e32 v241, 0xffff0000, v145
	v_pk_add_f32 v[78:79], v[78:79], v[240:241]
	v_lshlrev_b32_e32 v240, 16, v146
	v_and_b32_e32 v241, 0xffff0000, v146
	v_pk_add_f32 v[72:73], v[72:73], v[240:241]
	v_lshlrev_b32_e32 v240, 16, v147
	v_and_b32_e32 v241, 0xffff0000, v147
	v_pk_add_f32 v[74:75], v[74:75], v[240:241]
	s_add_u32 s42, s14, 0x200
	s_addc_u32 s43, s15, 0
	global_load_dwordx4 v[144:147], v235, s[42:43] offset:16
	s_waitcnt vmcnt(16)
	v_lshlrev_b32_e32 v240, 16, v148
	v_and_b32_e32 v241, 0xffff0000, v148
	v_pk_add_f32 v[100:101], v[100:101], v[240:241]
	v_lshlrev_b32_e32 v240, 16, v149
	v_and_b32_e32 v241, 0xffff0000, v149
	v_pk_add_f32 v[102:103], v[102:103], v[240:241]
	v_lshlrev_b32_e32 v240, 16, v150
	v_and_b32_e32 v241, 0xffff0000, v150
	v_pk_add_f32 v[96:97], v[96:97], v[240:241]
	v_lshlrev_b32_e32 v240, 16, v151
	v_and_b32_e32 v241, 0xffff0000, v151
	v_pk_add_f32 v[98:99], v[98:99], v[240:241]
	s_add_u32 s98, s10, 0x200
	s_addc_u32 s99, s11, 0
	global_load_dwordx4 v[148:151], v203, s[98:99] offset:16
	s_waitcnt vmcnt(16)
	v_lshlrev_b32_e32 v240, 16, v152
	v_and_b32_e32 v241, 0xffff0000, v152
	v_pk_add_f32 v[68:69], v[68:69], v[240:241]
	v_lshlrev_b32_e32 v240, 16, v153
	v_and_b32_e32 v241, 0xffff0000, v153
	v_pk_add_f32 v[70:71], v[70:71], v[240:241]
	v_lshlrev_b32_e32 v240, 16, v154
	v_and_b32_e32 v241, 0xffff0000, v154
	v_pk_add_f32 v[64:65], v[64:65], v[240:241]
	v_lshlrev_b32_e32 v240, 16, v155
	v_and_b32_e32 v241, 0xffff0000, v155
	v_pk_add_f32 v[66:67], v[66:67], v[240:241]
	s_add_u32 s42, s14, 0x18000
	s_addc_u32 s43, s15, 0
	global_load_dwordx4 v[152:155], v235, s[42:43]
	s_waitcnt vmcnt(16)
	v_lshlrev_b32_e32 v240, 16, v156
	v_and_b32_e32 v241, 0xffff0000, v156
	v_pk_add_f32 v[60:61], v[60:61], v[240:241]
	v_lshlrev_b32_e32 v240, 16, v157
	v_and_b32_e32 v241, 0xffff0000, v157
	v_pk_add_f32 v[62:63], v[62:63], v[240:241]
	v_lshlrev_b32_e32 v240, 16, v158
	v_and_b32_e32 v241, 0xffff0000, v158
	v_pk_add_f32 v[56:57], v[56:57], v[240:241]
	v_lshlrev_b32_e32 v240, 16, v159
	v_and_b32_e32 v241, 0xffff0000, v159
	v_pk_add_f32 v[58:59], v[58:59], v[240:241]
	s_add_u32 s98, s10, 0x10000
	s_addc_u32 s99, s11, 0
	global_load_dwordx4 v[156:159], v203, s[98:99]
	s_waitcnt vmcnt(16)
	v_lshlrev_b32_e32 v240, 16, v160
	v_and_b32_e32 v241, 0xffff0000, v160
	v_pk_add_f32 v[28:29], v[28:29], v[240:241]
	v_lshlrev_b32_e32 v240, 16, v161
	v_and_b32_e32 v241, 0xffff0000, v161
	v_pk_add_f32 v[30:31], v[30:31], v[240:241]
	v_lshlrev_b32_e32 v240, 16, v162
	v_and_b32_e32 v241, 0xffff0000, v162
	v_pk_add_f32 v[24:25], v[24:25], v[240:241]
	v_lshlrev_b32_e32 v240, 16, v163
	v_and_b32_e32 v241, 0xffff0000, v163
	v_pk_add_f32 v[26:27], v[26:27], v[240:241]
	s_add_u32 s42, s14, 0x18000
	s_addc_u32 s43, s15, 0
	global_load_dwordx4 v[160:163], v235, s[42:43] offset:16
	s_waitcnt vmcnt(16)
	v_lshlrev_b32_e32 v240, 16, v164
	v_and_b32_e32 v241, 0xffff0000, v164
	v_pk_add_f32 v[52:53], v[52:53], v[240:241]
	v_lshlrev_b32_e32 v240, 16, v165
	v_and_b32_e32 v241, 0xffff0000, v165
	v_pk_add_f32 v[54:55], v[54:55], v[240:241]
	v_lshlrev_b32_e32 v240, 16, v166
	v_and_b32_e32 v241, 0xffff0000, v166
	v_pk_add_f32 v[48:49], v[48:49], v[240:241]
	v_lshlrev_b32_e32 v240, 16, v167
	v_and_b32_e32 v241, 0xffff0000, v167
	v_pk_add_f32 v[50:51], v[50:51], v[240:241]
	s_add_u32 s98, s10, 0x10000
	s_addc_u32 s99, s11, 0
	global_load_dwordx4 v[164:167], v203, s[98:99] offset:16
	s_waitcnt vmcnt(16)
	v_lshlrev_b32_e32 v240, 16, v168
	v_and_b32_e32 v241, 0xffff0000, v168
	v_pk_add_f32 v[20:21], v[20:21], v[240:241]
	v_lshlrev_b32_e32 v240, 16, v169
	v_and_b32_e32 v241, 0xffff0000, v169
	v_pk_add_f32 v[22:23], v[22:23], v[240:241]
	v_lshlrev_b32_e32 v240, 16, v170
	v_and_b32_e32 v241, 0xffff0000, v170
	v_pk_add_f32 v[16:17], v[16:17], v[240:241]
	v_lshlrev_b32_e32 v240, 16, v171
	v_and_b32_e32 v241, 0xffff0000, v171
	v_pk_add_f32 v[18:19], v[18:19], v[240:241]
	s_add_u32 s42, s14, 0x18200
	s_addc_u32 s43, s15, 0
	global_load_dwordx4 v[168:171], v235, s[42:43]
	s_waitcnt vmcnt(16)
	v_lshlrev_b32_e32 v240, 16, v172
	v_and_b32_e32 v241, 0xffff0000, v172
	v_pk_add_f32 v[44:45], v[44:45], v[240:241]
	v_lshlrev_b32_e32 v240, 16, v173
	v_and_b32_e32 v241, 0xffff0000, v173
	v_pk_add_f32 v[46:47], v[46:47], v[240:241]
	v_lshlrev_b32_e32 v240, 16, v174
	v_and_b32_e32 v241, 0xffff0000, v174
	v_pk_add_f32 v[40:41], v[40:41], v[240:241]
	v_lshlrev_b32_e32 v240, 16, v175
	v_and_b32_e32 v241, 0xffff0000, v175
	v_pk_add_f32 v[42:43], v[42:43], v[240:241]
	s_add_u32 s98, s10, 0x10200
	s_addc_u32 s99, s11, 0
	global_load_dwordx4 v[172:175], v203, s[98:99]
	s_waitcnt vmcnt(16)
	v_lshlrev_b32_e32 v240, 16, v176
	v_and_b32_e32 v241, 0xffff0000, v176
	v_pk_add_f32 v[12:13], v[12:13], v[240:241]
	v_lshlrev_b32_e32 v240, 16, v177
	v_and_b32_e32 v241, 0xffff0000, v177
	v_pk_add_f32 v[14:15], v[14:15], v[240:241]
	v_lshlrev_b32_e32 v240, 16, v178
	v_and_b32_e32 v241, 0xffff0000, v178
	v_pk_add_f32 v[8:9], v[8:9], v[240:241]
	v_lshlrev_b32_e32 v240, 16, v179
	v_and_b32_e32 v241, 0xffff0000, v179
	v_pk_add_f32 v[10:11], v[10:11], v[240:241]
	s_add_u32 s42, s14, 0x18200
	s_addc_u32 s43, s15, 0
	global_load_dwordx4 v[176:179], v235, s[42:43] offset:16
	s_waitcnt vmcnt(16)
	v_lshlrev_b32_e32 v240, 16, v180
	v_and_b32_e32 v241, 0xffff0000, v180
	v_pk_add_f32 v[36:37], v[36:37], v[240:241]
	v_lshlrev_b32_e32 v240, 16, v181
	v_and_b32_e32 v241, 0xffff0000, v181
	v_pk_add_f32 v[38:39], v[38:39], v[240:241]
	v_lshlrev_b32_e32 v240, 16, v182
	v_and_b32_e32 v241, 0xffff0000, v182
	v_pk_add_f32 v[32:33], v[32:33], v[240:241]
	v_lshlrev_b32_e32 v240, 16, v183
	v_and_b32_e32 v241, 0xffff0000, v183
	v_pk_add_f32 v[34:35], v[34:35], v[240:241]
	s_add_u32 s98, s10, 0x10200
	s_addc_u32 s99, s11, 0
	global_load_dwordx4 v[180:183], v203, s[98:99] offset:16
	s_waitcnt vmcnt(16)
	v_lshlrev_b32_e32 v240, 16, v206
	v_and_b32_e32 v241, 0xffff0000, v206
	v_pk_add_f32 v[4:5], v[4:5], v[240:241]
	v_lshlrev_b32_e32 v240, 16, v207
	v_and_b32_e32 v241, 0xffff0000, v207
	v_pk_add_f32 v[6:7], v[6:7], v[240:241]
	v_lshlrev_b32_e32 v240, 16, v208
	v_and_b32_e32 v241, 0xffff0000, v208
	v_pk_add_f32 v[0:1], v[0:1], v[240:241]
	v_lshlrev_b32_e32 v240, 16, v209
	v_and_b32_e32 v241, 0xffff0000, v209
	v_pk_add_f32 v[2:3], v[2:3], v[240:241]
	s_add_u32 s42, s14, 0x30000
	s_addc_u32 s43, s15, 0
	global_load_dwordx4 v[206:209], v235, s[42:43]
	s_waitcnt vmcnt(15)
	v_pk_fma_f32 v[124:125], v[210:211], v[124:125], v[236:237]
	v_pk_fma_f32 v[126:127], v[212:213], v[126:127], v[238:239]
	s_add_u32 s98, s10, 0x0
	s_addc_u32 s99, s11, 0
	global_store_dwordx4 v203, v[124:127], s[98:99]
	s_add_u32 s42, s10, 0x20000
	s_addc_u32 s43, s11, 0
	global_load_dwordx4 v[210:213], v203, s[42:43]
	s_add_u32 s98, s14, 0x30000
	s_addc_u32 s99, s15, 0
	global_load_dwordx4 v[236:239], v235, s[98:99] offset:16
	s_waitcnt vmcnt(16)
	v_pk_fma_f32 v[120:121], v[128:129], v[120:121], v[132:133]
	v_pk_fma_f32 v[122:123], v[130:131], v[122:123], v[134:135]
	s_add_u32 s42, s10, 0x0
	s_addc_u32 s43, s11, 0
	global_store_dwordx4 v203, v[120:123], s[42:43] offset:16
	s_add_u32 s98, s10, 0x20000
	s_addc_u32 s99, s11, 0
	global_load_dwordx4 v[128:131], v203, s[98:99] offset:16
	s_add_u32 s42, s14, 0x30200
	s_addc_u32 s43, s15, 0
	global_load_dwordx4 v[132:135], v235, s[42:43]
	s_waitcnt vmcnt(17)
	v_pk_fma_f32 v[92:93], v[136:137], v[92:93], v[140:141]
	v_pk_fma_f32 v[94:95], v[138:139], v[94:95], v[142:143]
	s_add_u32 s98, s10, 0x200
	s_addc_u32 s99, s11, 0
	global_store_dwordx4 v203, v[92:95], s[98:99]
	s_add_u32 s42, s10, 0x20200
	s_addc_u32 s43, s11, 0
	global_load_dwordx4 v[136:139], v203, s[42:43]
	s_add_u32 s98, s14, 0x30200
	s_addc_u32 s99, s15, 0
	global_load_dwordx4 v[140:143], v235, s[98:99] offset:16
	s_waitcnt vmcnt(18)
	v_pk_fma_f32 v[88:89], v[144:145], v[88:89], v[148:149]
	v_pk_fma_f32 v[90:91], v[146:147], v[90:91], v[150:151]
	s_add_u32 s42, s10, 0x200
	s_addc_u32 s43, s11, 0
	global_store_dwordx4 v203, v[88:91], s[42:43] offset:16
	s_add_u32 s98, s10, 0x20200
	s_addc_u32 s99, s11, 0
	global_load_dwordx4 v[144:147], v203, s[98:99] offset:16
	s_add_u32 s42, s14, 0x48000
	s_addc_u32 s43, s15, 0
	global_load_dwordx4 v[148:151], v235, s[42:43]
	s_waitcnt vmcnt(19)
	v_pk_fma_f32 v[116:117], v[152:153], v[116:117], v[156:157]
	v_pk_fma_f32 v[118:119], v[154:155], v[118:119], v[158:159]
	s_add_u32 s98, s10, 0x10000
	s_addc_u32 s99, s11, 0
	global_store_dwordx4 v203, v[116:119], s[98:99]
	s_add_u32 s42, s10, 0x30000
	s_addc_u32 s43, s11, 0
	global_load_dwordx4 v[152:155], v203, s[42:43]
	s_add_u32 s98, s14, 0x48000
	s_addc_u32 s99, s15, 0
	global_load_dwordx4 v[156:159], v235, s[98:99] offset:16
	s_waitcnt vmcnt(20)
	v_pk_fma_f32 v[112:113], v[160:161], v[112:113], v[164:165]
	v_pk_fma_f32 v[114:115], v[162:163], v[114:115], v[166:167]
	s_add_u32 s42, s10, 0x10000
	s_addc_u32 s43, s11, 0
	global_store_dwordx4 v203, v[112:115], s[42:43] offset:16
	s_add_u32 s98, s10, 0x30000
	s_addc_u32 s99, s11, 0
	global_load_dwordx4 v[160:163], v203, s[98:99] offset:16
	s_add_u32 s42, s14, 0x48200
	s_addc_u32 s43, s15, 0
	global_load_dwordx4 v[164:167], v235, s[42:43]
	s_waitcnt vmcnt(21)
	v_pk_fma_f32 v[84:85], v[168:169], v[84:85], v[172:173]
	v_pk_fma_f32 v[86:87], v[170:171], v[86:87], v[174:175]
	s_add_u32 s98, s10, 0x10200
	s_addc_u32 s99, s11, 0
	global_store_dwordx4 v203, v[84:87], s[98:99]
	s_add_u32 s42, s10, 0x30200
	s_addc_u32 s43, s11, 0
	global_load_dwordx4 v[168:171], v203, s[42:43]
	s_add_u32 s98, s14, 0x48200
	s_addc_u32 s99, s15, 0
	global_load_dwordx4 v[172:175], v235, s[98:99] offset:16
	s_waitcnt vmcnt(22)
	v_pk_fma_f32 v[80:81], v[176:177], v[80:81], v[180:181]
	v_pk_fma_f32 v[82:83], v[178:179], v[82:83], v[182:183]
	s_add_u32 s42, s10, 0x10200
	s_addc_u32 s43, s11, 0
	global_store_dwordx4 v203, v[80:83], s[42:43] offset:16
	s_add_u32 s98, s10, 0x30200
	s_addc_u32 s99, s11, 0
	global_load_dwordx4 v[176:179], v203, s[98:99] offset:16
	s_add_u32 s42, s14, 0xc0000
	s_addc_u32 s43, s15, 0
	global_load_dwordx4 v[180:183], v235, s[42:43]
	s_waitcnt vmcnt(22)
	v_pk_fma_f32 v[108:109], v[206:207], v[108:109], v[210:211]
	v_pk_fma_f32 v[110:111], v[208:209], v[110:111], v[212:213]
	s_add_u32 s98, s10, 0x20000
	s_addc_u32 s99, s11, 0
	global_store_dwordx4 v203, v[108:111], s[98:99]
	s_add_u32 s42, s10, 0x80000
	s_addc_u32 s43, s11, 0
	global_load_dwordx4 v[206:209], v203, s[42:43]
	s_add_u32 s98, s14, 0xc0000
	s_addc_u32 s99, s15, 0
	global_load_dwordx4 v[210:213], v235, s[98:99] offset:16
	s_waitcnt vmcnt(22)
	v_pk_fma_f32 v[104:105], v[236:237], v[104:105], v[128:129]
	v_pk_fma_f32 v[106:107], v[238:239], v[106:107], v[130:131]
	s_add_u32 s42, s10, 0x20000
	s_addc_u32 s43, s11, 0
	global_store_dwordx4 v203, v[104:107], s[42:43] offset:16
	s_add_u32 s98, s10, 0x80000
	s_addc_u32 s99, s11, 0
	global_load_dwordx4 v[236:239], v203, s[98:99] offset:16
	s_add_u32 s42, s14, 0xc0200
	s_addc_u32 s43, s15, 0
	global_load_dwordx4 v[128:131], v235, s[42:43]
	s_waitcnt vmcnt(22)
	v_pk_fma_f32 v[76:77], v[132:133], v[76:77], v[136:137]
	v_pk_fma_f32 v[78:79], v[134:135], v[78:79], v[138:139]
	s_add_u32 s98, s10, 0x20200
	s_addc_u32 s99, s11, 0
	global_store_dwordx4 v203, v[76:79], s[98:99]
	s_add_u32 s42, s10, 0x80200
	s_addc_u32 s43, s11, 0
	global_load_dwordx4 v[132:135], v203, s[42:43]
	s_add_u32 s98, s14, 0xc0200
	s_addc_u32 s99, s15, 0
	global_load_dwordx4 v[136:139], v235, s[98:99] offset:16
	s_waitcnt vmcnt(22)
	v_pk_fma_f32 v[72:73], v[140:141], v[72:73], v[144:145]
	v_pk_fma_f32 v[74:75], v[142:143], v[74:75], v[146:147]
	s_add_u32 s42, s10, 0x20200
	s_addc_u32 s43, s11, 0
	global_store_dwordx4 v203, v[72:75], s[42:43] offset:16
	s_add_u32 s98, s10, 0x80200
	s_addc_u32 s99, s11, 0
	global_load_dwordx4 v[140:143], v203, s[98:99] offset:16
	s_add_u32 s42, s14, 0xd8000
	s_addc_u32 s43, s15, 0
	global_load_dwordx4 v[144:147], v235, s[42:43]
	s_waitcnt vmcnt(22)
	v_pk_fma_f32 v[100:101], v[148:149], v[100:101], v[152:153]
	v_pk_fma_f32 v[102:103], v[150:151], v[102:103], v[154:155]
	s_add_u32 s98, s10, 0x30000
	s_addc_u32 s99, s11, 0
	global_store_dwordx4 v203, v[100:103], s[98:99]
	s_add_u32 s42, s10, 0x90000
	s_addc_u32 s43, s11, 0
	global_load_dwordx4 v[148:151], v203, s[42:43]
	s_add_u32 s98, s14, 0xd8000
	s_addc_u32 s99, s15, 0
	global_load_dwordx4 v[152:155], v235, s[98:99] offset:16
	s_waitcnt vmcnt(22)
	v_pk_fma_f32 v[96:97], v[156:157], v[96:97], v[160:161]
	v_pk_fma_f32 v[98:99], v[158:159], v[98:99], v[162:163]
	s_add_u32 s42, s10, 0x30000
	s_addc_u32 s43, s11, 0
	global_store_dwordx4 v203, v[96:99], s[42:43] offset:16
	s_add_u32 s98, s10, 0x90000
	s_addc_u32 s99, s11, 0
	global_load_dwordx4 v[156:159], v203, s[98:99] offset:16
	s_add_u32 s42, s14, 0xd8200
	s_addc_u32 s43, s15, 0
	global_load_dwordx4 v[160:163], v235, s[42:43]
	s_waitcnt vmcnt(22)
	v_pk_fma_f32 v[68:69], v[164:165], v[68:69], v[168:169]
	v_pk_fma_f32 v[70:71], v[166:167], v[70:71], v[170:171]
	s_add_u32 s98, s10, 0x30200
	s_addc_u32 s99, s11, 0
	global_store_dwordx4 v203, v[68:71], s[98:99]
	s_add_u32 s42, s10, 0x90200
	s_addc_u32 s43, s11, 0
	global_load_dwordx4 v[164:167], v203, s[42:43]
	s_add_u32 s98, s14, 0xd8200
	s_addc_u32 s99, s15, 0
	global_load_dwordx4 v[168:171], v235, s[98:99] offset:16
	s_waitcnt vmcnt(22)
	v_pk_fma_f32 v[64:65], v[172:173], v[64:65], v[176:177]
	v_pk_fma_f32 v[66:67], v[174:175], v[66:67], v[178:179]
	s_add_u32 s42, s10, 0x30200
	s_addc_u32 s43, s11, 0
	global_store_dwordx4 v203, v[64:67], s[42:43] offset:16
	s_add_u32 s98, s10, 0x90200
	s_addc_u32 s99, s11, 0
	global_load_dwordx4 v[172:175], v203, s[98:99] offset:16
	s_add_u32 s42, s14, 0xf0000
	s_addc_u32 s43, s15, 0
	global_load_dwordx4 v[176:179], v235, s[42:43]
	s_waitcnt vmcnt(22)
	v_pk_fma_f32 v[60:61], v[180:181], v[60:61], v[206:207]
	v_pk_fma_f32 v[62:63], v[182:183], v[62:63], v[208:209]
	s_add_u32 s98, s10, 0x80000
	s_addc_u32 s99, s11, 0
	global_store_dwordx4 v203, v[60:63], s[98:99]
	s_add_u32 s42, s10, 0xa0000
	s_addc_u32 s43, s11, 0
	global_load_dwordx4 v[180:183], v203, s[42:43]
	s_add_u32 s98, s14, 0xf0000
	s_addc_u32 s99, s15, 0
	global_load_dwordx4 v[206:209], v235, s[98:99] offset:16
	s_waitcnt vmcnt(22)
	v_pk_fma_f32 v[56:57], v[210:211], v[56:57], v[236:237]
	v_pk_fma_f32 v[58:59], v[212:213], v[58:59], v[238:239]
	s_add_u32 s42, s10, 0x80000
	s_addc_u32 s43, s11, 0
	global_store_dwordx4 v203, v[56:59], s[42:43] offset:16
	s_add_u32 s98, s10, 0xa0000
	s_addc_u32 s99, s11, 0
	global_load_dwordx4 v[210:213], v203, s[98:99] offset:16
	s_add_u32 s42, s14, 0xf0200
	s_addc_u32 s43, s15, 0
	global_load_dwordx4 v[236:239], v235, s[42:43]
	s_waitcnt vmcnt(22)
	v_pk_fma_f32 v[28:29], v[128:129], v[28:29], v[132:133]
	v_pk_fma_f32 v[30:31], v[130:131], v[30:31], v[134:135]
	s_add_u32 s98, s10, 0x80200
	s_addc_u32 s99, s11, 0
	global_store_dwordx4 v203, v[28:31], s[98:99]
	s_add_u32 s42, s10, 0xa0200
	s_addc_u32 s43, s11, 0
	global_load_dwordx4 v[128:131], v203, s[42:43]
	s_add_u32 s98, s14, 0xf0200
	s_addc_u32 s99, s15, 0
	global_load_dwordx4 v[132:135], v235, s[98:99] offset:16
	s_waitcnt vmcnt(22)
	v_pk_fma_f32 v[24:25], v[136:137], v[24:25], v[140:141]
	v_pk_fma_f32 v[26:27], v[138:139], v[26:27], v[142:143]
	s_add_u32 s42, s10, 0x80200
	s_addc_u32 s43, s11, 0
	global_store_dwordx4 v203, v[24:27], s[42:43] offset:16
	s_add_u32 s98, s10, 0xa0200
	s_addc_u32 s99, s11, 0
	global_load_dwordx4 v[136:139], v203, s[98:99] offset:16
	s_waitcnt vmcnt(21)
	v_pk_fma_f32 v[52:53], v[144:145], v[52:53], v[148:149]
	v_pk_fma_f32 v[54:55], v[146:147], v[54:55], v[150:151]
	s_add_u32 s42, s10, 0x90000
	s_addc_u32 s43, s11, 0
	global_store_dwordx4 v203, v[52:55], s[42:43]
	s_waitcnt vmcnt(19)
	v_pk_fma_f32 v[48:49], v[152:153], v[48:49], v[156:157]
	v_pk_fma_f32 v[50:51], v[154:155], v[50:51], v[158:159]
	s_add_u32 s98, s10, 0x90000
	s_addc_u32 s99, s11, 0
	global_store_dwordx4 v203, v[48:51], s[98:99] offset:16
	s_waitcnt vmcnt(17)
	v_pk_fma_f32 v[20:21], v[160:161], v[20:21], v[164:165]
	v_pk_fma_f32 v[22:23], v[162:163], v[22:23], v[166:167]
	s_add_u32 s42, s10, 0x90200
	s_addc_u32 s43, s11, 0
	global_store_dwordx4 v203, v[20:23], s[42:43]
	s_waitcnt vmcnt(15)
	v_pk_fma_f32 v[16:17], v[168:169], v[16:17], v[172:173]
	v_pk_fma_f32 v[18:19], v[170:171], v[18:19], v[174:175]
	s_add_u32 s98, s10, 0x90200
	s_addc_u32 s99, s11, 0
	global_store_dwordx4 v203, v[16:19], s[98:99] offset:16
	s_waitcnt vmcnt(13)
	v_pk_fma_f32 v[44:45], v[176:177], v[44:45], v[180:181]
	v_pk_fma_f32 v[46:47], v[178:179], v[46:47], v[182:183]
	s_add_u32 s42, s10, 0xa0000
	s_addc_u32 s43, s11, 0
	global_store_dwordx4 v203, v[44:47], s[42:43]
	s_waitcnt vmcnt(11)
	v_pk_fma_f32 v[40:41], v[206:207], v[40:41], v[210:211]
	v_pk_fma_f32 v[42:43], v[208:209], v[42:43], v[212:213]
	s_add_u32 s98, s10, 0xa0000
	s_addc_u32 s99, s11, 0
	global_store_dwordx4 v203, v[40:43], s[98:99] offset:16
	s_waitcnt vmcnt(9)
	v_pk_fma_f32 v[12:13], v[236:237], v[12:13], v[128:129]
	v_pk_fma_f32 v[14:15], v[238:239], v[14:15], v[130:131]
	s_add_u32 s42, s10, 0xa0200
	s_addc_u32 s43, s11, 0
	global_store_dwordx4 v203, v[12:15], s[42:43]
	s_waitcnt vmcnt(7)
	v_pk_fma_f32 v[8:9], v[132:133], v[8:9], v[136:137]
	v_pk_fma_f32 v[10:11], v[134:135], v[10:11], v[138:139]
	s_add_u32 s98, s10, 0xa0200
	s_addc_u32 s99, s11, 0
	global_store_dwordx4 v203, v[8:11], s[98:99] offset:16
	s_branch .Lfs_predone
.Lfs_np1:
	s_add_u32 s42, s62, 0x0
	s_addc_u32 s43, s63, 0
	global_load_dwordx4 v[128:131], v205, s[42:43] sc0 sc1
	s_add_u32 s98, s62, 0x1000
	s_addc_u32 s99, s63, 0
	global_load_dwordx4 v[132:135], v205, s[98:99] sc0 sc1
	s_add_u32 s42, s62, 0x400
	s_addc_u32 s43, s63, 0
	global_load_dwordx4 v[136:139], v205, s[42:43] sc0 sc1
	s_add_u32 s98, s62, 0x1400
	s_addc_u32 s99, s63, 0
	global_load_dwordx4 v[140:143], v205, s[98:99] sc0 sc1
	s_add_u32 s42, s62, 0x800
	s_addc_u32 s43, s63, 0
	global_load_dwordx4 v[144:147], v205, s[42:43] sc0 sc1
	s_add_u32 s98, s62, 0x1800
	s_addc_u32 s99, s63, 0
	global_load_dwordx4 v[148:151], v205, s[98:99] sc0 sc1
	s_add_u32 s42, s62, 0xc00
	s_addc_u32 s43, s63, 0
	global_load_dwordx4 v[152:155], v205, s[42:43] sc0 sc1
	s_add_u32 s98, s62, 0x1c00
	s_addc_u32 s99, s63, 0
	global_load_dwordx4 v[156:159], v205, s[98:99] sc0 sc1
	s_add_u32 s42, s62, 0x2000
	s_addc_u32 s43, s63, 0
	global_load_dwordx4 v[160:163], v205, s[42:43] sc0 sc1
	s_add_u32 s98, s62, 0x3000
	s_addc_u32 s99, s63, 0
	global_load_dwordx4 v[164:167], v205, s[98:99] sc0 sc1
	s_add_u32 s42, s62, 0x2400
	s_addc_u32 s43, s63, 0
	global_load_dwordx4 v[168:171], v205, s[42:43] sc0 sc1
	s_add_u32 s98, s62, 0x3400
	s_addc_u32 s99, s63, 0
	global_load_dwordx4 v[172:175], v205, s[98:99] sc0 sc1
	s_add_u32 s42, s62, 0x2800
	s_addc_u32 s43, s63, 0
	global_load_dwordx4 v[176:179], v205, s[42:43] sc0 sc1
	s_add_u32 s98, s62, 0x3800
	s_addc_u32 s99, s63, 0
	global_load_dwordx4 v[180:183], v205, s[98:99] sc0 sc1
	s_add_u32 s42, s62, 0x2c00
	s_addc_u32 s43, s63, 0
	global_load_dwordx4 v[206:209], v205, s[42:43] sc0 sc1
	s_add_u32 s98, s62, 0x3c00
	s_addc_u32 s99, s63, 0
	global_load_dwordx4 v[210:213], v205, s[98:99] sc0 sc1
	s_add_u32 s42, s14, 0x0
	s_addc_u32 s43, s15, 0
	global_load_dwordx4 v[236:239], v235, s[42:43]
	s_waitcnt vmcnt(16)
	v_lshlrev_b32_e32 v240, 16, v128
	v_and_b32_e32 v241, 0xffff0000, v128
	v_pk_add_f32 v[124:125], v[124:125], v[240:241]
	v_lshlrev_b32_e32 v240, 16, v129
	v_and_b32_e32 v241, 0xffff0000, v129
	v_pk_add_f32 v[126:127], v[126:127], v[240:241]
	v_lshlrev_b32_e32 v240, 16, v130
	v_and_b32_e32 v241, 0xffff0000, v130
	v_pk_add_f32 v[120:121], v[120:121], v[240:241]
	v_lshlrev_b32_e32 v240, 16, v131
	v_and_b32_e32 v241, 0xffff0000, v131
	v_pk_add_f32 v[122:123], v[122:123], v[240:241]
	s_add_u32 s98, s10, 0x0
	s_addc_u32 s99, s11, 0
	global_load_dwordx4 v[128:131], v203, s[98:99]
	s_waitcnt vmcnt(16)
	v_lshlrev_b32_e32 v240, 16, v132
	v_and_b32_e32 v241, 0xffff0000, v132
	v_pk_add_f32 v[92:93], v[92:93], v[240:241]
	v_lshlrev_b32_e32 v240, 16, v133
	v_and_b32_e32 v241, 0xffff0000, v133
	v_pk_add_f32 v[94:95], v[94:95], v[240:241]
	v_lshlrev_b32_e32 v240, 16, v134
	v_and_b32_e32 v241, 0xffff0000, v134
	v_pk_add_f32 v[88:89], v[88:89], v[240:241]
	v_lshlrev_b32_e32 v240, 16, v135
	v_and_b32_e32 v241, 0xffff0000, v135
	v_pk_add_f32 v[90:91], v[90:91], v[240:241]
	s_add_u32 s42, s14, 0x0
	s_addc_u32 s43, s15, 0
	global_load_dwordx4 v[132:135], v235, s[42:43] offset:16
	s_waitcnt vmcnt(16)
	v_lshlrev_b32_e32 v240, 16, v136
	v_and_b32_e32 v241, 0xffff0000, v136
	v_pk_add_f32 v[116:117], v[116:117], v[240:241]
	v_lshlrev_b32_e32 v240, 16, v137
	v_and_b32_e32 v241, 0xffff0000, v137
	v_pk_add_f32 v[118:119], v[118:119], v[240:241]
	v_lshlrev_b32_e32 v240, 16, v138
	v_and_b32_e32 v241, 0xffff0000, v138
	v_pk_add_f32 v[112:113], v[112:113], v[240:241]
	v_lshlrev_b32_e32 v240, 16, v139
	v_and_b32_e32 v241, 0xffff0000, v139
	v_pk_add_f32 v[114:115], v[114:115], v[240:241]
	s_add_u32 s98, s10, 0x0
	s_addc_u32 s99, s11, 0
	global_load_dwordx4 v[136:139], v203, s[98:99] offset:16
	s_waitcnt vmcnt(16)
	v_lshlrev_b32_e32 v240, 16, v140
	v_and_b32_e32 v241, 0xffff0000, v140
	v_pk_add_f32 v[84:85], v[84:85], v[240:241]
	v_lshlrev_b32_e32 v240, 16, v141
	v_and_b32_e32 v241, 0xffff0000, v141
	v_pk_add_f32 v[86:87], v[86:87], v[240:241]
	v_lshlrev_b32_e32 v240, 16, v142
	v_and_b32_e32 v241, 0xffff0000, v142
	v_pk_add_f32 v[80:81], v[80:81], v[240:241]
	v_lshlrev_b32_e32 v240, 16, v143
	v_and_b32_e32 v241, 0xffff0000, v143
	v_pk_add_f32 v[82:83], v[82:83], v[240:241]
	s_add_u32 s42, s14, 0x200
	s_addc_u32 s43, s15, 0
	global_load_dwordx4 v[140:143], v235, s[42:43]
	s_waitcnt vmcnt(16)
	v_lshlrev_b32_e32 v240, 16, v144
	v_and_b32_e32 v241, 0xffff0000, v144
	v_pk_add_f32 v[108:109], v[108:109], v[240:241]
	v_lshlrev_b32_e32 v240, 16, v145
	v_and_b32_e32 v241, 0xffff0000, v145
	v_pk_add_f32 v[110:111], v[110:111], v[240:241]
	v_lshlrev_b32_e32 v240, 16, v146
	v_and_b32_e32 v241, 0xffff0000, v146
	v_pk_add_f32 v[104:105], v[104:105], v[240:241]
	v_lshlrev_b32_e32 v240, 16, v147
	v_and_b32_e32 v241, 0xffff0000, v147
	v_pk_add_f32 v[106:107], v[106:107], v[240:241]
	s_add_u32 s98, s10, 0x200
	s_addc_u32 s99, s11, 0
	global_load_dwordx4 v[144:147], v203, s[98:99]
	s_waitcnt vmcnt(16)
	v_lshlrev_b32_e32 v240, 16, v148
	v_and_b32_e32 v241, 0xffff0000, v148
	v_pk_add_f32 v[76:77], v[76:77], v[240:241]
	v_lshlrev_b32_e32 v240, 16, v149
	v_and_b32_e32 v241, 0xffff0000, v149
	v_pk_add_f32 v[78:79], v[78:79], v[240:241]
	v_lshlrev_b32_e32 v240, 16, v150
	v_and_b32_e32 v241, 0xffff0000, v150
	v_pk_add_f32 v[72:73], v[72:73], v[240:241]
	v_lshlrev_b32_e32 v240, 16, v151
	v_and_b32_e32 v241, 0xffff0000, v151
	v_pk_add_f32 v[74:75], v[74:75], v[240:241]
	s_add_u32 s42, s14, 0x200
	s_addc_u32 s43, s15, 0
	global_load_dwordx4 v[148:151], v235, s[42:43] offset:16
	s_waitcnt vmcnt(16)
	v_lshlrev_b32_e32 v240, 16, v152
	v_and_b32_e32 v241, 0xffff0000, v152
	v_pk_add_f32 v[100:101], v[100:101], v[240:241]
	v_lshlrev_b32_e32 v240, 16, v153
	v_and_b32_e32 v241, 0xffff0000, v153
	v_pk_add_f32 v[102:103], v[102:103], v[240:241]
	v_lshlrev_b32_e32 v240, 16, v154
	v_and_b32_e32 v241, 0xffff0000, v154
	v_pk_add_f32 v[96:97], v[96:97], v[240:241]
	v_lshlrev_b32_e32 v240, 16, v155
	v_and_b32_e32 v241, 0xffff0000, v155
	v_pk_add_f32 v[98:99], v[98:99], v[240:241]
	s_add_u32 s98, s10, 0x200
	s_addc_u32 s99, s11, 0
	global_load_dwordx4 v[152:155], v203, s[98:99] offset:16
	s_waitcnt vmcnt(16)
	v_lshlrev_b32_e32 v240, 16, v156
	v_and_b32_e32 v241, 0xffff0000, v156
	v_pk_add_f32 v[68:69], v[68:69], v[240:241]
	v_lshlrev_b32_e32 v240, 16, v157
	v_and_b32_e32 v241, 0xffff0000, v157
	v_pk_add_f32 v[70:71], v[70:71], v[240:241]
	v_lshlrev_b32_e32 v240, 16, v158
	v_and_b32_e32 v241, 0xffff0000, v158
	v_pk_add_f32 v[64:65], v[64:65], v[240:241]
	v_lshlrev_b32_e32 v240, 16, v159
	v_and_b32_e32 v241, 0xffff0000, v159
	v_pk_add_f32 v[66:67], v[66:67], v[240:241]
	s_add_u32 s42, s14, 0x18000
	s_addc_u32 s43, s15, 0
	global_load_dwordx4 v[156:159], v235, s[42:43]
	s_waitcnt vmcnt(16)
	v_lshlrev_b32_e32 v240, 16, v160
	v_and_b32_e32 v241, 0xffff0000, v160
	v_pk_add_f32 v[60:61], v[60:61], v[240:241]
	v_lshlrev_b32_e32 v240, 16, v161
	v_and_b32_e32 v241, 0xffff0000, v161
	v_pk_add_f32 v[62:63], v[62:63], v[240:241]
	v_lshlrev_b32_e32 v240, 16, v162
	v_and_b32_e32 v241, 0xffff0000, v162
	v_pk_add_f32 v[56:57], v[56:57], v[240:241]
	v_lshlrev_b32_e32 v240, 16, v163
	v_and_b32_e32 v241, 0xffff0000, v163
	v_pk_add_f32 v[58:59], v[58:59], v[240:241]
	s_add_u32 s98, s10, 0x10000
	s_addc_u32 s99, s11, 0
	global_load_dwordx4 v[160:163], v203, s[98:99]
	s_waitcnt vmcnt(16)
	v_lshlrev_b32_e32 v240, 16, v164
	v_and_b32_e32 v241, 0xffff0000, v164
	v_pk_add_f32 v[28:29], v[28:29], v[240:241]
	v_lshlrev_b32_e32 v240, 16, v165
	v_and_b32_e32 v241, 0xffff0000, v165
	v_pk_add_f32 v[30:31], v[30:31], v[240:241]
	v_lshlrev_b32_e32 v240, 16, v166
	v_and_b32_e32 v241, 0xffff0000, v166
	v_pk_add_f32 v[24:25], v[24:25], v[240:241]
	v_lshlrev_b32_e32 v240, 16, v167
	v_and_b32_e32 v241, 0xffff0000, v167
	v_pk_add_f32 v[26:27], v[26:27], v[240:241]
	s_add_u32 s42, s14, 0x18000
	s_addc_u32 s43, s15, 0
	global_load_dwordx4 v[164:167], v235, s[42:43] offset:16
	s_waitcnt vmcnt(16)
	v_lshlrev_b32_e32 v240, 16, v168
	v_and_b32_e32 v241, 0xffff0000, v168
	v_pk_add_f32 v[52:53], v[52:53], v[240:241]
	v_lshlrev_b32_e32 v240, 16, v169
	v_and_b32_e32 v241, 0xffff0000, v169
	v_pk_add_f32 v[54:55], v[54:55], v[240:241]
	v_lshlrev_b32_e32 v240, 16, v170
	v_and_b32_e32 v241, 0xffff0000, v170
	v_pk_add_f32 v[48:49], v[48:49], v[240:241]
	v_lshlrev_b32_e32 v240, 16, v171
	v_and_b32_e32 v241, 0xffff0000, v171
	v_pk_add_f32 v[50:51], v[50:51], v[240:241]
	s_add_u32 s98, s10, 0x10000
	s_addc_u32 s99, s11, 0
	global_load_dwordx4 v[168:171], v203, s[98:99] offset:16
	s_waitcnt vmcnt(16)
	v_lshlrev_b32_e32 v240, 16, v172
	v_and_b32_e32 v241, 0xffff0000, v172
	v_pk_add_f32 v[20:21], v[20:21], v[240:241]
	v_lshlrev_b32_e32 v240, 16, v173
	v_and_b32_e32 v241, 0xffff0000, v173
	v_pk_add_f32 v[22:23], v[22:23], v[240:241]
	v_lshlrev_b32_e32 v240, 16, v174
	v_and_b32_e32 v241, 0xffff0000, v174
	v_pk_add_f32 v[16:17], v[16:17], v[240:241]
	v_lshlrev_b32_e32 v240, 16, v175
	v_and_b32_e32 v241, 0xffff0000, v175
	v_pk_add_f32 v[18:19], v[18:19], v[240:241]
	s_add_u32 s42, s14, 0x18200
	s_addc_u32 s43, s15, 0
	global_load_dwordx4 v[172:175], v235, s[42:43]
	s_waitcnt vmcnt(16)
	v_lshlrev_b32_e32 v240, 16, v176
	v_and_b32_e32 v241, 0xffff0000, v176
	v_pk_add_f32 v[44:45], v[44:45], v[240:241]
	v_lshlrev_b32_e32 v240, 16, v177
	v_and_b32_e32 v241, 0xffff0000, v177
	v_pk_add_f32 v[46:47], v[46:47], v[240:241]
	v_lshlrev_b32_e32 v240, 16, v178
	v_and_b32_e32 v241, 0xffff0000, v178
	v_pk_add_f32 v[40:41], v[40:41], v[240:241]
	v_lshlrev_b32_e32 v240, 16, v179
	v_and_b32_e32 v241, 0xffff0000, v179
	v_pk_add_f32 v[42:43], v[42:43], v[240:241]
	s_add_u32 s98, s10, 0x10200
	s_addc_u32 s99, s11, 0
	global_load_dwordx4 v[176:179], v203, s[98:99]
	s_waitcnt vmcnt(16)
	v_lshlrev_b32_e32 v240, 16, v180
	v_and_b32_e32 v241, 0xffff0000, v180
	v_pk_add_f32 v[12:13], v[12:13], v[240:241]
	v_lshlrev_b32_e32 v240, 16, v181
	v_and_b32_e32 v241, 0xffff0000, v181
	v_pk_add_f32 v[14:15], v[14:15], v[240:241]
	v_lshlrev_b32_e32 v240, 16, v182
	v_and_b32_e32 v241, 0xffff0000, v182
	v_pk_add_f32 v[8:9], v[8:9], v[240:241]
	v_lshlrev_b32_e32 v240, 16, v183
	v_and_b32_e32 v241, 0xffff0000, v183
	v_pk_add_f32 v[10:11], v[10:11], v[240:241]
	s_add_u32 s42, s14, 0x18200
	s_addc_u32 s43, s15, 0
	global_load_dwordx4 v[180:183], v235, s[42:43] offset:16
	s_waitcnt vmcnt(16)
	v_lshlrev_b32_e32 v240, 16, v206
	v_and_b32_e32 v241, 0xffff0000, v206
	v_pk_add_f32 v[36:37], v[36:37], v[240:241]
	v_lshlrev_b32_e32 v240, 16, v207
	v_and_b32_e32 v241, 0xffff0000, v207
	v_pk_add_f32 v[38:39], v[38:39], v[240:241]
	v_lshlrev_b32_e32 v240, 16, v208
	v_and_b32_e32 v241, 0xffff0000, v208
	v_pk_add_f32 v[32:33], v[32:33], v[240:241]
	v_lshlrev_b32_e32 v240, 16, v209
	v_and_b32_e32 v241, 0xffff0000, v209
	v_pk_add_f32 v[34:35], v[34:35], v[240:241]
	s_add_u32 s98, s10, 0x10200
	s_addc_u32 s99, s11, 0
	global_load_dwordx4 v[206:209], v203, s[98:99] offset:16
	s_waitcnt vmcnt(16)
	v_lshlrev_b32_e32 v240, 16, v210
	v_and_b32_e32 v241, 0xffff0000, v210
	v_pk_add_f32 v[4:5], v[4:5], v[240:241]
	v_lshlrev_b32_e32 v240, 16, v211
	v_and_b32_e32 v241, 0xffff0000, v211
	v_pk_add_f32 v[6:7], v[6:7], v[240:241]
	v_lshlrev_b32_e32 v240, 16, v212
	v_and_b32_e32 v241, 0xffff0000, v212
	v_pk_add_f32 v[0:1], v[0:1], v[240:241]
	v_lshlrev_b32_e32 v240, 16, v213
	v_and_b32_e32 v241, 0xffff0000, v213
	v_pk_add_f32 v[2:3], v[2:3], v[240:241]
	s_add_u32 s42, s14, 0x30000
	s_addc_u32 s43, s15, 0
	global_load_dwordx4 v[210:213], v235, s[42:43]
	s_waitcnt vmcnt(15)
	v_pk_fma_f32 v[124:125], v[236:237], v[124:125], v[128:129]
	v_pk_fma_f32 v[126:127], v[238:239], v[126:127], v[130:131]
	s_add_u32 s98, s10, 0x0
	s_addc_u32 s99, s11, 0
	global_store_dwordx4 v203, v[124:127], s[98:99]
	s_add_u32 s42, s10, 0x20000
	s_addc_u32 s43, s11, 0
	global_load_dwordx4 v[236:239], v203, s[42:43]
	s_add_u32 s98, s14, 0x30000
	s_addc_u32 s99, s15, 0
	global_load_dwordx4 v[128:131], v235, s[98:99] offset:16
	s_waitcnt vmcnt(16)
	v_pk_fma_f32 v[120:121], v[132:133], v[120:121], v[136:137]
	v_pk_fma_f32 v[122:123], v[134:135], v[122:123], v[138:139]
	s_add_u32 s42, s10, 0x0
	s_addc_u32 s43, s11, 0
	global_store_dwordx4 v203, v[120:123], s[42:43] offset:16
	s_add_u32 s98, s10, 0x20000
	s_addc_u32 s99, s11, 0
	global_load_dwordx4 v[132:135], v203, s[98:99] offset:16
	s_add_u32 s42, s14, 0x30200
	s_addc_u32 s43, s15, 0
	global_load_dwordx4 v[136:139], v235, s[42:43]
	s_waitcnt vmcnt(17)
	v_pk_fma_f32 v[92:93], v[140:141], v[92:93], v[144:145]
	v_pk_fma_f32 v[94:95], v[142:143], v[94:95], v[146:147]
	s_add_u32 s98, s10, 0x200
	s_addc_u32 s99, s11, 0
	global_store_dwordx4 v203, v[92:95], s[98:99]
	s_add_u32 s42, s10, 0x20200
	s_addc_u32 s43, s11, 0
	global_load_dwordx4 v[140:143], v203, s[42:43]
	s_add_u32 s98, s14, 0x30200
	s_addc_u32 s99, s15, 0
	global_load_dwordx4 v[144:147], v235, s[98:99] offset:16
	s_waitcnt vmcnt(18)
	v_pk_fma_f32 v[88:89], v[148:149], v[88:89], v[152:153]
	v_pk_fma_f32 v[90:91], v[150:151], v[90:91], v[154:155]
	s_add_u32 s42, s10, 0x200
	s_addc_u32 s43, s11, 0
	global_store_dwordx4 v203, v[88:91], s[42:43] offset:16
	s_add_u32 s98, s10, 0x20200
	s_addc_u32 s99, s11, 0
	global_load_dwordx4 v[148:151], v203, s[98:99] offset:16
	s_add_u32 s42, s14, 0x48000
	s_addc_u32 s43, s15, 0
	global_load_dwordx4 v[152:155], v235, s[42:43]
	s_waitcnt vmcnt(19)
	v_pk_fma_f32 v[116:117], v[156:157], v[116:117], v[160:161]
	v_pk_fma_f32 v[118:119], v[158:159], v[118:119], v[162:163]
	s_add_u32 s98, s10, 0x10000
	s_addc_u32 s99, s11, 0
	global_store_dwordx4 v203, v[116:119], s[98:99]
	s_add_u32 s42, s10, 0x30000
	s_addc_u32 s43, s11, 0
	global_load_dwordx4 v[156:159], v203, s[42:43]
	s_add_u32 s98, s14, 0x48000
	s_addc_u32 s99, s15, 0
	global_load_dwordx4 v[160:163], v235, s[98:99] offset:16
	s_waitcnt vmcnt(20)
	v_pk_fma_f32 v[112:113], v[164:165], v[112:113], v[168:169]
	v_pk_fma_f32 v[114:115], v[166:167], v[114:115], v[170:171]
	s_add_u32 s42, s10, 0x10000
	s_addc_u32 s43, s11, 0
	global_store_dwordx4 v203, v[112:115], s[42:43] offset:16
	s_add_u32 s98, s10, 0x30000
	s_addc_u32 s99, s11, 0
	global_load_dwordx4 v[164:167], v203, s[98:99] offset:16
	s_add_u32 s42, s14, 0x48200
	s_addc_u32 s43, s15, 0
	global_load_dwordx4 v[168:171], v235, s[42:43]
	s_waitcnt vmcnt(21)
	v_pk_fma_f32 v[84:85], v[172:173], v[84:85], v[176:177]
	v_pk_fma_f32 v[86:87], v[174:175], v[86:87], v[178:179]
	s_add_u32 s98, s10, 0x10200
	s_addc_u32 s99, s11, 0
	global_store_dwordx4 v203, v[84:87], s[98:99]
	s_add_u32 s42, s10, 0x30200
	s_addc_u32 s43, s11, 0
	global_load_dwordx4 v[172:175], v203, s[42:43]
	s_add_u32 s98, s14, 0x48200
	s_addc_u32 s99, s15, 0
	global_load_dwordx4 v[176:179], v235, s[98:99] offset:16
	s_waitcnt vmcnt(22)
	v_pk_fma_f32 v[80:81], v[180:181], v[80:81], v[206:207]
	v_pk_fma_f32 v[82:83], v[182:183], v[82:83], v[208:209]
	s_add_u32 s42, s10, 0x10200
	s_addc_u32 s43, s11, 0
	global_store_dwordx4 v203, v[80:83], s[42:43] offset:16
	s_add_u32 s98, s10, 0x30200
	s_addc_u32 s99, s11, 0
	global_load_dwordx4 v[180:183], v203, s[98:99] offset:16
	s_add_u32 s42, s14, 0xc0000
	s_addc_u32 s43, s15, 0
	global_load_dwordx4 v[206:209], v235, s[42:43]
	s_waitcnt vmcnt(22)
	v_pk_fma_f32 v[108:109], v[210:211], v[108:109], v[236:237]
	v_pk_fma_f32 v[110:111], v[212:213], v[110:111], v[238:239]
	s_add_u32 s98, s10, 0x20000
	s_addc_u32 s99, s11, 0
	global_store_dwordx4 v203, v[108:111], s[98:99]
	s_add_u32 s42, s10, 0x80000
	s_addc_u32 s43, s11, 0
	global_load_dwordx4 v[210:213], v203, s[42:43]
	s_add_u32 s98, s14, 0xc0000
	s_addc_u32 s99, s15, 0
	global_load_dwordx4 v[236:239], v235, s[98:99] offset:16
	s_waitcnt vmcnt(22)
	v_pk_fma_f32 v[104:105], v[128:129], v[104:105], v[132:133]
	v_pk_fma_f32 v[106:107], v[130:131], v[106:107], v[134:135]
	s_add_u32 s42, s10, 0x20000
	s_addc_u32 s43, s11, 0
	global_store_dwordx4 v203, v[104:107], s[42:43] offset:16
	s_add_u32 s98, s10, 0x80000
	s_addc_u32 s99, s11, 0
	global_load_dwordx4 v[128:131], v203, s[98:99] offset:16
	s_add_u32 s42, s14, 0xc0200
	s_addc_u32 s43, s15, 0
	global_load_dwordx4 v[132:135], v235, s[42:43]
	s_waitcnt vmcnt(22)
	v_pk_fma_f32 v[76:77], v[136:137], v[76:77], v[140:141]
	v_pk_fma_f32 v[78:79], v[138:139], v[78:79], v[142:143]
	s_add_u32 s98, s10, 0x20200
	s_addc_u32 s99, s11, 0
	global_store_dwordx4 v203, v[76:79], s[98:99]
	s_add_u32 s42, s10, 0x80200
	s_addc_u32 s43, s11, 0
	global_load_dwordx4 v[136:139], v203, s[42:43]
	s_add_u32 s98, s14, 0xc0200
	s_addc_u32 s99, s15, 0
	global_load_dwordx4 v[140:143], v235, s[98:99] offset:16
	s_waitcnt vmcnt(22)
	v_pk_fma_f32 v[72:73], v[144:145], v[72:73], v[148:149]
	v_pk_fma_f32 v[74:75], v[146:147], v[74:75], v[150:151]
	s_add_u32 s42, s10, 0x20200
	s_addc_u32 s43, s11, 0
	global_store_dwordx4 v203, v[72:75], s[42:43] offset:16
	s_add_u32 s98, s10, 0x80200
	s_addc_u32 s99, s11, 0
	global_load_dwordx4 v[144:147], v203, s[98:99] offset:16
	s_add_u32 s42, s14, 0xd8000
	s_addc_u32 s43, s15, 0
	global_load_dwordx4 v[148:151], v235, s[42:43]
	s_waitcnt vmcnt(22)
	v_pk_fma_f32 v[100:101], v[152:153], v[100:101], v[156:157]
	v_pk_fma_f32 v[102:103], v[154:155], v[102:103], v[158:159]
	s_add_u32 s98, s10, 0x30000
	s_addc_u32 s99, s11, 0
	global_store_dwordx4 v203, v[100:103], s[98:99]
	s_add_u32 s42, s10, 0x90000
	s_addc_u32 s43, s11, 0
	global_load_dwordx4 v[152:155], v203, s[42:43]
	s_add_u32 s98, s14, 0xd8000
	s_addc_u32 s99, s15, 0
	global_load_dwordx4 v[156:159], v235, s[98:99] offset:16
	s_waitcnt vmcnt(22)
	v_pk_fma_f32 v[96:97], v[160:161], v[96:97], v[164:165]
	v_pk_fma_f32 v[98:99], v[162:163], v[98:99], v[166:167]
	s_add_u32 s42, s10, 0x30000
	s_addc_u32 s43, s11, 0
	global_store_dwordx4 v203, v[96:99], s[42:43] offset:16
	s_add_u32 s98, s10, 0x90000
	s_addc_u32 s99, s11, 0
	global_load_dwordx4 v[160:163], v203, s[98:99] offset:16
	s_add_u32 s42, s14, 0xd8200
	s_addc_u32 s43, s15, 0
	global_load_dwordx4 v[164:167], v235, s[42:43]
	s_waitcnt vmcnt(22)
	v_pk_fma_f32 v[68:69], v[168:169], v[68:69], v[172:173]
	v_pk_fma_f32 v[70:71], v[170:171], v[70:71], v[174:175]
	s_add_u32 s98, s10, 0x30200
	s_addc_u32 s99, s11, 0
	global_store_dwordx4 v203, v[68:71], s[98:99]
	s_add_u32 s42, s10, 0x90200
	s_addc_u32 s43, s11, 0
	global_load_dwordx4 v[168:171], v203, s[42:43]
	s_add_u32 s98, s14, 0xd8200
	s_addc_u32 s99, s15, 0
	global_load_dwordx4 v[172:175], v235, s[98:99] offset:16
	s_waitcnt vmcnt(22)
	v_pk_fma_f32 v[64:65], v[176:177], v[64:65], v[180:181]
	v_pk_fma_f32 v[66:67], v[178:179], v[66:67], v[182:183]
	s_add_u32 s42, s10, 0x30200
	s_addc_u32 s43, s11, 0
	global_store_dwordx4 v203, v[64:67], s[42:43] offset:16
	s_add_u32 s98, s10, 0x90200
	s_addc_u32 s99, s11, 0
	global_load_dwordx4 v[176:179], v203, s[98:99] offset:16
	s_add_u32 s42, s14, 0xf0000
	s_addc_u32 s43, s15, 0
	global_load_dwordx4 v[180:183], v235, s[42:43]
	s_waitcnt vmcnt(22)
	v_pk_fma_f32 v[60:61], v[206:207], v[60:61], v[210:211]
	v_pk_fma_f32 v[62:63], v[208:209], v[62:63], v[212:213]
	s_add_u32 s98, s10, 0x80000
	s_addc_u32 s99, s11, 0
	global_store_dwordx4 v203, v[60:63], s[98:99]
	s_add_u32 s42, s10, 0xa0000
	s_addc_u32 s43, s11, 0
	global_load_dwordx4 v[206:209], v203, s[42:43]
	s_add_u32 s98, s14, 0xf0000
	s_addc_u32 s99, s15, 0
	global_load_dwordx4 v[210:213], v235, s[98:99] offset:16
	s_waitcnt vmcnt(22)
	v_pk_fma_f32 v[56:57], v[236:237], v[56:57], v[128:129]
	v_pk_fma_f32 v[58:59], v[238:239], v[58:59], v[130:131]
	s_add_u32 s42, s10, 0x80000
	s_addc_u32 s43, s11, 0
	global_store_dwordx4 v203, v[56:59], s[42:43] offset:16
	s_add_u32 s98, s10, 0xa0000
	s_addc_u32 s99, s11, 0
	global_load_dwordx4 v[236:239], v203, s[98:99] offset:16
	s_add_u32 s42, s14, 0xf0200
	s_addc_u32 s43, s15, 0
	global_load_dwordx4 v[128:131], v235, s[42:43]
	s_waitcnt vmcnt(22)
	v_pk_fma_f32 v[28:29], v[132:133], v[28:29], v[136:137]
	v_pk_fma_f32 v[30:31], v[134:135], v[30:31], v[138:139]
	s_add_u32 s98, s10, 0x80200
	s_addc_u32 s99, s11, 0
	global_store_dwordx4 v203, v[28:31], s[98:99]
	s_add_u32 s42, s10, 0xa0200
	s_addc_u32 s43, s11, 0
	global_load_dwordx4 v[132:135], v203, s[42:43]
	s_add_u32 s98, s14, 0xf0200
	s_addc_u32 s99, s15, 0
	global_load_dwordx4 v[136:139], v235, s[98:99] offset:16
	s_waitcnt vmcnt(22)
	v_pk_fma_f32 v[24:25], v[140:141], v[24:25], v[144:145]
	v_pk_fma_f32 v[26:27], v[142:143], v[26:27], v[146:147]
	s_add_u32 s42, s10, 0x80200
	s_addc_u32 s43, s11, 0
	global_store_dwordx4 v203, v[24:27], s[42:43] offset:16
	s_add_u32 s98, s10, 0xa0200
	s_addc_u32 s99, s11, 0
	global_load_dwordx4 v[140:143], v203, s[98:99] offset:16
	s_waitcnt vmcnt(21)
	v_pk_fma_f32 v[52:53], v[148:149], v[52:53], v[152:153]
	v_pk_fma_f32 v[54:55], v[150:151], v[54:55], v[154:155]
	s_add_u32 s42, s10, 0x90000
	s_addc_u32 s43, s11, 0
	global_store_dwordx4 v203, v[52:55], s[42:43]
	s_waitcnt vmcnt(19)
	v_pk_fma_f32 v[48:49], v[156:157], v[48:49], v[160:161]
	v_pk_fma_f32 v[50:51], v[158:159], v[50:51], v[162:163]
	s_add_u32 s98, s10, 0x90000
	s_addc_u32 s99, s11, 0
	global_store_dwordx4 v203, v[48:51], s[98:99] offset:16
	s_waitcnt vmcnt(17)
	v_pk_fma_f32 v[20:21], v[164:165], v[20:21], v[168:169]
	v_pk_fma_f32 v[22:23], v[166:167], v[22:23], v[170:171]
	s_add_u32 s42, s10, 0x90200
	s_addc_u32 s43, s11, 0
	global_store_dwordx4 v203, v[20:23], s[42:43]
	s_waitcnt vmcnt(15)
	v_pk_fma_f32 v[16:17], v[172:173], v[16:17], v[176:177]
	v_pk_fma_f32 v[18:19], v[174:175], v[18:19], v[178:179]
	s_add_u32 s98, s10, 0x90200
	s_addc_u32 s99, s11, 0
	global_store_dwordx4 v203, v[16:19], s[98:99] offset:16
	s_waitcnt vmcnt(13)
	v_pk_fma_f32 v[44:45], v[180:181], v[44:45], v[206:207]
	v_pk_fma_f32 v[46:47], v[182:183], v[46:47], v[208:209]
	s_add_u32 s42, s10, 0xa0000
	s_addc_u32 s43, s11, 0
	global_store_dwordx4 v203, v[44:47], s[42:43]
	s_waitcnt vmcnt(11)
	v_pk_fma_f32 v[40:41], v[210:211], v[40:41], v[236:237]
	v_pk_fma_f32 v[42:43], v[212:213], v[42:43], v[238:239]
	s_add_u32 s98, s10, 0xa0000
	s_addc_u32 s99, s11, 0
	global_store_dwordx4 v203, v[40:43], s[98:99] offset:16
	s_waitcnt vmcnt(9)
	v_pk_fma_f32 v[12:13], v[128:129], v[12:13], v[132:133]
	v_pk_fma_f32 v[14:15], v[130:131], v[14:15], v[134:135]
	s_add_u32 s42, s10, 0xa0200
	s_addc_u32 s43, s11, 0
	global_store_dwordx4 v203, v[12:15], s[42:43]
	s_waitcnt vmcnt(7)
	v_pk_fma_f32 v[8:9], v[136:137], v[8:9], v[140:141]
	v_pk_fma_f32 v[10:11], v[138:139], v[10:11], v[142:143]
	s_add_u32 s98, s10, 0xa0200
	s_addc_u32 s99, s11, 0
	global_store_dwordx4 v203, v[8:11], s[98:99] offset:16
.Lfs_predone:
	s_mov_b32 s34, 0
	s_andn2_b64 vcc, exec, s[84:85]
	s_cbranch_vccnz .Lfs_LBB0_1423
	s_waitcnt vmcnt(0)
	v_add_u32_e32 v145, 0xffffc000, v204
	v_lshrrev_b32_e32 v145, 3, v145
	v_cmp_gt_i32_e32 vcc, s90, v204
	v_ashrrev_i32_e32 v144, 11, v204
	v_add_u32_e32 v145, 8, v145
	v_cndmask_b32_e32 v144, v145, v144, vcc
	v_mov_b64_e32 v[146:147], s[14:15]
	v_ashrrev_i32_e32 v145, 31, v144
	v_mad_i64_i32 v[146:147], s[36:37], v144, s38, v[146:147]
	v_lshlrev_b64 v[148:149], 2, v[200:201]
	v_lshl_add_u64 v[152:153], v[146:147], 0, v[148:149]
	v_lshl_add_u64 v[146:147], s[16:17], 0, v[148:149]
	v_lshlrev_b64 v[144:145], 12, v[144:145]
	v_lshl_add_u64 v[160:161], v[146:147], 0, v[144:145]
	global_load_dwordx4 v[144:147], v[152:153], off offset:16
	global_load_dwordx4 v[148:151], v[152:153], off
	s_and_b64 vcc, exec, s[80:81]
	s_cbranch_vccz .Lfs_LBB0_1582
	global_load_dwordx4 v[156:159], v[152:153], off offset:512
	s_nop 0
	global_load_dwordx4 v[152:155], v[152:153], off offset:528
	s_and_b64 vcc, exec, s[80:81]
	s_cbranch_vccz .Lfs_LBB0_1583
.Lfs_LBB0_1423:
	v_ashrrev_i32_e32 v205, 31, v204
	v_lshlrev_b64 v[160:161], 12, v[204:205]
	v_lshl_add_u64 v[176:177], s[10:11], 0, v[160:161]
	v_lshl_add_u64 v[178:179], v[200:201], 2, v[176:177]
	v_mov_b64_e32 v[164:165], v[120:121]
	v_mov_b64_e32 v[166:167], v[122:123]
	v_mov_b64_e32 v[160:161], v[124:125]
	v_mov_b64_e32 v[162:163], v[126:127]
	s_cmp_eq_u32 s34, 2
	v_mov_b64_e32 v[174:175], v[126:127]
	v_mov_b64_e32 v[170:171], v[122:123]
	s_cselect_b64 s[88:89], -1, 0
	s_cmp_lg_u32 s34, 2
	v_mov_b64_e32 v[172:173], v[124:125]
	v_mov_b64_e32 v[168:169], v[120:121]
	s_cbranch_scc1 .Lfs_LBB0_1428
	s_mov_b64 s[84:85], s[62:63]
	v_lshlrev_b32_e32 v180, 2, v194
	v_mov_b32_e32 v181, v185
	s_cmp_lt_i32 s30, 2
	v_lshl_add_u64 v[182:183], s[84:85], 0, v[180:181]
	flat_load_dwordx4 v[168:171], v[182:183]
	s_cbranch_scc1 .Lfs_Lskw_0
	v_add_co_u32_e32 v182, vcc, 0x20000, v182
	s_nop 1
	v_addc_co_u32_e32 v183, vcc, 0, v183, vcc
	flat_load_dwordx4 v[206:209], v[182:183]
	s_cmp_lt_i32 s30, 3
	s_cbranch_scc1 .Lfs_Lskw_0
	v_mov_b32_e32 v181, v185
	v_lshl_add_u64 v[180:181], s[84:85], 0, v[180:181]
	v_add_co_u32_e32 v180, vcc, 0x40000, v180
	s_nop 1
	v_addc_co_u32_e32 v181, vcc, 0, v181, vcc
	flat_load_dwordx4 v[180:183], v[180:181]

.Lfs_LBB0_1428:
	v_ashrrev_i32_e32 v203, 31, v202
	v_lshlrev_b64 v[206:207], 10, v[202:203]
	s_waitcnt vmcnt(0)
	s_and_b64 vcc, exec, s[80:81]
	s_cbranch_vccnz .Lfs_LBB0_1430
	v_lshl_add_u64 v[172:173], v[206:207], 1, s[18:19]
	v_mul_f32_e32 v174, v140, v160
	v_mul_f32_e32 v175, v141, v161
	v_cvt_pk_bf16_f32 v168, v174, v175
	v_mul_f32_e32 v178, v142, v162
	v_mul_f32_e32 v179, v143, v163
	v_cvt_pk_bf16_f32 v169, v178, v179
	v_lshl_add_u64 v[172:173], v[200:201], 1, v[172:173]
	v_mul_f32_e32 v180, v136, v164
	v_mul_f32_e32 v181, v137, v165
	v_cvt_pk_bf16_f32 v170, v180, v181
	v_mul_f32_e32 v182, v138, v166
	v_mul_f32_e32 v183, v139, v167
	v_cvt_pk_bf16_f32 v171, v182, v183
	global_store_dwordx4 v[172:173], v[168:171], off
	s_nop 1
	v_mov_b32_e32 v168, v185
	v_mov_b32_e32 v169, v185
	v_cvt_pk_fp8_f32 v168, v174, v175
	v_cvt_pk_fp8_f32 v169, v180, v181
	v_lshl_add_u64 v[170:171], s[70:71], 0, v[206:207]
	v_lshl_add_u64 v[170:171], v[170:171], 0, v[200:201]
	v_cvt_pk_fp8_f32 v168, v178, v179 op_sel:[0,0,1]
	v_cvt_pk_fp8_f32 v169, v182, v183 op_sel:[0,0,1]
	global_store_dwordx2 v[170:171], v[168:169], off

.Lfs_LBB0_1572:
	s_or_b64 exec, exec, s[80:81]
	s_mov_b64 s[80:81], 0
	s_branch .LBB0_1573
.Lfs_LBB0_1582:
	global_load_dwordx4 v[136:139], v[160:161], off offset:16
	global_load_dwordx4 v[140:143], v[160:161], off
	global_load_dwordx4 v[156:159], v[152:153], off offset:512
	s_nop 0
	global_load_dwordx4 v[152:155], v[152:153], off offset:528
	s_and_b64 vcc, exec, s[80:81]
	s_cbranch_vccnz .Lfs_LBB0_1423

.LBB0_1573:
	s_and_b64 vcc, exec, s[80:81]
	s_cbranch_vccz .LBB0_1575
	s_mov_b64 s[30:31], s[28:29]
	v_cvt_pk_bf16_f32 v124, v124, v125
	v_cvt_pk_bf16_f32 v125, v126, v127
	v_cvt_pk_bf16_f32 v126, v120, v121
	v_cvt_pk_bf16_f32 v127, v122, v123
	s_and_b64 vcc, exec, s[78:79]
	v_lshl_add_u64 v[120:121], s[30:31], 0, v[184:185]
	v_readlane_b32 s30, v242, 2
	v_readlane_b32 s31, v242, 3
	flat_store_dwordx4 v[120:121], v[124:127] sc0 sc1
	v_cvt_pk_bf16_f32 v116, v116, v117
	v_cvt_pk_bf16_f32 v117, v118, v119
	v_cvt_pk_bf16_f32 v118, v112, v113
	v_cvt_pk_bf16_f32 v119, v114, v115
	s_nop 0
	v_lshl_add_u64 v[112:113], s[30:31], 0, v[184:185]
	v_readlane_b32 s30, v242, 4
	v_readlane_b32 s31, v242, 5
	flat_store_dwordx4 v[112:113], v[116:119] sc0 sc1
	v_cvt_pk_bf16_f32 v108, v108, v109
	v_cvt_pk_bf16_f32 v109, v110, v111
	v_cvt_pk_bf16_f32 v110, v104, v105
	v_cvt_pk_bf16_f32 v111, v106, v107
	s_nop 0
	v_lshl_add_u64 v[104:105], s[30:31], 0, v[184:185]
	v_readlane_b32 s30, v242, 6
	v_readlane_b32 s31, v242, 7
	flat_store_dwordx4 v[104:105], v[108:111] sc0 sc1
	v_cvt_pk_bf16_f32 v100, v100, v101
	v_cvt_pk_bf16_f32 v101, v102, v103
	v_cvt_pk_bf16_f32 v102, v96, v97
	v_cvt_pk_bf16_f32 v103, v98, v99
	s_nop 0
	v_lshl_add_u64 v[96:97], s[30:31], 0, v[184:185]
	v_readlane_b32 s30, v242, 8
	v_readlane_b32 s31, v242, 9
	flat_store_dwordx4 v[96:97], v[100:103] sc0 sc1
	v_cvt_pk_bf16_f32 v92, v92, v93
	v_cvt_pk_bf16_f32 v93, v94, v95
	v_cvt_pk_bf16_f32 v94, v88, v89
	v_cvt_pk_bf16_f32 v95, v90, v91
	s_nop 0
	v_lshl_add_u64 v[88:89], s[30:31], 0, v[184:185]
	v_readlane_b32 s30, v242, 10
	v_readlane_b32 s31, v242, 11
	flat_store_dwordx4 v[88:89], v[92:95] sc0 sc1
	v_cvt_pk_bf16_f32 v84, v84, v85
	v_cvt_pk_bf16_f32 v85, v86, v87
	v_cvt_pk_bf16_f32 v86, v80, v81
	v_cvt_pk_bf16_f32 v87, v82, v83
	s_nop 0
	v_lshl_add_u64 v[80:81], s[30:31], 0, v[184:185]
	v_readlane_b32 s30, v242, 12
	v_readlane_b32 s31, v242, 13
	flat_store_dwordx4 v[80:81], v[84:87] sc0 sc1
	v_cvt_pk_bf16_f32 v76, v76, v77
	v_cvt_pk_bf16_f32 v77, v78, v79
	v_cvt_pk_bf16_f32 v78, v72, v73
	v_cvt_pk_bf16_f32 v79, v74, v75
	s_nop 0
	v_lshl_add_u64 v[72:73], s[30:31], 0, v[184:185]
	v_readlane_b32 s30, v242, 14
	v_readlane_b32 s31, v242, 15
	flat_store_dwordx4 v[72:73], v[76:79] sc0 sc1
	v_cvt_pk_bf16_f32 v68, v68, v69
	v_cvt_pk_bf16_f32 v69, v70, v71
	v_cvt_pk_bf16_f32 v70, v64, v65
	v_cvt_pk_bf16_f32 v71, v66, v67
	s_nop 0
	v_lshl_add_u64 v[64:65], s[30:31], 0, v[184:185]
	s_mov_b64 s[30:31], s[46:47]
	flat_store_dwordx4 v[64:65], v[68:71] sc0 sc1
	v_cvt_pk_bf16_f32 v60, v60, v61
	v_cvt_pk_bf16_f32 v61, v62, v63
	v_cvt_pk_bf16_f32 v62, v56, v57
	v_cvt_pk_bf16_f32 v63, v58, v59
	s_nop 0
	v_lshl_add_u64 v[56:57], s[30:31], 0, v[184:185]
	s_mov_b64 s[30:31], s[48:49]
	flat_store_dwordx4 v[56:57], v[60:63] sc0 sc1
	v_cvt_pk_bf16_f32 v52, v52, v53
	v_cvt_pk_bf16_f32 v53, v54, v55
	v_cvt_pk_bf16_f32 v54, v48, v49
	v_cvt_pk_bf16_f32 v55, v50, v51
	s_nop 0
	v_lshl_add_u64 v[48:49], s[30:31], 0, v[184:185]
	s_mov_b64 s[30:31], s[50:51]
	flat_store_dwordx4 v[48:49], v[52:55] sc0 sc1
	v_cvt_pk_bf16_f32 v44, v44, v45
	v_cvt_pk_bf16_f32 v45, v46, v47
	v_cvt_pk_bf16_f32 v46, v40, v41
	v_cvt_pk_bf16_f32 v47, v42, v43
	s_nop 0
	v_lshl_add_u64 v[40:41], s[30:31], 0, v[184:185]
	s_mov_b64 s[30:31], s[52:53]
	flat_store_dwordx4 v[40:41], v[44:47] sc0 sc1
	v_cvt_pk_bf16_f32 v36, v36, v37
	v_cvt_pk_bf16_f32 v37, v38, v39
	v_cvt_pk_bf16_f32 v38, v32, v33
	v_cvt_pk_bf16_f32 v39, v34, v35
	s_nop 0
	v_lshl_add_u64 v[32:33], s[30:31], 0, v[184:185]
	s_mov_b64 s[30:31], s[54:55]
	flat_store_dwordx4 v[32:33], v[36:39] sc0 sc1
	v_cvt_pk_bf16_f32 v28, v28, v29
	v_cvt_pk_bf16_f32 v29, v30, v31
	v_cvt_pk_bf16_f32 v30, v24, v25
	v_cvt_pk_bf16_f32 v31, v26, v27
	s_nop 0
	v_lshl_add_u64 v[24:25], s[30:31], 0, v[184:185]
	s_mov_b64 s[30:31], s[56:57]
	flat_store_dwordx4 v[24:25], v[28:31] sc0 sc1
	v_cvt_pk_bf16_f32 v20, v20, v21
	v_cvt_pk_bf16_f32 v21, v22, v23
	v_cvt_pk_bf16_f32 v22, v16, v17
	v_cvt_pk_bf16_f32 v23, v18, v19
	s_nop 0
	v_lshl_add_u64 v[16:17], s[30:31], 0, v[184:185]
	s_mov_b64 s[30:31], s[58:59]
	flat_store_dwordx4 v[16:17], v[20:23] sc0 sc1
	v_cvt_pk_bf16_f32 v12, v12, v13
	v_cvt_pk_bf16_f32 v13, v14, v15
	v_cvt_pk_bf16_f32 v14, v8, v9
	v_cvt_pk_bf16_f32 v15, v10, v11
	s_nop 0
	v_lshl_add_u64 v[8:9], s[30:31], 0, v[184:185]
	s_mov_b64 s[30:31], s[60:61]
	flat_store_dwordx4 v[8:9], v[12:15] sc0 sc1
	v_cvt_pk_bf16_f32 v4, v4, v5
	v_cvt_pk_bf16_f32 v5, v6, v7
	v_cvt_pk_bf16_f32 v6, v0, v1
	v_cvt_pk_bf16_f32 v7, v2, v3
	s_nop 0
	v_lshl_add_u64 v[0:1], s[30:31], 0, v[184:185]
	flat_store_dwordx4 v[0:1], v[4:7] sc0 sc1
	s_waitcnt vmcnt(0)
	s_barrier
	s_cbranch_vccz .LBB0_1578

.LBB0_1578:
	s_waitcnt vmcnt(0) lgkmcnt(0)
	s_waitcnt vmcnt(0)
	s_mov_b64 s[78:79], exec
	v_readlane_b32 s30, v242, 46
	v_readlane_b32 s31, v242, 47
	s_and_b64 s[30:31], s[78:79], s[30:31]
	s_mov_b64 exec, s[30:31]
	s_cbranch_execz .LBB0_1581
	s_mov_b64 s[80:81], exec
	v_mbcnt_lo_u32_b32 v0, s80, 0
	v_mbcnt_hi_u32_b32 v0, s81, v0
	v_cmp_eq_u32_e32 vcc, 0, v0
	s_and_b64 s[30:31], exec, vcc
	s_mov_b64 exec, s[30:31]
	s_cbranch_execz .LBB0_1581
	s_bcnt1_i32_b64 s30, s[80:81]
	s_lshl_b32 s30, s30, 3
	v_mov_b32_e32 v0, s30
	global_atomic_add v185, v0, s[26:27]
